# K-loop LDS-DMA loads use the scalar-base form (SGPR base + 32-bit lane offset, +kstep via offset:128 with m0-128): 16 64-bit VALU address adds per iteration per wave removed in all 8 GEMM mainloops; o
# speedup vs baseline: 1.0095x; 1.0042x over previous
; #define PG8_STAGE(bufoff, gbase, voff) do { _Pragma("unroll") for (int _i = 0; _i < 2; ++_i) \
;         __builtin_amdgcn_global_load_lds((const unsigned*)((const char*)(gbase) + (voff)[_i]), (PG8_LAS unsigned*)(lds + (bufoff) + ldsw + _i * 8192), 16, 0, 0); } while (0)
; #define PG8_LDA(dst, b, h) do { _Pragma("unroll") for (int m = 0; m < 4; ++m) _Pragma("unroll") for (int k = 0; k < 2; ++k) dst[m][k] = *(const PG8_LAS bf16x8*)(lds + PG8_SA(b, h) + aoff + m * 2048 + k * 1024); } while (0)
; #define PG8_LDB(dst, b, h) do { _Pragma("unroll") for (int n = 0; n < 2; ++n) _Pragma("unroll") for (int k = 0; k < 2; ++k) dst[n][k] = *(const PG8_LAS bf16x8*)(lds + PG8_SB(b, h) + boff + n * 2048 + k * 1024); } while (0)
; #define PG8_WAIT_V(n) asm volatile("s_waitcnt vmcnt(" #n ")" ::: "memory")
; #define PG8_WAIT_L(n) asm volatile("s_waitcnt lgkmcnt(" #n ")" ::: "memory")
; #define PG8_BAR __builtin_amdgcn_s_barrier()
; #define PG8_SCHED __builtin_amdgcn_sched_barrier(0)
; template <class Epi, class Sched, bool ALIGN_EPI = false, bool SP2 = false>
; __device__ __forceinline__ void gemm_phase(PG8_LAS unsigned char* lds, const Gemm g, const Sched& S, const Epi& E, int tid_in) {
;     ...
;         const char* nA = has_next ? (const char*)g.A + (size_t)nxt.pm * tstep : cA; const char* nB = has_next ? (const char*)g.Bt + (size_t)nxt.pn * tstepB : cB;
;         for (int t = 0; t < nt; t += 2) {
;             const bool last = (t == nt - 2);
;             const char* a1 = cA + (size_t)(t + 1) * kstep;
;             const char* a2 = last ? nA : cA + (size_t)(t + 2) * kstep; const char* b2 = last ? nB : cB + (size_t)(t + 2) * kstep;
;             const char* a3 = a2 + kstep; const char* b3 = b2 + kstep;
;             if (last && has_next) S.a_ready(nxt);
;             if constexpr (SP2) {
;             PG8_LDB(B0, 0, 0); PG8_LDB(B1, 0, 1); PG8_SCHED; PG8_LDA(At, 0, 0); PG8_STAGE(PG8_SA(1, 1), a1 + hstep, voffA);
;             PG8_WAIT_V(8); PG8_WAIT_L(0); PG8_BAR; PG8_MMA(0, 0, At, B0); PG8_MMA(0, 1, At, B1); PG8_BAR; PG8_SCHED;
;             PG8_LDA(At, 0, 1); PG8_STAGE(PG8_SB(0, 0), b2, voffB); PG8_STAGE(PG8_SB(0, 1), b2 + hstepB, voffB); PG8_STAGE(PG8_SA(0, 0), a2, voffA);
;             PG8_WAIT_V(8); PG8_WAIT_L(0); PG8_BAR; PG8_MMA(1, 0, At, B0); PG8_MMA(1, 1, At, B1); PG8_BAR; PG8_SCHED;
.Lkb_skip_0:
.LBB0_80:
	ds_read_b128 v[156:159], v150
	ds_read_b128 v[160:163], v150 offset:1024
	ds_read_b128 v[164:167], v150 offset:2048
	ds_read_b128 v[168:171], v150 offset:3072
	ds_read_b128 v[172:175], v151
	ds_read_b128 v[176:179], v151 offset:1024
	ds_read_b128 v[180:183], v151 offset:2048
	ds_read_b128 v[184:187], v151 offset:3072
	s_add_u32 s26, s48, 0xfff80080
	s_addc_u32 s27, s49, -1
	s_cmp_eq_u32 s76, 28
	s_cselect_b32 s53, s41, s27
	s_cselect_b32 s52, s70, s26
	s_cselect_b32 s51, s39, s75
	s_cselect_b32 s50, s71, s74
	s_add_i32 m0, s47, 0xc000
	ds_read_b128 v[188:191], v152
	ds_read_b128 v[192:195], v152 offset:1024
	ds_read_b128 v[196:199], v152 offset:2048
	ds_read_b128 v[200:203], v152 offset:3072
	ds_read_b128 v[212:215], v152 offset:4096
	ds_read_b128 v[216:219], v152 offset:5120
	ds_read_b128 v[220:223], v152 offset:6144
	ds_read_b128 v[224:227], v152 offset:7168
	global_load_lds_dwordx4 v138, s[48:49]
	s_add_i32 m0, s47, 0xe000
	s_nop 0
	global_load_lds_dwordx4 v140, s[48:49]
	s_waitcnt vmcnt(8)
	s_waitcnt lgkmcnt(0)
	s_barrier
	s_setprio 1
	s_waitcnt lgkmcnt(0)
	v_mfma_f32_16x16x32_bf16 v[124:127], v[156:159], v[188:191], v[124:127]
	v_mfma_f32_16x16x32_bf16 v[120:123], v[164:167], v[188:191], v[120:123]
	v_mfma_f32_16x16x32_bf16 v[108:111], v[156:159], v[196:199], v[108:111]
	v_mfma_f32_16x16x32_bf16 v[104:107], v[164:167], v[196:199], v[104:107]
	v_mfma_f32_16x16x32_bf16 v[92:95], v[156:159], v[212:215], v[92:95]
	v_mfma_f32_16x16x32_bf16 v[88:91], v[164:167], v[212:215], v[88:91]
	v_mfma_f32_16x16x32_bf16 v[76:79], v[156:159], v[220:223], v[76:79]
	v_mfma_f32_16x16x32_bf16 v[72:75], v[164:167], v[220:223], v[72:75]
	v_mfma_f32_16x16x32_bf16 v[124:127], v[160:163], v[192:195], v[124:127]
	v_mfma_f32_16x16x32_bf16 v[120:123], v[168:171], v[192:195], v[120:123]
	v_mfma_f32_16x16x32_bf16 v[108:111], v[160:163], v[200:203], v[108:111]
	v_mfma_f32_16x16x32_bf16 v[104:107], v[168:171], v[200:203], v[104:107]
	v_mfma_f32_16x16x32_bf16 v[92:95], v[160:163], v[216:219], v[92:95]
	v_mfma_f32_16x16x32_bf16 v[88:91], v[168:171], v[216:219], v[88:91]
	v_mfma_f32_16x16x32_bf16 v[76:79], v[160:163], v[224:227], v[76:79]
	v_mfma_f32_16x16x32_bf16 v[72:75], v[168:171], v[224:227], v[72:75]
	s_setprio 0
	s_setprio 1
	v_mfma_f32_16x16x32_bf16 v[116:119], v[172:175], v[188:191], v[116:119]
	v_mfma_f32_16x16x32_bf16 v[112:115], v[180:183], v[188:191], v[112:115]
	v_mfma_f32_16x16x32_bf16 v[100:103], v[172:175], v[196:199], v[100:103]
	v_mfma_f32_16x16x32_bf16 v[96:99], v[180:183], v[196:199], v[96:99]
	v_mfma_f32_16x16x32_bf16 v[84:87], v[172:175], v[212:215], v[84:87]
	v_mfma_f32_16x16x32_bf16 v[80:83], v[180:183], v[212:215], v[80:83]
	v_mfma_f32_16x16x32_bf16 v[68:71], v[172:175], v[220:223], v[68:71]
	v_mfma_f32_16x16x32_bf16 v[64:67], v[180:183], v[220:223], v[64:67]
	v_mfma_f32_16x16x32_bf16 v[116:119], v[176:179], v[192:195], v[116:119]
	v_mfma_f32_16x16x32_bf16 v[112:115], v[184:187], v[192:195], v[112:115]
	v_mfma_f32_16x16x32_bf16 v[100:103], v[176:179], v[200:203], v[100:103]
	v_mfma_f32_16x16x32_bf16 v[96:99], v[184:187], v[200:203], v[96:99]
	v_mfma_f32_16x16x32_bf16 v[84:87], v[176:179], v[216:219], v[84:87]
	v_mfma_f32_16x16x32_bf16 v[80:83], v[184:187], v[216:219], v[80:83]
	v_mfma_f32_16x16x32_bf16 v[68:71], v[176:179], v[224:227], v[68:71]
	v_mfma_f32_16x16x32_bf16 v[64:67], v[184:187], v[224:227], v[64:67]
	s_setprio 0
	s_barrier
	s_add_i32 s26, s67, s54
	s_mov_b32 m0, s26
	ds_read_b128 v[188:191], v152 offset:16384
	ds_read_b128 v[192:195], v152 offset:17408
	ds_read_b128 v[196:199], v152 offset:18432
	ds_read_b128 v[200:203], v152 offset:19456
	ds_read_b128 v[212:215], v152 offset:20480
	ds_read_b128 v[216:219], v152 offset:21504
	ds_read_b128 v[220:223], v152 offset:22528
	ds_read_b128 v[224:227], v152 offset:23552
	global_load_lds_dwordx4 v132, s[50:51]
	s_add_i32 m0, s26, 0x2000
	s_add_u32 s26, s50, 0x20000
	s_addc_u32 s27, s51, 0
	s_add_i32 s33, s68, s54
	global_load_lds_dwordx4 v128, s[50:51]
	s_mov_b32 m0, s33
	s_nop 0
	global_load_lds_dwordx4 v132, s[26:27]
	s_add_i32 m0, s33, 0x2000
	s_nop 0
	global_load_lds_dwordx4 v128, s[26:27]
	s_mov_b32 m0, s47
	s_nop 0
	global_load_lds_dwordx4 v134, s[52:53]
	s_mov_b32 m0, s56
	s_nop 0
	global_load_lds_dwordx4 v130, s[52:53]
	s_waitcnt vmcnt(8)
	s_waitcnt lgkmcnt(0)
	s_barrier
	s_setprio 1
	s_waitcnt lgkmcnt(0)
	v_mfma_f32_16x16x32_bf16 v[60:63], v[156:159], v[188:191], v[60:63]
	v_mfma_f32_16x16x32_bf16 v[56:59], v[164:167], v[188:191], v[56:59]
	v_mfma_f32_16x16x32_bf16 v[44:47], v[156:159], v[196:199], v[44:47]
	v_mfma_f32_16x16x32_bf16 v[40:43], v[164:167], v[196:199], v[40:43]
	v_mfma_f32_16x16x32_bf16 v[28:31], v[156:159], v[212:215], v[28:31]
	v_mfma_f32_16x16x32_bf16 v[24:27], v[164:167], v[212:215], v[24:27]
	v_mfma_f32_16x16x32_bf16 v[12:15], v[156:159], v[220:223], v[12:15]
	v_mfma_f32_16x16x32_bf16 v[8:11], v[164:167], v[220:223], v[8:11]
	v_mfma_f32_16x16x32_bf16 v[60:63], v[160:163], v[192:195], v[60:63]
	v_mfma_f32_16x16x32_bf16 v[56:59], v[168:171], v[192:195], v[56:59]
	v_mfma_f32_16x16x32_bf16 v[44:47], v[160:163], v[200:203], v[44:47]
	v_mfma_f32_16x16x32_bf16 v[40:43], v[168:171], v[200:203], v[40:43]
	v_mfma_f32_16x16x32_bf16 v[28:31], v[160:163], v[216:219], v[28:31]
	v_mfma_f32_16x16x32_bf16 v[24:27], v[168:171], v[216:219], v[24:27]
	v_mfma_f32_16x16x32_bf16 v[12:15], v[160:163], v[224:227], v[12:15]
	v_mfma_f32_16x16x32_bf16 v[8:11], v[168:171], v[224:227], v[8:11]
	s_setprio 0
	s_setprio 1
	v_mfma_f32_16x16x32_bf16 v[52:55], v[172:175], v[188:191], v[52:55]
	v_mfma_f32_16x16x32_bf16 v[48:51], v[180:183], v[188:191], v[48:51]
	v_mfma_f32_16x16x32_bf16 v[36:39], v[172:175], v[196:199], v[36:39]
	v_mfma_f32_16x16x32_bf16 v[32:35], v[180:183], v[196:199], v[32:35]
	v_mfma_f32_16x16x32_bf16 v[20:23], v[172:175], v[212:215], v[20:23]
	v_mfma_f32_16x16x32_bf16 v[16:19], v[180:183], v[212:215], v[16:19]
	v_mfma_f32_16x16x32_bf16 v[4:7], v[172:175], v[220:223], v[4:7]
	v_mfma_f32_16x16x32_bf16 v[0:3], v[180:183], v[220:223], v[0:3]
	v_mfma_f32_16x16x32_bf16 v[52:55], v[176:179], v[192:195], v[52:55]
	v_mfma_f32_16x16x32_bf16 v[48:51], v[184:187], v[192:195], v[48:51]
	v_mfma_f32_16x16x32_bf16 v[36:39], v[176:179], v[200:203], v[36:39]
	v_mfma_f32_16x16x32_bf16 v[32:35], v[184:187], v[200:203], v[32:35]
	v_mfma_f32_16x16x32_bf16 v[20:23], v[176:179], v[216:219], v[20:23]
	v_mfma_f32_16x16x32_bf16 v[16:19], v[184:187], v[216:219], v[16:19]
	v_mfma_f32_16x16x32_bf16 v[4:7], v[176:179], v[224:227], v[4:7]
	v_mfma_f32_16x16x32_bf16 v[0:3], v[184:187], v[224:227], v[0:3]
	s_setprio 0
	s_barrier
; #define PG8_STAGE(bufoff, gbase, voff) do { _Pragma("unroll") for (int _i = 0; _i < 2; ++_i) \
;         __builtin_amdgcn_global_load_lds((const unsigned*)((const char*)(gbase) + (voff)[_i]), (PG8_LAS unsigned*)(lds + (bufoff) + ldsw + _i * 8192), 16, 0, 0); } while (0)
; #define PG8_BAR __builtin_amdgcn_s_barrier()
; template <class Epi, class Sched, bool ALIGN_EPI = false, bool SP2 = false>
; __device__ __forceinline__ void gemm_phase(PG8_LAS unsigned char* lds, const Gemm g, const Sched& S, const Epi& E, int tid_in) {
;     ...
;             PG8_LDB(B0, 1, 0); PG8_LDB(B1, 1, 1); PG8_SCHED; PG8_LDA(At, 1, 0); PG8_STAGE(PG8_SA(0, 1), a2 + hstep, voffA);
;             PG8_WAIT_V(8); PG8_WAIT_L(0); PG8_BAR; PG8_MMA(0, 0, At, B0); PG8_MMA(0, 1, At, B1); PG8_BAR; PG8_SCHED;
;             PG8_LDA(At, 1, 1); PG8_STAGE(PG8_SB(1, 0), b3, voffB); PG8_STAGE(PG8_SB(1, 1), b3 + hstepB, voffB); PG8_STAGE(PG8_SA(1, 0), a3, voffA);
;             PG8_WAIT_V(8); PG8_WAIT_L(0); PG8_BAR; PG8_MMA(1, 0, At, B0); PG8_MMA(1, 1, At, B1); PG8_BAR; PG8_SCHED;
;             } else {
;             PG8_LDB(B0, 0, 0); PG8_SCHED; PG8_LDA(At, 0, 0); PG8_STAGE(PG8_SA(1, 1), a1 + hstep, voffA);
;             PG8_WAIT_L(8); PG8_BAR; PG8_WAIT_L(0); PG8_MMA(0, 0, At, B0); PG8_BAR; PG8_SCHED;
;             PG8_LDB(B1, 0, 1); PG8_STAGE(PG8_SB(0, 0), b2, voffB);
;             PG8_BAR; PG8_WAIT_L(0); PG8_MMA(0, 1, At, B1); PG8_BAR;
;             PG8_LDA(At, 0, 1); PG8_STAGE(PG8_SA(0, 0), a2, voffA);
;             PG8_BAR; PG8_WAIT_L(0); PG8_MMA(1, 0, At, B0); PG8_BAR; PG8_SCHED;
;             PG8_STAGE(PG8_SB(0, 1), b2 + hstepB, voffB);
;             PG8_WAIT_V(6); PG8_BAR; PG8_MMA(1, 1, At, B1); PG8_BAR;
;             PG8_LDB(B0, 1, 0); PG8_SCHED; PG8_LDA(At, 1, 0); PG8_STAGE(PG8_SA(0, 1), a2 + hstep, voffA);
;             PG8_WAIT_L(8); PG8_BAR; PG8_WAIT_L(0); PG8_MMA(0, 0, At, B0); PG8_BAR; PG8_SCHED;
;             PG8_LDB(B1, 1, 1); PG8_STAGE(PG8_SB(1, 0), b3, voffB);
;             PG8_BAR; PG8_WAIT_L(0); PG8_MMA(0, 1, At, B1); PG8_BAR;
;             PG8_LDA(At, 1, 1); PG8_STAGE(PG8_SA(1, 0), a3, voffA);
;             PG8_BAR; PG8_WAIT_L(0); PG8_MMA(1, 0, At, B0); PG8_BAR; PG8_SCHED;
;             PG8_STAGE(PG8_SB(1, 1), b3 + hstepB, voffB);
;             PG8_WAIT_V(6); PG8_BAR; PG8_MMA(1, 1, At, B1); PG8_BAR;
;             }
;         }
;         if constexpr (ALIGN_EPI) { if (wr == 0) PG8_BAR; }
	s_add_i32 s33, 0, 0x18000
	v_add_u32_e32 v155, s33, v146
	s_add_i32 s77, 0, 0x1c000
	ds_read_b128 v[156:159], v155
	ds_read_b128 v[160:163], v155 offset:1024
	ds_read_b128 v[164:167], v155 offset:2048
	ds_read_b128 v[168:171], v155 offset:3072
	v_add_u32_e32 v155, s77, v146
	ds_read_b128 v[172:175], v155
	ds_read_b128 v[176:179], v155 offset:1024
	ds_read_b128 v[180:183], v155 offset:2048
	ds_read_b128 v[184:187], v155 offset:3072
	s_add_u32 s26, s52, 0x80000
	s_addc_u32 s27, s53, 0
	s_mov_b32 m0, s57
	ds_read_b128 v[188:191], v152 offset:32768
	ds_read_b128 v[192:195], v152 offset:33792
	ds_read_b128 v[196:199], v152 offset:34816
	ds_read_b128 v[200:203], v152 offset:35840
	ds_read_b128 v[212:215], v152 offset:36864
	ds_read_b128 v[216:219], v152 offset:37888
	ds_read_b128 v[220:223], v152 offset:38912
	ds_read_b128 v[224:227], v152 offset:39936
	global_load_lds_dwordx4 v134, s[26:27]
	s_mov_b32 m0, s58
	s_nop 0
	global_load_lds_dwordx4 v130, s[26:27]
	s_waitcnt vmcnt(8)
	s_waitcnt lgkmcnt(0)
	s_barrier
	s_setprio 1
	s_waitcnt lgkmcnt(0)
	v_mfma_f32_16x16x32_bf16 v[124:127], v[156:159], v[188:191], v[124:127]
	v_mfma_f32_16x16x32_bf16 v[120:123], v[164:167], v[188:191], v[120:123]
	v_mfma_f32_16x16x32_bf16 v[108:111], v[156:159], v[196:199], v[108:111]
	v_mfma_f32_16x16x32_bf16 v[104:107], v[164:167], v[196:199], v[104:107]
	v_mfma_f32_16x16x32_bf16 v[92:95], v[156:159], v[212:215], v[92:95]
	v_mfma_f32_16x16x32_bf16 v[88:91], v[164:167], v[212:215], v[88:91]
	v_mfma_f32_16x16x32_bf16 v[76:79], v[156:159], v[220:223], v[76:79]
	v_mfma_f32_16x16x32_bf16 v[72:75], v[164:167], v[220:223], v[72:75]
	v_mfma_f32_16x16x32_bf16 v[124:127], v[160:163], v[192:195], v[124:127]
	v_mfma_f32_16x16x32_bf16 v[120:123], v[168:171], v[192:195], v[120:123]
	v_mfma_f32_16x16x32_bf16 v[108:111], v[160:163], v[200:203], v[108:111]
	v_mfma_f32_16x16x32_bf16 v[104:107], v[168:171], v[200:203], v[104:107]
	v_mfma_f32_16x16x32_bf16 v[92:95], v[160:163], v[216:219], v[92:95]
	v_mfma_f32_16x16x32_bf16 v[88:91], v[168:171], v[216:219], v[88:91]
	v_mfma_f32_16x16x32_bf16 v[76:79], v[160:163], v[224:227], v[76:79]
	v_mfma_f32_16x16x32_bf16 v[72:75], v[168:171], v[224:227], v[72:75]
	s_setprio 0
	s_setprio 1
	v_mfma_f32_16x16x32_bf16 v[116:119], v[172:175], v[188:191], v[116:119]
	v_mfma_f32_16x16x32_bf16 v[112:115], v[180:183], v[188:191], v[112:115]
	v_mfma_f32_16x16x32_bf16 v[100:103], v[172:175], v[196:199], v[100:103]
	v_mfma_f32_16x16x32_bf16 v[96:99], v[180:183], v[196:199], v[96:99]
	v_mfma_f32_16x16x32_bf16 v[84:87], v[172:175], v[212:215], v[84:87]
	v_mfma_f32_16x16x32_bf16 v[80:83], v[180:183], v[212:215], v[80:83]
	v_mfma_f32_16x16x32_bf16 v[68:71], v[172:175], v[220:223], v[68:71]
	v_mfma_f32_16x16x32_bf16 v[64:67], v[180:183], v[220:223], v[64:67]
	v_mfma_f32_16x16x32_bf16 v[116:119], v[176:179], v[192:195], v[116:119]
	v_mfma_f32_16x16x32_bf16 v[112:115], v[184:187], v[192:195], v[112:115]
	v_mfma_f32_16x16x32_bf16 v[100:103], v[176:179], v[200:203], v[100:103]
	v_mfma_f32_16x16x32_bf16 v[96:99], v[184:187], v[200:203], v[96:99]
	v_mfma_f32_16x16x32_bf16 v[84:87], v[176:179], v[216:219], v[84:87]
	v_mfma_f32_16x16x32_bf16 v[80:83], v[184:187], v[216:219], v[80:83]
	v_mfma_f32_16x16x32_bf16 v[68:71], v[176:179], v[224:227], v[68:71]
	v_mfma_f32_16x16x32_bf16 v[64:67], v[184:187], v[224:227], v[64:67]
	s_setprio 0
	s_barrier
	s_add_i32 s26, s33, s54
	s_add_i32 m0, s26, 0xffffff80
	ds_read_b128 v[188:191], v152 offset:49152
	ds_read_b128 v[192:195], v152 offset:50176
	ds_read_b128 v[196:199], v152 offset:51200
	ds_read_b128 v[200:203], v152 offset:52224
	ds_read_b128 v[212:215], v152 offset:53248
	ds_read_b128 v[216:219], v152 offset:54272
	ds_read_b128 v[220:223], v152 offset:55296
	ds_read_b128 v[224:227], v152 offset:56320
	global_load_lds_dwordx4 v132, s[50:51] offset:128
	s_add_i32 m0, s26, 0x1f80
	s_add_u32 s26, s50, 0x20080
	s_addc_u32 s27, s51, 0
	s_add_i32 s33, s77, s54
	global_load_lds_dwordx4 v128, s[50:51] offset:128
	s_mov_b32 m0, s33
	s_nop 0
	global_load_lds_dwordx4 v132, s[26:27]
	s_add_i32 m0, s33, 0x2000
	s_nop 0
	global_load_lds_dwordx4 v128, s[26:27]
	s_add_i32 m0, s61, 0xffffff80
	s_nop 0
	global_load_lds_dwordx4 v134, s[52:53] offset:128
	s_add_i32 m0, s62, 0xffffff80
	s_nop 0
	global_load_lds_dwordx4 v130, s[52:53] offset:128
	s_waitcnt vmcnt(8)
	s_waitcnt lgkmcnt(0)
	s_barrier
	s_setprio 1
	s_waitcnt lgkmcnt(0)
	v_mfma_f32_16x16x32_bf16 v[60:63], v[156:159], v[188:191], v[60:63]
	v_mfma_f32_16x16x32_bf16 v[56:59], v[164:167], v[188:191], v[56:59]
	v_mfma_f32_16x16x32_bf16 v[44:47], v[156:159], v[196:199], v[44:47]
	v_mfma_f32_16x16x32_bf16 v[40:43], v[164:167], v[196:199], v[40:43]
	v_mfma_f32_16x16x32_bf16 v[28:31], v[156:159], v[212:215], v[28:31]
	v_mfma_f32_16x16x32_bf16 v[24:27], v[164:167], v[212:215], v[24:27]
	v_mfma_f32_16x16x32_bf16 v[12:15], v[156:159], v[220:223], v[12:15]
	v_mfma_f32_16x16x32_bf16 v[8:11], v[164:167], v[220:223], v[8:11]
	v_mfma_f32_16x16x32_bf16 v[60:63], v[160:163], v[192:195], v[60:63]
	v_mfma_f32_16x16x32_bf16 v[56:59], v[168:171], v[192:195], v[56:59]
	v_mfma_f32_16x16x32_bf16 v[44:47], v[160:163], v[200:203], v[44:47]
	v_mfma_f32_16x16x32_bf16 v[40:43], v[168:171], v[200:203], v[40:43]
	v_mfma_f32_16x16x32_bf16 v[28:31], v[160:163], v[216:219], v[28:31]
	v_mfma_f32_16x16x32_bf16 v[24:27], v[168:171], v[216:219], v[24:27]
	v_mfma_f32_16x16x32_bf16 v[12:15], v[160:163], v[224:227], v[12:15]
	v_mfma_f32_16x16x32_bf16 v[8:11], v[168:171], v[224:227], v[8:11]
	s_setprio 0
	s_setprio 1
	v_mfma_f32_16x16x32_bf16 v[52:55], v[172:175], v[188:191], v[52:55]
	v_mfma_f32_16x16x32_bf16 v[48:51], v[180:183], v[188:191], v[48:51]
	v_mfma_f32_16x16x32_bf16 v[36:39], v[172:175], v[196:199], v[36:39]
	v_mfma_f32_16x16x32_bf16 v[32:35], v[180:183], v[196:199], v[32:35]
	v_mfma_f32_16x16x32_bf16 v[20:23], v[172:175], v[212:215], v[20:23]
	v_mfma_f32_16x16x32_bf16 v[16:19], v[180:183], v[212:215], v[16:19]
	v_mfma_f32_16x16x32_bf16 v[4:7], v[172:175], v[220:223], v[4:7]
	v_mfma_f32_16x16x32_bf16 v[0:3], v[180:183], v[220:223], v[0:3]
	v_mfma_f32_16x16x32_bf16 v[52:55], v[176:179], v[192:195], v[52:55]
	v_mfma_f32_16x16x32_bf16 v[48:51], v[184:187], v[192:195], v[48:51]
	v_mfma_f32_16x16x32_bf16 v[36:39], v[176:179], v[200:203], v[36:39]
	v_mfma_f32_16x16x32_bf16 v[32:35], v[184:187], v[200:203], v[32:35]
	v_mfma_f32_16x16x32_bf16 v[20:23], v[176:179], v[216:219], v[20:23]
	v_mfma_f32_16x16x32_bf16 v[16:19], v[184:187], v[216:219], v[16:19]
	v_mfma_f32_16x16x32_bf16 v[4:7], v[176:179], v[224:227], v[4:7]
	v_mfma_f32_16x16x32_bf16 v[0:3], v[184:187], v[224:227], v[0:3]
	s_setprio 0
	s_barrier
	s_add_i32 s76, s76, 2
	s_add_u32 s48, s48, 0x100
	s_addc_u32 s49, s49, 0
	s_add_u32 s74, s74, 0x100
	s_addc_u32 s75, s75, 0
	s_cmp_gt_u32 s76, 29
	s_cbranch_scc0 .LBB0_80
	s_and_b64 vcc, exec, s[14:15]
	s_cbranch_vccz .LBB0_83
	s_barrier

; #define PG8_STAGE(bufoff, gbase, voff) do { _Pragma("unroll") for (int _i = 0; _i < 2; ++_i) \
;         __builtin_amdgcn_global_load_lds((const unsigned*)((const char*)(gbase) + (voff)[_i]), (PG8_LAS unsigned*)(lds + (bufoff) + ldsw + _i * 8192), 16, 0, 0); } while (0)
; #define PG8_LDA(dst, b, h) do { _Pragma("unroll") for (int m = 0; m < 4; ++m) _Pragma("unroll") for (int k = 0; k < 2; ++k) dst[m][k] = *(const PG8_LAS bf16x8*)(lds + PG8_SA(b, h) + aoff + m * 2048 + k * 1024); } while (0)
; #define PG8_LDB(dst, b, h) do { _Pragma("unroll") for (int n = 0; n < 2; ++n) _Pragma("unroll") for (int k = 0; k < 2; ++k) dst[n][k] = *(const PG8_LAS bf16x8*)(lds + PG8_SB(b, h) + boff + n * 2048 + k * 1024); } while (0)
; #define PG8_WAIT_V(n) asm volatile("s_waitcnt vmcnt(" #n ")" ::: "memory")
; #define PG8_WAIT_L(n) asm volatile("s_waitcnt lgkmcnt(" #n ")" ::: "memory")
; #define PG8_BAR __builtin_amdgcn_s_barrier()
; #define PG8_SCHED __builtin_amdgcn_sched_barrier(0)
; template <class Epi, class Sched, bool ALIGN_EPI = false, bool SP2 = false>
; __device__ __forceinline__ void gemm_phase(PG8_LAS unsigned char* lds, const Gemm g, const Sched& S, const Epi& E, int tid_in) {
;     ...
;         const char* nA = has_next ? (const char*)g.A + (size_t)nxt.pm * tstep : cA; const char* nB = has_next ? (const char*)g.Bt + (size_t)nxt.pn * tstepB : cB;
;         for (int t = 0; t < nt; t += 2) {
;             const bool last = (t == nt - 2);
;             const char* a1 = cA + (size_t)(t + 1) * kstep;
;             const char* a2 = last ? nA : cA + (size_t)(t + 2) * kstep; const char* b2 = last ? nB : cB + (size_t)(t + 2) * kstep;
;             const char* a3 = a2 + kstep; const char* b3 = b2 + kstep;
;             if (last && has_next) S.a_ready(nxt);
;             if constexpr (SP2) {
;             PG8_LDB(B0, 0, 0); PG8_LDB(B1, 0, 1); PG8_SCHED; PG8_LDA(At, 0, 0); PG8_STAGE(PG8_SA(1, 1), a1 + hstep, voffA);
;             PG8_WAIT_V(8); PG8_WAIT_L(0); PG8_BAR; PG8_MMA(0, 0, At, B0); PG8_MMA(0, 1, At, B1); PG8_BAR; PG8_SCHED;
;             PG8_LDA(At, 0, 1); PG8_STAGE(PG8_SB(0, 0), b2, voffB); PG8_STAGE(PG8_SB(0, 1), b2 + hstepB, voffB); PG8_STAGE(PG8_SA(0, 0), a2, voffA);
;             PG8_WAIT_V(8); PG8_WAIT_L(0); PG8_BAR; PG8_MMA(1, 0, At, B0); PG8_MMA(1, 1, At, B1); PG8_BAR; PG8_SCHED;
.Lkb_skip_1:
.LBB0_292:
	ds_read_b128 v[146:149], v153
	ds_read_b128 v[158:161], v153 offset:1024
	ds_read_b128 v[162:165], v153 offset:2048
	ds_read_b128 v[166:169], v153 offset:3072
	ds_read_b128 v[170:173], v154
	ds_read_b128 v[174:177], v154 offset:1024
	ds_read_b128 v[178:181], v154 offset:2048
	ds_read_b128 v[182:185], v154 offset:3072
	s_add_u32 s26, s58, 0xfff80080
	s_addc_u32 s27, s59, -1
	s_cmp_eq_u32 s79, 28
	s_cselect_b32 s63, s49, s27
	s_cselect_b32 s62, s55, s26
	s_cselect_b32 s61, s47, s77
	s_cselect_b32 s60, s75, s76
	s_add_i32 m0, s57, 0xc000
	ds_read_b128 v[186:189], v155
	ds_read_b128 v[190:193], v155 offset:1024
	ds_read_b128 v[194:197], v155 offset:2048
	ds_read_b128 v[198:201], v155 offset:3072
	ds_read_b128 v[202:205], v155 offset:4096
	ds_read_b128 v[206:209], v155 offset:5120
	ds_read_b128 v[212:215], v155 offset:6144
	ds_read_b128 v[216:219], v155 offset:7168
	global_load_lds_dwordx4 v138, s[58:59]
	s_add_i32 m0, s57, 0xe000
	s_nop 0
	global_load_lds_dwordx4 v140, s[58:59]
	s_waitcnt vmcnt(8)
	s_waitcnt lgkmcnt(0)
	s_barrier
	s_setprio 1
	s_waitcnt lgkmcnt(0)
	v_mfma_f32_16x16x32_bf16 v[124:127], v[146:149], v[186:189], v[124:127]
	v_mfma_f32_16x16x32_bf16 v[120:123], v[162:165], v[186:189], v[120:123]
	v_mfma_f32_16x16x32_bf16 v[108:111], v[146:149], v[194:197], v[108:111]
	v_mfma_f32_16x16x32_bf16 v[104:107], v[162:165], v[194:197], v[104:107]
	v_mfma_f32_16x16x32_bf16 v[92:95], v[146:149], v[202:205], v[92:95]
	v_mfma_f32_16x16x32_bf16 v[88:91], v[162:165], v[202:205], v[88:91]
	v_mfma_f32_16x16x32_bf16 v[76:79], v[146:149], v[212:215], v[76:79]
	v_mfma_f32_16x16x32_bf16 v[72:75], v[162:165], v[212:215], v[72:75]
	v_mfma_f32_16x16x32_bf16 v[124:127], v[158:161], v[190:193], v[124:127]
	v_mfma_f32_16x16x32_bf16 v[120:123], v[166:169], v[190:193], v[120:123]
	v_mfma_f32_16x16x32_bf16 v[108:111], v[158:161], v[198:201], v[108:111]
	v_mfma_f32_16x16x32_bf16 v[104:107], v[166:169], v[198:201], v[104:107]
	v_mfma_f32_16x16x32_bf16 v[92:95], v[158:161], v[206:209], v[92:95]
	v_mfma_f32_16x16x32_bf16 v[88:91], v[166:169], v[206:209], v[88:91]
	v_mfma_f32_16x16x32_bf16 v[76:79], v[158:161], v[216:219], v[76:79]
	v_mfma_f32_16x16x32_bf16 v[72:75], v[166:169], v[216:219], v[72:75]
	s_setprio 0
	s_setprio 1
	v_mfma_f32_16x16x32_bf16 v[116:119], v[170:173], v[186:189], v[116:119]
	v_mfma_f32_16x16x32_bf16 v[112:115], v[178:181], v[186:189], v[112:115]
	v_mfma_f32_16x16x32_bf16 v[100:103], v[170:173], v[194:197], v[100:103]
	v_mfma_f32_16x16x32_bf16 v[96:99], v[178:181], v[194:197], v[96:99]
	v_mfma_f32_16x16x32_bf16 v[84:87], v[170:173], v[202:205], v[84:87]
	v_mfma_f32_16x16x32_bf16 v[80:83], v[178:181], v[202:205], v[80:83]
	v_mfma_f32_16x16x32_bf16 v[68:71], v[170:173], v[212:215], v[68:71]
	v_mfma_f32_16x16x32_bf16 v[64:67], v[178:181], v[212:215], v[64:67]
	v_mfma_f32_16x16x32_bf16 v[116:119], v[174:177], v[190:193], v[116:119]
	v_mfma_f32_16x16x32_bf16 v[112:115], v[182:185], v[190:193], v[112:115]
	v_mfma_f32_16x16x32_bf16 v[100:103], v[174:177], v[198:201], v[100:103]
	v_mfma_f32_16x16x32_bf16 v[96:99], v[182:185], v[198:201], v[96:99]
	v_mfma_f32_16x16x32_bf16 v[84:87], v[174:177], v[206:209], v[84:87]
	v_mfma_f32_16x16x32_bf16 v[80:83], v[182:185], v[206:209], v[80:83]
	v_mfma_f32_16x16x32_bf16 v[68:71], v[174:177], v[216:219], v[68:71]
	v_mfma_f32_16x16x32_bf16 v[64:67], v[182:185], v[216:219], v[64:67]
	s_setprio 0
	s_barrier
	s_add_i32 s26, s73, s66
	s_mov_b32 m0, s26
	ds_read_b128 v[186:189], v155 offset:16384
	ds_read_b128 v[190:193], v155 offset:17408
	ds_read_b128 v[194:197], v155 offset:18432
	ds_read_b128 v[198:201], v155 offset:19456
	ds_read_b128 v[202:205], v155 offset:20480
	ds_read_b128 v[206:209], v155 offset:21504
	ds_read_b128 v[212:215], v155 offset:22528
	ds_read_b128 v[216:219], v155 offset:23552
	global_load_lds_dwordx4 v130, s[60:61]
	s_add_i32 m0, s26, 0x2000
	s_add_u32 s26, s60, 0x20000
	s_addc_u32 s27, s61, 0
	s_add_i32 s33, s74, s66
	global_load_lds_dwordx4 v134, s[60:61]
	s_mov_b32 m0, s33
	s_nop 0
	global_load_lds_dwordx4 v130, s[26:27]
	s_add_i32 m0, s33, 0x2000
	s_nop 0
	global_load_lds_dwordx4 v134, s[26:27]
	s_mov_b32 m0, s57
	s_nop 0
	global_load_lds_dwordx4 v128, s[62:63]
	s_mov_b32 m0, s67
	s_nop 0
	global_load_lds_dwordx4 v132, s[62:63]
	s_waitcnt vmcnt(8)
	s_waitcnt lgkmcnt(0)
	s_barrier
	s_setprio 1
	s_waitcnt lgkmcnt(0)
	v_mfma_f32_16x16x32_bf16 v[60:63], v[146:149], v[186:189], v[60:63]
	v_mfma_f32_16x16x32_bf16 v[56:59], v[162:165], v[186:189], v[56:59]
	v_mfma_f32_16x16x32_bf16 v[44:47], v[146:149], v[194:197], v[44:47]
	v_mfma_f32_16x16x32_bf16 v[40:43], v[162:165], v[194:197], v[40:43]
	v_mfma_f32_16x16x32_bf16 v[28:31], v[146:149], v[202:205], v[28:31]
	v_mfma_f32_16x16x32_bf16 v[24:27], v[162:165], v[202:205], v[24:27]
	v_mfma_f32_16x16x32_bf16 v[12:15], v[146:149], v[212:215], v[12:15]
	v_mfma_f32_16x16x32_bf16 v[8:11], v[162:165], v[212:215], v[8:11]
	v_mfma_f32_16x16x32_bf16 v[60:63], v[158:161], v[190:193], v[60:63]
	v_mfma_f32_16x16x32_bf16 v[56:59], v[166:169], v[190:193], v[56:59]
	v_mfma_f32_16x16x32_bf16 v[44:47], v[158:161], v[198:201], v[44:47]
	v_mfma_f32_16x16x32_bf16 v[40:43], v[166:169], v[198:201], v[40:43]
	v_mfma_f32_16x16x32_bf16 v[28:31], v[158:161], v[206:209], v[28:31]
	v_mfma_f32_16x16x32_bf16 v[24:27], v[166:169], v[206:209], v[24:27]
	v_mfma_f32_16x16x32_bf16 v[12:15], v[158:161], v[216:219], v[12:15]
	v_mfma_f32_16x16x32_bf16 v[8:11], v[166:169], v[216:219], v[8:11]
	s_setprio 0
	s_setprio 1
	v_mfma_f32_16x16x32_bf16 v[52:55], v[170:173], v[186:189], v[52:55]
	v_mfma_f32_16x16x32_bf16 v[48:51], v[178:181], v[186:189], v[48:51]
	v_mfma_f32_16x16x32_bf16 v[36:39], v[170:173], v[194:197], v[36:39]
	v_mfma_f32_16x16x32_bf16 v[32:35], v[178:181], v[194:197], v[32:35]
	v_mfma_f32_16x16x32_bf16 v[20:23], v[170:173], v[202:205], v[20:23]
	v_mfma_f32_16x16x32_bf16 v[16:19], v[178:181], v[202:205], v[16:19]
	v_mfma_f32_16x16x32_bf16 v[4:7], v[170:173], v[212:215], v[4:7]
	v_mfma_f32_16x16x32_bf16 v[0:3], v[178:181], v[212:215], v[0:3]
	v_mfma_f32_16x16x32_bf16 v[52:55], v[174:177], v[190:193], v[52:55]
	v_mfma_f32_16x16x32_bf16 v[48:51], v[182:185], v[190:193], v[48:51]
	v_mfma_f32_16x16x32_bf16 v[36:39], v[174:177], v[198:201], v[36:39]
	v_mfma_f32_16x16x32_bf16 v[32:35], v[182:185], v[198:201], v[32:35]
	v_mfma_f32_16x16x32_bf16 v[20:23], v[174:177], v[206:209], v[20:23]
	v_mfma_f32_16x16x32_bf16 v[16:19], v[182:185], v[206:209], v[16:19]
	v_mfma_f32_16x16x32_bf16 v[4:7], v[174:177], v[216:219], v[4:7]
	v_mfma_f32_16x16x32_bf16 v[0:3], v[182:185], v[216:219], v[0:3]
	s_setprio 0
	s_barrier
; #define PG8_STAGE(bufoff, gbase, voff) do { _Pragma("unroll") for (int _i = 0; _i < 2; ++_i) \
;         __builtin_amdgcn_global_load_lds((const unsigned*)((const char*)(gbase) + (voff)[_i]), (PG8_LAS unsigned*)(lds + (bufoff) + ldsw + _i * 8192), 16, 0, 0); } while (0)
; #define PG8_LDA(dst, b, h) do { _Pragma("unroll") for (int m = 0; m < 4; ++m) _Pragma("unroll") for (int k = 0; k < 2; ++k) dst[m][k] = *(const PG8_LAS bf16x8*)(lds + PG8_SA(b, h) + aoff + m * 2048 + k * 1024); } while (0)
; #define PG8_LDB(dst, b, h) do { _Pragma("unroll") for (int n = 0; n < 2; ++n) _Pragma("unroll") for (int k = 0; k < 2; ++k) dst[n][k] = *(const PG8_LAS bf16x8*)(lds + PG8_SB(b, h) + boff + n * 2048 + k * 1024); } while (0)
; #define PG8_MMA(ai, bj, At, Bt) do { __builtin_amdgcn_s_setprio(1); _Pragma("unroll") for (int m = 0; m < 4; ++m) _Pragma("unroll") for (int n = 0; n < 2; ++n) _Pragma("unroll") for (int k = 0; k < 2; ++k) \
;         acc[ai][bj][m][n] = __builtin_amdgcn_mfma_f32_16x16x32_bf16(Bt[n][k], At[m][k], acc[ai][bj][m][n], 0, 0, 0); __builtin_amdgcn_s_setprio(0); } while (0)
; #define PG8_WAIT_V(n) asm volatile("s_waitcnt vmcnt(" #n ")" ::: "memory")
; #define PG8_WAIT_L(n) asm volatile("s_waitcnt lgkmcnt(" #n ")" ::: "memory")
; #define PG8_BAR __builtin_amdgcn_s_barrier()
; #define PG8_SCHED __builtin_amdgcn_sched_barrier(0)
; template <class Epi, class Sched, bool ALIGN_EPI = false, bool SP2 = false>
; __device__ __forceinline__ void gemm_phase(PG8_LAS unsigned char* lds, const Gemm g, const Sched& S, const Epi& E, int tid_in) {
;     ...
;             PG8_LDB(B0, 1, 0); PG8_LDB(B1, 1, 1); PG8_SCHED; PG8_LDA(At, 1, 0); PG8_STAGE(PG8_SA(0, 1), a2 + hstep, voffA);
;             PG8_WAIT_V(8); PG8_WAIT_L(0); PG8_BAR; PG8_MMA(0, 0, At, B0); PG8_MMA(0, 1, At, B1); PG8_BAR; PG8_SCHED;
;             PG8_LDA(At, 1, 1); PG8_STAGE(PG8_SB(1, 0), b3, voffB); PG8_STAGE(PG8_SB(1, 1), b3 + hstepB, voffB); PG8_STAGE(PG8_SA(1, 0), a3, voffA);
	s_add_i32 s33, 0, 0x18000
	s_add_i32 s84, 0, 0x1c000
	v_add_u32_e32 v166, s33, v137
	v_add_u32_e32 v182, s84, v137
	ds_read_b128 v[146:149], v166
	ds_read_b128 v[158:161], v166 offset:1024
	ds_read_b128 v[162:165], v166 offset:2048
	ds_read_b128 v[166:169], v166 offset:3072
	ds_read_b128 v[170:173], v182
	ds_read_b128 v[174:177], v182 offset:1024
	ds_read_b128 v[178:181], v182 offset:2048
	ds_read_b128 v[182:185], v182 offset:3072
	s_add_u32 s26, s62, 0x80000
	s_addc_u32 s27, s63, 0
	s_mov_b32 m0, s68
	ds_read_b128 v[186:189], v155 offset:32768
	ds_read_b128 v[190:193], v155 offset:33792
	ds_read_b128 v[194:197], v155 offset:34816
	ds_read_b128 v[198:201], v155 offset:35840
	ds_read_b128 v[202:205], v155 offset:36864
	ds_read_b128 v[206:209], v155 offset:37888
	ds_read_b128 v[212:215], v155 offset:38912
	ds_read_b128 v[216:219], v155 offset:39936
	global_load_lds_dwordx4 v128, s[26:27]
	s_mov_b32 m0, s69
	s_nop 0
	global_load_lds_dwordx4 v132, s[26:27]
	s_waitcnt vmcnt(8)
	s_waitcnt lgkmcnt(0)
	s_barrier
	s_setprio 1
	s_waitcnt lgkmcnt(0)
	v_mfma_f32_16x16x32_bf16 v[124:127], v[146:149], v[186:189], v[124:127]
	v_mfma_f32_16x16x32_bf16 v[120:123], v[162:165], v[186:189], v[120:123]
	v_mfma_f32_16x16x32_bf16 v[108:111], v[146:149], v[194:197], v[108:111]
	v_mfma_f32_16x16x32_bf16 v[104:107], v[162:165], v[194:197], v[104:107]
	v_mfma_f32_16x16x32_bf16 v[92:95], v[146:149], v[202:205], v[92:95]
	v_mfma_f32_16x16x32_bf16 v[88:91], v[162:165], v[202:205], v[88:91]
	v_mfma_f32_16x16x32_bf16 v[76:79], v[146:149], v[212:215], v[76:79]
	v_mfma_f32_16x16x32_bf16 v[72:75], v[162:165], v[212:215], v[72:75]
	v_mfma_f32_16x16x32_bf16 v[124:127], v[158:161], v[190:193], v[124:127]
	v_mfma_f32_16x16x32_bf16 v[120:123], v[166:169], v[190:193], v[120:123]
	v_mfma_f32_16x16x32_bf16 v[108:111], v[158:161], v[198:201], v[108:111]
	v_mfma_f32_16x16x32_bf16 v[104:107], v[166:169], v[198:201], v[104:107]
	v_mfma_f32_16x16x32_bf16 v[92:95], v[158:161], v[206:209], v[92:95]
	v_mfma_f32_16x16x32_bf16 v[88:91], v[166:169], v[206:209], v[88:91]
	v_mfma_f32_16x16x32_bf16 v[76:79], v[158:161], v[216:219], v[76:79]
	v_mfma_f32_16x16x32_bf16 v[72:75], v[166:169], v[216:219], v[72:75]
	s_setprio 0
	s_setprio 1
	v_mfma_f32_16x16x32_bf16 v[116:119], v[170:173], v[186:189], v[116:119]
	v_mfma_f32_16x16x32_bf16 v[112:115], v[178:181], v[186:189], v[112:115]
	v_mfma_f32_16x16x32_bf16 v[100:103], v[170:173], v[194:197], v[100:103]
	v_mfma_f32_16x16x32_bf16 v[96:99], v[178:181], v[194:197], v[96:99]
	v_mfma_f32_16x16x32_bf16 v[84:87], v[170:173], v[202:205], v[84:87]
	v_mfma_f32_16x16x32_bf16 v[80:83], v[178:181], v[202:205], v[80:83]
	v_mfma_f32_16x16x32_bf16 v[68:71], v[170:173], v[212:215], v[68:71]
	v_mfma_f32_16x16x32_bf16 v[64:67], v[178:181], v[212:215], v[64:67]
	v_mfma_f32_16x16x32_bf16 v[116:119], v[174:177], v[190:193], v[116:119]
	v_mfma_f32_16x16x32_bf16 v[112:115], v[182:185], v[190:193], v[112:115]
	v_mfma_f32_16x16x32_bf16 v[100:103], v[174:177], v[198:201], v[100:103]
	v_mfma_f32_16x16x32_bf16 v[96:99], v[182:185], v[198:201], v[96:99]
	v_mfma_f32_16x16x32_bf16 v[84:87], v[174:177], v[206:209], v[84:87]
	v_mfma_f32_16x16x32_bf16 v[80:83], v[182:185], v[206:209], v[80:83]
	v_mfma_f32_16x16x32_bf16 v[68:71], v[174:177], v[216:219], v[68:71]
	v_mfma_f32_16x16x32_bf16 v[64:67], v[182:185], v[216:219], v[64:67]
	s_setprio 0
	s_barrier
	s_add_i32 s26, s33, s66
	s_add_i32 m0, s26, 0xffffff80
	ds_read_b128 v[186:189], v155 offset:49152
	ds_read_b128 v[190:193], v155 offset:50176
	ds_read_b128 v[194:197], v155 offset:51200
	ds_read_b128 v[198:201], v155 offset:52224
	ds_read_b128 v[202:205], v155 offset:53248
	ds_read_b128 v[206:209], v155 offset:54272
	ds_read_b128 v[212:215], v155 offset:55296
	ds_read_b128 v[216:219], v155 offset:56320
	global_load_lds_dwordx4 v130, s[60:61] offset:128
	s_add_i32 m0, s26, 0x1f80
	s_add_u32 s26, s60, 0x20080
	s_addc_u32 s27, s61, 0
	s_add_i32 s33, s84, s66
	global_load_lds_dwordx4 v134, s[60:61] offset:128
	s_mov_b32 m0, s33
	s_nop 0
	global_load_lds_dwordx4 v130, s[26:27]
	s_add_i32 m0, s33, 0x2000
	s_nop 0
	global_load_lds_dwordx4 v134, s[26:27]
	s_add_i32 m0, s71, 0xffffff80
	s_nop 0
	global_load_lds_dwordx4 v128, s[62:63] offset:128
	s_add_i32 m0, s72, 0xffffff80
	s_nop 0
	global_load_lds_dwordx4 v132, s[62:63] offset:128
	s_waitcnt vmcnt(8)
	s_waitcnt lgkmcnt(0)
	s_barrier
; #define PG8_MMA(ai, bj, At, Bt) do { __builtin_amdgcn_s_setprio(1); _Pragma("unroll") for (int m = 0; m < 4; ++m) _Pragma("unroll") for (int n = 0; n < 2; ++n) _Pragma("unroll") for (int k = 0; k < 2; ++k) \
;         acc[ai][bj][m][n] = __builtin_amdgcn_mfma_f32_16x16x32_bf16(Bt[n][k], At[m][k], acc[ai][bj][m][n], 0, 0, 0); __builtin_amdgcn_s_setprio(0); } while (0)
; #define PG8_WAIT_V(n) asm volatile("s_waitcnt vmcnt(" #n ")" ::: "memory")
; #define PG8_WAIT_L(n) asm volatile("s_waitcnt lgkmcnt(" #n ")" ::: "memory")
; #define PG8_BAR __builtin_amdgcn_s_barrier()
; #define PG8_SCHED __builtin_amdgcn_sched_barrier(0)
; template <class Epi, class Sched, bool ALIGN_EPI = false, bool SP2 = false>
; __device__ __forceinline__ void gemm_phase(PG8_LAS unsigned char* lds, const Gemm g, const Sched& S, const Epi& E, int tid_in) {
;     ...
;             PG8_WAIT_V(8); PG8_WAIT_L(0); PG8_BAR; PG8_MMA(1, 0, At, B0); PG8_MMA(1, 1, At, B1); PG8_BAR; PG8_SCHED;
;     __device__ __forceinline__ void operator()(const f32x4 (&acc)[2][2][4][2], const Unit& u, int wr, int wc, int fr, int fq) const {
;     ...
;                 const int row = u.pm * BM + ai * HALF + wr * 64 + m * 16 + r; float q = 0.f;
; #pragma unroll
;                 for (int bj = 0; bj < 2; ++bj) {
;                     const size_t off = (size_t)row * 2048 + u.pn * BM + wc * 64 + bj * 32 + 8 * p;
;                     f32x4 b0, b1;
;                     if (BASE_F32) { b0 = *(const f32x4*)((const float*)base + off); b1 = *(const f32x4*)((const float*)base + off + 4); }
	s_setprio 1
	s_waitcnt lgkmcnt(0)
	v_mfma_f32_16x16x32_bf16 v[60:63], v[146:149], v[186:189], v[60:63]
	v_mfma_f32_16x16x32_bf16 v[56:59], v[162:165], v[186:189], v[56:59]
	v_mfma_f32_16x16x32_bf16 v[44:47], v[146:149], v[194:197], v[44:47]
	v_mfma_f32_16x16x32_bf16 v[40:43], v[162:165], v[194:197], v[40:43]
	v_mfma_f32_16x16x32_bf16 v[28:31], v[146:149], v[202:205], v[28:31]
	v_mfma_f32_16x16x32_bf16 v[24:27], v[162:165], v[202:205], v[24:27]
	v_mfma_f32_16x16x32_bf16 v[12:15], v[146:149], v[212:215], v[12:15]
	v_mfma_f32_16x16x32_bf16 v[8:11], v[162:165], v[212:215], v[8:11]
	v_mfma_f32_16x16x32_bf16 v[60:63], v[158:161], v[190:193], v[60:63]
	v_mfma_f32_16x16x32_bf16 v[56:59], v[166:169], v[190:193], v[56:59]
	v_mfma_f32_16x16x32_bf16 v[44:47], v[158:161], v[198:201], v[44:47]
	v_mfma_f32_16x16x32_bf16 v[40:43], v[166:169], v[198:201], v[40:43]
	v_mfma_f32_16x16x32_bf16 v[28:31], v[158:161], v[206:209], v[28:31]
	v_mfma_f32_16x16x32_bf16 v[24:27], v[166:169], v[206:209], v[24:27]
	v_mfma_f32_16x16x32_bf16 v[12:15], v[158:161], v[216:219], v[12:15]
	v_mfma_f32_16x16x32_bf16 v[8:11], v[166:169], v[216:219], v[8:11]
	s_setprio 0
	s_setprio 1
	v_mfma_f32_16x16x32_bf16 v[52:55], v[170:173], v[186:189], v[52:55]
	v_mfma_f32_16x16x32_bf16 v[48:51], v[178:181], v[186:189], v[48:51]
	v_mfma_f32_16x16x32_bf16 v[36:39], v[170:173], v[194:197], v[36:39]
	v_mfma_f32_16x16x32_bf16 v[32:35], v[178:181], v[194:197], v[32:35]
	v_mfma_f32_16x16x32_bf16 v[20:23], v[170:173], v[202:205], v[20:23]
	v_mfma_f32_16x16x32_bf16 v[16:19], v[178:181], v[202:205], v[16:19]
	v_mfma_f32_16x16x32_bf16 v[4:7], v[170:173], v[212:215], v[4:7]
	v_mfma_f32_16x16x32_bf16 v[0:3], v[178:181], v[212:215], v[0:3]
	v_mfma_f32_16x16x32_bf16 v[52:55], v[174:177], v[190:193], v[52:55]
	v_mfma_f32_16x16x32_bf16 v[48:51], v[182:185], v[190:193], v[48:51]
	v_mfma_f32_16x16x32_bf16 v[36:39], v[174:177], v[198:201], v[36:39]
	v_mfma_f32_16x16x32_bf16 v[32:35], v[182:185], v[198:201], v[32:35]
	v_mfma_f32_16x16x32_bf16 v[20:23], v[174:177], v[206:209], v[20:23]
	v_mfma_f32_16x16x32_bf16 v[16:19], v[182:185], v[206:209], v[16:19]
	v_mfma_f32_16x16x32_bf16 v[4:7], v[174:177], v[216:219], v[4:7]
	v_mfma_f32_16x16x32_bf16 v[0:3], v[182:185], v[216:219], v[0:3]
	s_setprio 0
	s_barrier
	s_add_i32 s79, s79, 2
	s_add_u32 s58, s58, 0x100
	s_addc_u32 s59, s59, 0
	s_add_u32 s76, s76, 0x100
	s_addc_u32 s77, s77, 0
	s_cmp_gt_u32 s79, 29
	s_cbranch_scc0 .LBB0_292
	v_lshl_add_u32 v148, s54, 8, v150
	v_lshl_or_b32 v146, s56, 8, v136
	v_lshl_add_u32 v147, v148, 11, v146
	v_lshlrev_b32_e32 v159, 1, v147
	v_lshlrev_b32_e32 v158, 2, v147
	v_lshlrev_b32_e32 v208, 3, v148
	global_load_dwordx4 v[160:163], v158, s[12:13]
	global_load_dwordx4 v[164:167], v158, s[12:13] offset:16
	global_load_dwordx4 v[168:171], v158, s[12:13] offset:128
	global_load_dwordx4 v[172:175], v158, s[12:13] offset:144
	v_add_u32_e32 v149, 0x20000, v158
	global_load_dwordx4 v[176:179], v149, s[12:13]
	global_load_dwordx4 v[180:183], v149, s[12:13] offset:16
	global_load_dwordx4 v[184:187], v149, s[12:13] offset:128
	global_load_dwordx4 v[188:191], v149, s[12:13] offset:144
	v_add_u32_e32 v209, 0x40000, v158
	global_load_dwordx4 v[192:195], v209, s[12:13]
	global_load_dwordx4 v[196:199], v209, s[12:13] offset:16
	global_load_dwordx4 v[200:203], v209, s[12:13] offset:128
	global_load_dwordx4 v[204:207], v209, s[12:13] offset:144
	v_add_u32_e32 v149, 0x60000, v158
	global_load_dwordx4 v[212:215], v149, s[12:13]
	global_load_dwordx4 v[216:219], v149, s[12:13] offset:16
	global_load_dwordx4 v[220:223], v149, s[12:13] offset:128
	global_load_dwordx4 v[224:227], v149, s[12:13] offset:144
	v_add_u32_e32 v209, 0x100000, v158
	global_load_dwordx4 v[228:231], v209, s[12:13]
	global_load_dwordx4 v[232:235], v209, s[12:13] offset:16
	global_load_dwordx4 v[236:239], v209, s[12:13] offset:128
	global_load_dwordx4 v[240:243], v209, s[12:13] offset:144
	s_and_b64 vcc, exec, s[44:45]
	s_cbranch_vccz .LBB0_295
	s_barrier

; #define PG8_STAGE(bufoff, gbase, voff) do { _Pragma("unroll") for (int _i = 0; _i < 2; ++_i) \
;         __builtin_amdgcn_global_load_lds((const unsigned*)((const char*)(gbase) + (voff)[_i]), (PG8_LAS unsigned*)(lds + (bufoff) + ldsw + _i * 8192), 16, 0, 0); } while (0)
; #define PG8_LDA(dst, b, h) do { _Pragma("unroll") for (int m = 0; m < 4; ++m) _Pragma("unroll") for (int k = 0; k < 2; ++k) dst[m][k] = *(const PG8_LAS bf16x8*)(lds + PG8_SA(b, h) + aoff + m * 2048 + k * 1024); } while (0)
; #define PG8_LDB(dst, b, h) do { _Pragma("unroll") for (int n = 0; n < 2; ++n) _Pragma("unroll") for (int k = 0; k < 2; ++k) dst[n][k] = *(const PG8_LAS bf16x8*)(lds + PG8_SB(b, h) + boff + n * 2048 + k * 1024); } while (0)
; #define PG8_WAIT_V(n) asm volatile("s_waitcnt vmcnt(" #n ")" ::: "memory")
; #define PG8_WAIT_L(n) asm volatile("s_waitcnt lgkmcnt(" #n ")" ::: "memory")
; #define PG8_BAR __builtin_amdgcn_s_barrier()
; #define PG8_SCHED __builtin_amdgcn_sched_barrier(0)
; template <class Epi, class Sched, bool ALIGN_EPI = false, bool SP2 = false>
; __device__ __forceinline__ void gemm_phase(PG8_LAS unsigned char* lds, const Gemm g, const Sched& S, const Epi& E, int tid_in) {
;     ...
;         const char* nA = has_next ? (const char*)g.A + (size_t)nxt.pm * tstep : cA; const char* nB = has_next ? (const char*)g.Bt + (size_t)nxt.pn * tstepB : cB;
;         for (int t = 0; t < nt; t += 2) {
;             const bool last = (t == nt - 2);
;             const char* a1 = cA + (size_t)(t + 1) * kstep;
;             const char* a2 = last ? nA : cA + (size_t)(t + 2) * kstep; const char* b2 = last ? nB : cB + (size_t)(t + 2) * kstep;
;             const char* a3 = a2 + kstep; const char* b3 = b2 + kstep;
;             if (last && has_next) S.a_ready(nxt);
;             if constexpr (SP2) {
;             PG8_LDB(B0, 0, 0); PG8_LDB(B1, 0, 1); PG8_SCHED; PG8_LDA(At, 0, 0); PG8_STAGE(PG8_SA(1, 1), a1 + hstep, voffA);
;             PG8_WAIT_V(8); PG8_WAIT_L(0); PG8_BAR; PG8_MMA(0, 0, At, B0); PG8_MMA(0, 1, At, B1); PG8_BAR; PG8_SCHED;
;             PG8_LDA(At, 0, 1); PG8_STAGE(PG8_SB(0, 0), b2, voffB); PG8_STAGE(PG8_SB(0, 1), b2 + hstepB, voffB); PG8_STAGE(PG8_SA(0, 0), a2, voffA);
;             PG8_WAIT_V(8); PG8_WAIT_L(0); PG8_BAR; PG8_MMA(1, 0, At, B0); PG8_MMA(1, 1, At, B1); PG8_BAR; PG8_SCHED;
.Lkb_skip_2:
.LBB0_394:
	ds_read_b128 v[156:159], v150
	ds_read_b128 v[160:163], v150 offset:1024
	ds_read_b128 v[164:167], v150 offset:2048
	ds_read_b128 v[168:171], v150 offset:3072
	ds_read_b128 v[172:175], v151
	ds_read_b128 v[176:179], v151 offset:1024
	ds_read_b128 v[180:183], v151 offset:2048
	ds_read_b128 v[184:187], v151 offset:3072
	s_add_u32 s26, s52, 0xfff80080
	s_addc_u32 s27, s53, -1
	s_cmp_eq_u32 s76, 28
	s_cselect_b32 s57, s45, s27
	s_cselect_b32 s56, s72, s26
	s_cselect_b32 s55, s43, s75
	s_cselect_b32 s54, s73, s74
	s_add_i32 m0, s51, 0xc000
	ds_read_b128 v[188:191], v152
	ds_read_b128 v[192:195], v152 offset:1024
	ds_read_b128 v[196:199], v152 offset:2048
	ds_read_b128 v[200:203], v152 offset:3072
	ds_read_b128 v[204:207], v152 offset:4096
	ds_read_b128 v[212:215], v152 offset:5120
	ds_read_b128 v[216:219], v152 offset:6144
	ds_read_b128 v[220:223], v152 offset:7168
	global_load_lds_dwordx4 v138, s[52:53]
	s_add_i32 m0, s51, 0xe000
	s_nop 0
	global_load_lds_dwordx4 v140, s[52:53]
	s_waitcnt vmcnt(8)
	s_waitcnt lgkmcnt(0)
	s_barrier
	s_setprio 1
	s_waitcnt lgkmcnt(0)
	v_mfma_f32_16x16x32_bf16 v[124:127], v[156:159], v[188:191], v[124:127]
	v_mfma_f32_16x16x32_bf16 v[120:123], v[164:167], v[188:191], v[120:123]
	v_mfma_f32_16x16x32_bf16 v[108:111], v[156:159], v[196:199], v[108:111]
	v_mfma_f32_16x16x32_bf16 v[104:107], v[164:167], v[196:199], v[104:107]
	v_mfma_f32_16x16x32_bf16 v[92:95], v[156:159], v[204:207], v[92:95]
	v_mfma_f32_16x16x32_bf16 v[88:91], v[164:167], v[204:207], v[88:91]
	v_mfma_f32_16x16x32_bf16 v[76:79], v[156:159], v[216:219], v[76:79]
	v_mfma_f32_16x16x32_bf16 v[72:75], v[164:167], v[216:219], v[72:75]
	v_mfma_f32_16x16x32_bf16 v[124:127], v[160:163], v[192:195], v[124:127]
	v_mfma_f32_16x16x32_bf16 v[120:123], v[168:171], v[192:195], v[120:123]
	v_mfma_f32_16x16x32_bf16 v[108:111], v[160:163], v[200:203], v[108:111]
	v_mfma_f32_16x16x32_bf16 v[104:107], v[168:171], v[200:203], v[104:107]
	v_mfma_f32_16x16x32_bf16 v[92:95], v[160:163], v[212:215], v[92:95]
	v_mfma_f32_16x16x32_bf16 v[88:91], v[168:171], v[212:215], v[88:91]
	v_mfma_f32_16x16x32_bf16 v[76:79], v[160:163], v[220:223], v[76:79]
	v_mfma_f32_16x16x32_bf16 v[72:75], v[168:171], v[220:223], v[72:75]
	s_setprio 0
	s_setprio 1
	v_mfma_f32_16x16x32_bf16 v[116:119], v[172:175], v[188:191], v[116:119]
	v_mfma_f32_16x16x32_bf16 v[112:115], v[180:183], v[188:191], v[112:115]
	v_mfma_f32_16x16x32_bf16 v[100:103], v[172:175], v[196:199], v[100:103]
	v_mfma_f32_16x16x32_bf16 v[96:99], v[180:183], v[196:199], v[96:99]
	v_mfma_f32_16x16x32_bf16 v[84:87], v[172:175], v[204:207], v[84:87]
	v_mfma_f32_16x16x32_bf16 v[80:83], v[180:183], v[204:207], v[80:83]
	v_mfma_f32_16x16x32_bf16 v[68:71], v[172:175], v[216:219], v[68:71]
	v_mfma_f32_16x16x32_bf16 v[64:67], v[180:183], v[216:219], v[64:67]
	v_mfma_f32_16x16x32_bf16 v[116:119], v[176:179], v[192:195], v[116:119]
	v_mfma_f32_16x16x32_bf16 v[112:115], v[184:187], v[192:195], v[112:115]
	v_mfma_f32_16x16x32_bf16 v[100:103], v[176:179], v[200:203], v[100:103]
	v_mfma_f32_16x16x32_bf16 v[96:99], v[184:187], v[200:203], v[96:99]
	v_mfma_f32_16x16x32_bf16 v[84:87], v[176:179], v[212:215], v[84:87]
	v_mfma_f32_16x16x32_bf16 v[80:83], v[184:187], v[212:215], v[80:83]
	v_mfma_f32_16x16x32_bf16 v[68:71], v[176:179], v[220:223], v[68:71]
	v_mfma_f32_16x16x32_bf16 v[64:67], v[184:187], v[220:223], v[64:67]
	s_setprio 0
	s_barrier
	s_add_i32 s26, s68, s60
	s_mov_b32 m0, s26
	ds_read_b128 v[188:191], v152 offset:16384
	ds_read_b128 v[192:195], v152 offset:17408
	ds_read_b128 v[196:199], v152 offset:18432
	ds_read_b128 v[200:203], v152 offset:19456
	ds_read_b128 v[204:207], v152 offset:20480
	ds_read_b128 v[212:215], v152 offset:21504
	ds_read_b128 v[216:219], v152 offset:22528
	ds_read_b128 v[220:223], v152 offset:23552
	global_load_lds_dwordx4 v130, s[54:55]
	s_add_i32 m0, s26, 0x2000
	s_add_u32 s26, s54, 0x20000
	s_addc_u32 s27, s55, 0
	s_add_i32 s33, s69, s60
	global_load_lds_dwordx4 v134, s[54:55]
	s_mov_b32 m0, s33
	s_nop 0
	global_load_lds_dwordx4 v130, s[26:27]
	s_add_i32 m0, s33, 0x2000
	s_nop 0
	global_load_lds_dwordx4 v134, s[26:27]
	s_mov_b32 m0, s51
	s_nop 0
	global_load_lds_dwordx4 v128, s[56:57]
	s_mov_b32 m0, s61
	s_nop 0
	global_load_lds_dwordx4 v132, s[56:57]
	s_waitcnt vmcnt(8)
	s_waitcnt lgkmcnt(0)
	s_barrier
	s_setprio 1
	s_waitcnt lgkmcnt(0)
	v_mfma_f32_16x16x32_bf16 v[60:63], v[156:159], v[188:191], v[60:63]
	v_mfma_f32_16x16x32_bf16 v[56:59], v[164:167], v[188:191], v[56:59]
	v_mfma_f32_16x16x32_bf16 v[44:47], v[156:159], v[196:199], v[44:47]
	v_mfma_f32_16x16x32_bf16 v[40:43], v[164:167], v[196:199], v[40:43]
	v_mfma_f32_16x16x32_bf16 v[28:31], v[156:159], v[204:207], v[28:31]
	v_mfma_f32_16x16x32_bf16 v[24:27], v[164:167], v[204:207], v[24:27]
	v_mfma_f32_16x16x32_bf16 v[12:15], v[156:159], v[216:219], v[12:15]
	v_mfma_f32_16x16x32_bf16 v[8:11], v[164:167], v[216:219], v[8:11]
	v_mfma_f32_16x16x32_bf16 v[60:63], v[160:163], v[192:195], v[60:63]
	v_mfma_f32_16x16x32_bf16 v[56:59], v[168:171], v[192:195], v[56:59]
	v_mfma_f32_16x16x32_bf16 v[44:47], v[160:163], v[200:203], v[44:47]
	v_mfma_f32_16x16x32_bf16 v[40:43], v[168:171], v[200:203], v[40:43]
	v_mfma_f32_16x16x32_bf16 v[28:31], v[160:163], v[212:215], v[28:31]
	v_mfma_f32_16x16x32_bf16 v[24:27], v[168:171], v[212:215], v[24:27]
	v_mfma_f32_16x16x32_bf16 v[12:15], v[160:163], v[220:223], v[12:15]
	v_mfma_f32_16x16x32_bf16 v[8:11], v[168:171], v[220:223], v[8:11]
	s_setprio 0
	s_setprio 1
	v_mfma_f32_16x16x32_bf16 v[52:55], v[172:175], v[188:191], v[52:55]
	v_mfma_f32_16x16x32_bf16 v[48:51], v[180:183], v[188:191], v[48:51]
	v_mfma_f32_16x16x32_bf16 v[36:39], v[172:175], v[196:199], v[36:39]
	v_mfma_f32_16x16x32_bf16 v[32:35], v[180:183], v[196:199], v[32:35]
	v_mfma_f32_16x16x32_bf16 v[20:23], v[172:175], v[204:207], v[20:23]
	v_mfma_f32_16x16x32_bf16 v[16:19], v[180:183], v[204:207], v[16:19]
	v_mfma_f32_16x16x32_bf16 v[4:7], v[172:175], v[216:219], v[4:7]
	v_mfma_f32_16x16x32_bf16 v[0:3], v[180:183], v[216:219], v[0:3]
	v_mfma_f32_16x16x32_bf16 v[52:55], v[176:179], v[192:195], v[52:55]
	v_mfma_f32_16x16x32_bf16 v[48:51], v[184:187], v[192:195], v[48:51]
	v_mfma_f32_16x16x32_bf16 v[36:39], v[176:179], v[200:203], v[36:39]
	v_mfma_f32_16x16x32_bf16 v[32:35], v[184:187], v[200:203], v[32:35]
	v_mfma_f32_16x16x32_bf16 v[20:23], v[176:179], v[212:215], v[20:23]
	v_mfma_f32_16x16x32_bf16 v[16:19], v[184:187], v[212:215], v[16:19]
	v_mfma_f32_16x16x32_bf16 v[4:7], v[176:179], v[220:223], v[4:7]
	v_mfma_f32_16x16x32_bf16 v[0:3], v[184:187], v[220:223], v[0:3]
	s_setprio 0
	s_barrier
; #define PG8_STAGE(bufoff, gbase, voff) do { _Pragma("unroll") for (int _i = 0; _i < 2; ++_i) \
;         __builtin_amdgcn_global_load_lds((const unsigned*)((const char*)(gbase) + (voff)[_i]), (PG8_LAS unsigned*)(lds + (bufoff) + ldsw + _i * 8192), 16, 0, 0); } while (0)
; #define PG8_BAR __builtin_amdgcn_s_barrier()
; template <class Epi, class Sched, bool ALIGN_EPI = false, bool SP2 = false>
; __device__ __forceinline__ void gemm_phase(PG8_LAS unsigned char* lds, const Gemm g, const Sched& S, const Epi& E, int tid_in) {
;     ...
;             PG8_LDB(B0, 1, 0); PG8_LDB(B1, 1, 1); PG8_SCHED; PG8_LDA(At, 1, 0); PG8_STAGE(PG8_SA(0, 1), a2 + hstep, voffA);
;             PG8_WAIT_V(8); PG8_WAIT_L(0); PG8_BAR; PG8_MMA(0, 0, At, B0); PG8_MMA(0, 1, At, B1); PG8_BAR; PG8_SCHED;
;             PG8_LDA(At, 1, 1); PG8_STAGE(PG8_SB(1, 0), b3, voffB); PG8_STAGE(PG8_SB(1, 1), b3 + hstepB, voffB); PG8_STAGE(PG8_SA(1, 0), a3, voffA);
;             PG8_WAIT_V(8); PG8_WAIT_L(0); PG8_BAR; PG8_MMA(1, 0, At, B0); PG8_MMA(1, 1, At, B1); PG8_BAR; PG8_SCHED;
;             } else {
;             PG8_LDB(B0, 0, 0); PG8_SCHED; PG8_LDA(At, 0, 0); PG8_STAGE(PG8_SA(1, 1), a1 + hstep, voffA);
;             PG8_WAIT_L(8); PG8_BAR; PG8_WAIT_L(0); PG8_MMA(0, 0, At, B0); PG8_BAR; PG8_SCHED;
;             PG8_LDB(B1, 0, 1); PG8_STAGE(PG8_SB(0, 0), b2, voffB);
;             PG8_BAR; PG8_WAIT_L(0); PG8_MMA(0, 1, At, B1); PG8_BAR;
;             PG8_LDA(At, 0, 1); PG8_STAGE(PG8_SA(0, 0), a2, voffA);
;             PG8_BAR; PG8_WAIT_L(0); PG8_MMA(1, 0, At, B0); PG8_BAR; PG8_SCHED;
;             PG8_STAGE(PG8_SB(0, 1), b2 + hstepB, voffB);
;             PG8_WAIT_V(6); PG8_BAR; PG8_MMA(1, 1, At, B1); PG8_BAR;
;             PG8_LDB(B0, 1, 0); PG8_SCHED; PG8_LDA(At, 1, 0); PG8_STAGE(PG8_SA(0, 1), a2 + hstep, voffA);
;             PG8_WAIT_L(8); PG8_BAR; PG8_WAIT_L(0); PG8_MMA(0, 0, At, B0); PG8_BAR; PG8_SCHED;
;             PG8_LDB(B1, 1, 1); PG8_STAGE(PG8_SB(1, 0), b3, voffB);
;             PG8_BAR; PG8_WAIT_L(0); PG8_MMA(0, 1, At, B1); PG8_BAR;
;             PG8_LDA(At, 1, 1); PG8_STAGE(PG8_SA(1, 0), a3, voffA);
;             PG8_BAR; PG8_WAIT_L(0); PG8_MMA(1, 0, At, B0); PG8_BAR; PG8_SCHED;
;             PG8_STAGE(PG8_SB(1, 1), b3 + hstepB, voffB);
;             PG8_WAIT_V(6); PG8_BAR; PG8_MMA(1, 1, At, B1); PG8_BAR;
;             }
;         }
;         if constexpr (ALIGN_EPI) { if (wr == 0) PG8_BAR; }
	s_add_i32 s33, 0, 0x18000
	v_add_u32_e32 v155, s33, v146
	s_add_i32 s77, 0, 0x1c000
	ds_read_b128 v[156:159], v155
	ds_read_b128 v[160:163], v155 offset:1024
	ds_read_b128 v[164:167], v155 offset:2048
	ds_read_b128 v[168:171], v155 offset:3072
	v_add_u32_e32 v155, s77, v146
	ds_read_b128 v[172:175], v155
	ds_read_b128 v[176:179], v155 offset:1024
	ds_read_b128 v[180:183], v155 offset:2048
	ds_read_b128 v[184:187], v155 offset:3072
	s_add_u32 s26, s56, 0x80000
	s_addc_u32 s27, s57, 0
	s_mov_b32 m0, s62
	ds_read_b128 v[188:191], v152 offset:32768
	ds_read_b128 v[192:195], v152 offset:33792
	ds_read_b128 v[196:199], v152 offset:34816
	ds_read_b128 v[200:203], v152 offset:35840
	ds_read_b128 v[204:207], v152 offset:36864
	ds_read_b128 v[212:215], v152 offset:37888
	ds_read_b128 v[216:219], v152 offset:38912
	ds_read_b128 v[220:223], v152 offset:39936
	global_load_lds_dwordx4 v128, s[26:27]
	s_mov_b32 m0, s63
	s_nop 0
	global_load_lds_dwordx4 v132, s[26:27]
	s_waitcnt vmcnt(8)
	s_waitcnt lgkmcnt(0)
	s_barrier
	s_setprio 1
	s_waitcnt lgkmcnt(0)
	v_mfma_f32_16x16x32_bf16 v[124:127], v[156:159], v[188:191], v[124:127]
	v_mfma_f32_16x16x32_bf16 v[120:123], v[164:167], v[188:191], v[120:123]
	v_mfma_f32_16x16x32_bf16 v[108:111], v[156:159], v[196:199], v[108:111]
	v_mfma_f32_16x16x32_bf16 v[104:107], v[164:167], v[196:199], v[104:107]
	v_mfma_f32_16x16x32_bf16 v[92:95], v[156:159], v[204:207], v[92:95]
	v_mfma_f32_16x16x32_bf16 v[88:91], v[164:167], v[204:207], v[88:91]
	v_mfma_f32_16x16x32_bf16 v[76:79], v[156:159], v[216:219], v[76:79]
	v_mfma_f32_16x16x32_bf16 v[72:75], v[164:167], v[216:219], v[72:75]
	v_mfma_f32_16x16x32_bf16 v[124:127], v[160:163], v[192:195], v[124:127]
	v_mfma_f32_16x16x32_bf16 v[120:123], v[168:171], v[192:195], v[120:123]
	v_mfma_f32_16x16x32_bf16 v[108:111], v[160:163], v[200:203], v[108:111]
	v_mfma_f32_16x16x32_bf16 v[104:107], v[168:171], v[200:203], v[104:107]
	v_mfma_f32_16x16x32_bf16 v[92:95], v[160:163], v[212:215], v[92:95]
	v_mfma_f32_16x16x32_bf16 v[88:91], v[168:171], v[212:215], v[88:91]
	v_mfma_f32_16x16x32_bf16 v[76:79], v[160:163], v[220:223], v[76:79]
	v_mfma_f32_16x16x32_bf16 v[72:75], v[168:171], v[220:223], v[72:75]
	s_setprio 0
	s_setprio 1
	v_mfma_f32_16x16x32_bf16 v[116:119], v[172:175], v[188:191], v[116:119]
	v_mfma_f32_16x16x32_bf16 v[112:115], v[180:183], v[188:191], v[112:115]
	v_mfma_f32_16x16x32_bf16 v[100:103], v[172:175], v[196:199], v[100:103]
	v_mfma_f32_16x16x32_bf16 v[96:99], v[180:183], v[196:199], v[96:99]
	v_mfma_f32_16x16x32_bf16 v[84:87], v[172:175], v[204:207], v[84:87]
	v_mfma_f32_16x16x32_bf16 v[80:83], v[180:183], v[204:207], v[80:83]
	v_mfma_f32_16x16x32_bf16 v[68:71], v[172:175], v[216:219], v[68:71]
	v_mfma_f32_16x16x32_bf16 v[64:67], v[180:183], v[216:219], v[64:67]
	v_mfma_f32_16x16x32_bf16 v[116:119], v[176:179], v[192:195], v[116:119]
	v_mfma_f32_16x16x32_bf16 v[112:115], v[184:187], v[192:195], v[112:115]
	v_mfma_f32_16x16x32_bf16 v[100:103], v[176:179], v[200:203], v[100:103]
	v_mfma_f32_16x16x32_bf16 v[96:99], v[184:187], v[200:203], v[96:99]
	v_mfma_f32_16x16x32_bf16 v[84:87], v[176:179], v[212:215], v[84:87]
	v_mfma_f32_16x16x32_bf16 v[80:83], v[184:187], v[212:215], v[80:83]
	v_mfma_f32_16x16x32_bf16 v[68:71], v[176:179], v[220:223], v[68:71]
	v_mfma_f32_16x16x32_bf16 v[64:67], v[184:187], v[220:223], v[64:67]
	s_setprio 0
	s_barrier
	s_add_i32 s26, s33, s60
	s_add_i32 m0, s26, 0xffffff80
	ds_read_b128 v[188:191], v152 offset:49152
	ds_read_b128 v[192:195], v152 offset:50176
	ds_read_b128 v[196:199], v152 offset:51200
	ds_read_b128 v[200:203], v152 offset:52224
	ds_read_b128 v[204:207], v152 offset:53248
	ds_read_b128 v[212:215], v152 offset:54272
	ds_read_b128 v[216:219], v152 offset:55296
	ds_read_b128 v[220:223], v152 offset:56320
	global_load_lds_dwordx4 v130, s[54:55] offset:128
	s_add_i32 m0, s26, 0x1f80
	s_add_u32 s26, s54, 0x20080
	s_addc_u32 s27, s55, 0
	s_add_i32 s33, s77, s60
	global_load_lds_dwordx4 v134, s[54:55] offset:128
	s_mov_b32 m0, s33
	s_nop 0
	global_load_lds_dwordx4 v130, s[26:27]
	s_add_i32 m0, s33, 0x2000
	s_nop 0
	global_load_lds_dwordx4 v134, s[26:27]
	s_add_i32 m0, s66, 0xffffff80
	s_nop 0
	global_load_lds_dwordx4 v128, s[56:57] offset:128
	s_add_i32 m0, s67, 0xffffff80
	s_nop 0
	global_load_lds_dwordx4 v132, s[56:57] offset:128
	s_waitcnt vmcnt(8)
	s_waitcnt lgkmcnt(0)
	s_barrier
	s_setprio 1
	s_waitcnt lgkmcnt(0)
	v_mfma_f32_16x16x32_bf16 v[60:63], v[156:159], v[188:191], v[60:63]
	v_mfma_f32_16x16x32_bf16 v[56:59], v[164:167], v[188:191], v[56:59]
	v_mfma_f32_16x16x32_bf16 v[44:47], v[156:159], v[196:199], v[44:47]
	v_mfma_f32_16x16x32_bf16 v[40:43], v[164:167], v[196:199], v[40:43]
	v_mfma_f32_16x16x32_bf16 v[28:31], v[156:159], v[204:207], v[28:31]
	v_mfma_f32_16x16x32_bf16 v[24:27], v[164:167], v[204:207], v[24:27]
	v_mfma_f32_16x16x32_bf16 v[12:15], v[156:159], v[216:219], v[12:15]
	v_mfma_f32_16x16x32_bf16 v[8:11], v[164:167], v[216:219], v[8:11]
	v_mfma_f32_16x16x32_bf16 v[60:63], v[160:163], v[192:195], v[60:63]
	v_mfma_f32_16x16x32_bf16 v[56:59], v[168:171], v[192:195], v[56:59]
	v_mfma_f32_16x16x32_bf16 v[44:47], v[160:163], v[200:203], v[44:47]
	v_mfma_f32_16x16x32_bf16 v[40:43], v[168:171], v[200:203], v[40:43]
	v_mfma_f32_16x16x32_bf16 v[28:31], v[160:163], v[212:215], v[28:31]
	v_mfma_f32_16x16x32_bf16 v[24:27], v[168:171], v[212:215], v[24:27]
	v_mfma_f32_16x16x32_bf16 v[12:15], v[160:163], v[220:223], v[12:15]
	v_mfma_f32_16x16x32_bf16 v[8:11], v[168:171], v[220:223], v[8:11]
	s_setprio 0
	s_setprio 1
	v_mfma_f32_16x16x32_bf16 v[52:55], v[172:175], v[188:191], v[52:55]
	v_mfma_f32_16x16x32_bf16 v[48:51], v[180:183], v[188:191], v[48:51]
	v_mfma_f32_16x16x32_bf16 v[36:39], v[172:175], v[196:199], v[36:39]
	v_mfma_f32_16x16x32_bf16 v[32:35], v[180:183], v[196:199], v[32:35]
	v_mfma_f32_16x16x32_bf16 v[20:23], v[172:175], v[204:207], v[20:23]
	v_mfma_f32_16x16x32_bf16 v[16:19], v[180:183], v[204:207], v[16:19]
	v_mfma_f32_16x16x32_bf16 v[4:7], v[172:175], v[216:219], v[4:7]
	v_mfma_f32_16x16x32_bf16 v[0:3], v[180:183], v[216:219], v[0:3]
	v_mfma_f32_16x16x32_bf16 v[52:55], v[176:179], v[192:195], v[52:55]
	v_mfma_f32_16x16x32_bf16 v[48:51], v[184:187], v[192:195], v[48:51]
	v_mfma_f32_16x16x32_bf16 v[36:39], v[176:179], v[200:203], v[36:39]
	v_mfma_f32_16x16x32_bf16 v[32:35], v[184:187], v[200:203], v[32:35]
	v_mfma_f32_16x16x32_bf16 v[20:23], v[176:179], v[212:215], v[20:23]
	v_mfma_f32_16x16x32_bf16 v[16:19], v[184:187], v[212:215], v[16:19]
	v_mfma_f32_16x16x32_bf16 v[4:7], v[176:179], v[220:223], v[4:7]
	v_mfma_f32_16x16x32_bf16 v[0:3], v[184:187], v[220:223], v[0:3]
	s_setprio 0
	s_barrier
	s_add_i32 s76, s76, 2
	s_add_u32 s52, s52, 0x100
	s_addc_u32 s53, s53, 0
	s_add_u32 s74, s74, 0x100
	s_addc_u32 s75, s75, 0
	s_cmp_gt_u32 s76, 29
	s_cbranch_scc0 .LBB0_394
	s_and_b64 vcc, exec, s[14:15]
	s_cbranch_vccz .LBB0_397
	s_barrier

; #define PG8_STAGE(bufoff, gbase, voff) do { _Pragma("unroll") for (int _i = 0; _i < 2; ++_i) \
;         __builtin_amdgcn_global_load_lds((const unsigned*)((const char*)(gbase) + (voff)[_i]), (PG8_LAS unsigned*)(lds + (bufoff) + ldsw + _i * 8192), 16, 0, 0); } while (0)
; #define PG8_LDA(dst, b, h) do { _Pragma("unroll") for (int m = 0; m < 4; ++m) _Pragma("unroll") for (int k = 0; k < 2; ++k) dst[m][k] = *(const PG8_LAS bf16x8*)(lds + PG8_SA(b, h) + aoff + m * 2048 + k * 1024); } while (0)
; #define PG8_LDB(dst, b, h) do { _Pragma("unroll") for (int n = 0; n < 2; ++n) _Pragma("unroll") for (int k = 0; k < 2; ++k) dst[n][k] = *(const PG8_LAS bf16x8*)(lds + PG8_SB(b, h) + boff + n * 2048 + k * 1024); } while (0)
; #define PG8_WAIT_V(n) asm volatile("s_waitcnt vmcnt(" #n ")" ::: "memory")
; #define PG8_WAIT_L(n) asm volatile("s_waitcnt lgkmcnt(" #n ")" ::: "memory")
; #define PG8_BAR __builtin_amdgcn_s_barrier()
; #define PG8_SCHED __builtin_amdgcn_sched_barrier(0)
; template <class Epi, class Sched, bool ALIGN_EPI = false, bool SP2 = false>
; __device__ __forceinline__ void gemm_phase(PG8_LAS unsigned char* lds, const Gemm g, const Sched& S, const Epi& E, int tid_in) {
;     ...
;         const char* nA = has_next ? (const char*)g.A + (size_t)nxt.pm * tstep : cA; const char* nB = has_next ? (const char*)g.Bt + (size_t)nxt.pn * tstepB : cB;
;         for (int t = 0; t < nt; t += 2) {
;             const bool last = (t == nt - 2);
;             const char* a1 = cA + (size_t)(t + 1) * kstep;
;             const char* a2 = last ? nA : cA + (size_t)(t + 2) * kstep; const char* b2 = last ? nB : cB + (size_t)(t + 2) * kstep;
;             const char* a3 = a2 + kstep; const char* b3 = b2 + kstep;
;             if (last && has_next) S.a_ready(nxt);
;             if constexpr (SP2) {
;             PG8_LDB(B0, 0, 0); PG8_LDB(B1, 0, 1); PG8_SCHED; PG8_LDA(At, 0, 0); PG8_STAGE(PG8_SA(1, 1), a1 + hstep, voffA);
;             PG8_WAIT_V(8); PG8_WAIT_L(0); PG8_BAR; PG8_MMA(0, 0, At, B0); PG8_MMA(0, 1, At, B1); PG8_BAR; PG8_SCHED;
;             PG8_LDA(At, 0, 1); PG8_STAGE(PG8_SB(0, 0), b2, voffB); PG8_STAGE(PG8_SB(0, 1), b2 + hstepB, voffB); PG8_STAGE(PG8_SA(0, 0), a2, voffA);
;             PG8_WAIT_V(8); PG8_WAIT_L(0); PG8_BAR; PG8_MMA(1, 0, At, B0); PG8_MMA(1, 1, At, B1); PG8_BAR; PG8_SCHED;
.Lkb_skip_3:
.LBB0_474:
	ds_read_b128 v[146:149], v153
	ds_read_b128 v[158:161], v153 offset:1024
	ds_read_b128 v[162:165], v153 offset:2048
	ds_read_b128 v[166:169], v153 offset:3072
	ds_read_b128 v[170:173], v154
	ds_read_b128 v[174:177], v154 offset:1024
	ds_read_b128 v[178:181], v154 offset:2048
	ds_read_b128 v[182:185], v154 offset:3072
	s_add_u32 s12, s56, 0x100
	s_addc_u32 s13, s57, 0
	s_cmpk_eq_i32 s79, 0x7c
	s_cselect_b32 s61, s51, s13
	s_cselect_b32 s60, s50, s12
	s_cselect_b32 s59, s49, s77
	s_cselect_b32 s58, s75, s76
	s_add_i32 m0, s55, 0xc000
	ds_read_b128 v[186:189], v155
	ds_read_b128 v[190:193], v155 offset:1024
	ds_read_b128 v[194:197], v155 offset:2048
	ds_read_b128 v[198:201], v155 offset:3072
	ds_read_b128 v[202:205], v155 offset:4096
	ds_read_b128 v[206:209], v155 offset:5120
	ds_read_b128 v[212:215], v155 offset:6144
	ds_read_b128 v[216:219], v155 offset:7168
	global_load_lds_dwordx4 v138, s[56:57]
	s_add_i32 m0, s55, 0xe000
	s_nop 0
	global_load_lds_dwordx4 v140, s[56:57]
	s_waitcnt vmcnt(8)
	s_waitcnt lgkmcnt(0)
	s_barrier
	s_setprio 1
	s_waitcnt lgkmcnt(0)
	v_mfma_f32_16x16x32_bf16 v[124:127], v[146:149], v[186:189], v[124:127]
	v_mfma_f32_16x16x32_bf16 v[120:123], v[162:165], v[186:189], v[120:123]
	v_mfma_f32_16x16x32_bf16 v[108:111], v[146:149], v[194:197], v[108:111]
	v_mfma_f32_16x16x32_bf16 v[104:107], v[162:165], v[194:197], v[104:107]
	v_mfma_f32_16x16x32_bf16 v[92:95], v[146:149], v[202:205], v[92:95]
	v_mfma_f32_16x16x32_bf16 v[88:91], v[162:165], v[202:205], v[88:91]
	v_mfma_f32_16x16x32_bf16 v[76:79], v[146:149], v[212:215], v[76:79]
	v_mfma_f32_16x16x32_bf16 v[72:75], v[162:165], v[212:215], v[72:75]
	v_mfma_f32_16x16x32_bf16 v[124:127], v[158:161], v[190:193], v[124:127]
	v_mfma_f32_16x16x32_bf16 v[120:123], v[166:169], v[190:193], v[120:123]
	v_mfma_f32_16x16x32_bf16 v[108:111], v[158:161], v[198:201], v[108:111]
	v_mfma_f32_16x16x32_bf16 v[104:107], v[166:169], v[198:201], v[104:107]
	v_mfma_f32_16x16x32_bf16 v[92:95], v[158:161], v[206:209], v[92:95]
	v_mfma_f32_16x16x32_bf16 v[88:91], v[166:169], v[206:209], v[88:91]
	v_mfma_f32_16x16x32_bf16 v[76:79], v[158:161], v[216:219], v[76:79]
	v_mfma_f32_16x16x32_bf16 v[72:75], v[166:169], v[216:219], v[72:75]
	s_setprio 0
	s_setprio 1
	v_mfma_f32_16x16x32_bf16 v[116:119], v[170:173], v[186:189], v[116:119]
	v_mfma_f32_16x16x32_bf16 v[112:115], v[178:181], v[186:189], v[112:115]
	v_mfma_f32_16x16x32_bf16 v[100:103], v[170:173], v[194:197], v[100:103]
	v_mfma_f32_16x16x32_bf16 v[96:99], v[178:181], v[194:197], v[96:99]
	v_mfma_f32_16x16x32_bf16 v[84:87], v[170:173], v[202:205], v[84:87]
	v_mfma_f32_16x16x32_bf16 v[80:83], v[178:181], v[202:205], v[80:83]
	v_mfma_f32_16x16x32_bf16 v[68:71], v[170:173], v[212:215], v[68:71]
	v_mfma_f32_16x16x32_bf16 v[64:67], v[178:181], v[212:215], v[64:67]
	v_mfma_f32_16x16x32_bf16 v[116:119], v[174:177], v[190:193], v[116:119]
	v_mfma_f32_16x16x32_bf16 v[112:115], v[182:185], v[190:193], v[112:115]
	v_mfma_f32_16x16x32_bf16 v[100:103], v[174:177], v[198:201], v[100:103]
	v_mfma_f32_16x16x32_bf16 v[96:99], v[182:185], v[198:201], v[96:99]
	v_mfma_f32_16x16x32_bf16 v[84:87], v[174:177], v[206:209], v[84:87]
	v_mfma_f32_16x16x32_bf16 v[80:83], v[182:185], v[206:209], v[80:83]
	v_mfma_f32_16x16x32_bf16 v[68:71], v[174:177], v[216:219], v[68:71]
	v_mfma_f32_16x16x32_bf16 v[64:67], v[182:185], v[216:219], v[64:67]
	s_setprio 0
	s_barrier
	s_add_i32 s26, s71, s64
	s_mov_b32 m0, s26
	ds_read_b128 v[186:189], v155 offset:16384
	ds_read_b128 v[190:193], v155 offset:17408
	ds_read_b128 v[194:197], v155 offset:18432
	ds_read_b128 v[198:201], v155 offset:19456
	ds_read_b128 v[202:205], v155 offset:20480
	ds_read_b128 v[206:209], v155 offset:21504
	ds_read_b128 v[212:215], v155 offset:22528
	ds_read_b128 v[216:219], v155 offset:23552
	global_load_lds_dwordx4 v130, s[58:59]
	s_add_i32 m0, s26, 0x2000
	s_add_u32 s26, s58, 0x80000
	s_addc_u32 s27, s59, 0
	s_add_i32 s33, s72, s64
	global_load_lds_dwordx4 v134, s[58:59]
	s_mov_b32 m0, s33
	s_nop 0
	global_load_lds_dwordx4 v130, s[26:27]
	s_add_i32 m0, s33, 0x2000
	s_nop 0
	global_load_lds_dwordx4 v134, s[26:27]
	s_mov_b32 m0, s55
	s_nop 0
	global_load_lds_dwordx4 v128, s[60:61]
	s_mov_b32 m0, s65
	s_nop 0
	global_load_lds_dwordx4 v132, s[60:61]
	s_waitcnt vmcnt(8)
	s_waitcnt lgkmcnt(0)
	s_barrier
	s_setprio 1
	s_waitcnt lgkmcnt(0)
	v_mfma_f32_16x16x32_bf16 v[60:63], v[146:149], v[186:189], v[60:63]
	v_mfma_f32_16x16x32_bf16 v[56:59], v[162:165], v[186:189], v[56:59]
	v_mfma_f32_16x16x32_bf16 v[44:47], v[146:149], v[194:197], v[44:47]
	v_mfma_f32_16x16x32_bf16 v[40:43], v[162:165], v[194:197], v[40:43]
	v_mfma_f32_16x16x32_bf16 v[28:31], v[146:149], v[202:205], v[28:31]
	v_mfma_f32_16x16x32_bf16 v[24:27], v[162:165], v[202:205], v[24:27]
	v_mfma_f32_16x16x32_bf16 v[12:15], v[146:149], v[212:215], v[12:15]
	v_mfma_f32_16x16x32_bf16 v[8:11], v[162:165], v[212:215], v[8:11]
	v_mfma_f32_16x16x32_bf16 v[60:63], v[158:161], v[190:193], v[60:63]
	v_mfma_f32_16x16x32_bf16 v[56:59], v[166:169], v[190:193], v[56:59]
	v_mfma_f32_16x16x32_bf16 v[44:47], v[158:161], v[198:201], v[44:47]
	v_mfma_f32_16x16x32_bf16 v[40:43], v[166:169], v[198:201], v[40:43]
	v_mfma_f32_16x16x32_bf16 v[28:31], v[158:161], v[206:209], v[28:31]
	v_mfma_f32_16x16x32_bf16 v[24:27], v[166:169], v[206:209], v[24:27]
	v_mfma_f32_16x16x32_bf16 v[12:15], v[158:161], v[216:219], v[12:15]
	v_mfma_f32_16x16x32_bf16 v[8:11], v[166:169], v[216:219], v[8:11]
	s_setprio 0
	s_setprio 1
	v_mfma_f32_16x16x32_bf16 v[52:55], v[170:173], v[186:189], v[52:55]
	v_mfma_f32_16x16x32_bf16 v[48:51], v[178:181], v[186:189], v[48:51]
	v_mfma_f32_16x16x32_bf16 v[36:39], v[170:173], v[194:197], v[36:39]
	v_mfma_f32_16x16x32_bf16 v[32:35], v[178:181], v[194:197], v[32:35]
	v_mfma_f32_16x16x32_bf16 v[20:23], v[170:173], v[202:205], v[20:23]
	v_mfma_f32_16x16x32_bf16 v[16:19], v[178:181], v[202:205], v[16:19]
	v_mfma_f32_16x16x32_bf16 v[4:7], v[170:173], v[212:215], v[4:7]
	v_mfma_f32_16x16x32_bf16 v[0:3], v[178:181], v[212:215], v[0:3]
	v_mfma_f32_16x16x32_bf16 v[52:55], v[174:177], v[190:193], v[52:55]
	v_mfma_f32_16x16x32_bf16 v[48:51], v[182:185], v[190:193], v[48:51]
	v_mfma_f32_16x16x32_bf16 v[36:39], v[174:177], v[198:201], v[36:39]
	v_mfma_f32_16x16x32_bf16 v[32:35], v[182:185], v[198:201], v[32:35]
	v_mfma_f32_16x16x32_bf16 v[20:23], v[174:177], v[206:209], v[20:23]
	v_mfma_f32_16x16x32_bf16 v[16:19], v[182:185], v[206:209], v[16:19]
	v_mfma_f32_16x16x32_bf16 v[4:7], v[174:177], v[216:219], v[4:7]
	v_mfma_f32_16x16x32_bf16 v[0:3], v[182:185], v[216:219], v[0:3]
	s_setprio 0
	s_barrier
; #define PG8_STAGE(bufoff, gbase, voff) do { _Pragma("unroll") for (int _i = 0; _i < 2; ++_i) \
;         __builtin_amdgcn_global_load_lds((const unsigned*)((const char*)(gbase) + (voff)[_i]), (PG8_LAS unsigned*)(lds + (bufoff) + ldsw + _i * 8192), 16, 0, 0); } while (0)
; #define PG8_LDA(dst, b, h) do { _Pragma("unroll") for (int m = 0; m < 4; ++m) _Pragma("unroll") for (int k = 0; k < 2; ++k) dst[m][k] = *(const PG8_LAS bf16x8*)(lds + PG8_SA(b, h) + aoff + m * 2048 + k * 1024); } while (0)
; #define PG8_LDB(dst, b, h) do { _Pragma("unroll") for (int n = 0; n < 2; ++n) _Pragma("unroll") for (int k = 0; k < 2; ++k) dst[n][k] = *(const PG8_LAS bf16x8*)(lds + PG8_SB(b, h) + boff + n * 2048 + k * 1024); } while (0)
; #define PG8_MMA(ai, bj, At, Bt) do { __builtin_amdgcn_s_setprio(1); _Pragma("unroll") for (int m = 0; m < 4; ++m) _Pragma("unroll") for (int n = 0; n < 2; ++n) _Pragma("unroll") for (int k = 0; k < 2; ++k) \
;         acc[ai][bj][m][n] = __builtin_amdgcn_mfma_f32_16x16x32_bf16(Bt[n][k], At[m][k], acc[ai][bj][m][n], 0, 0, 0); __builtin_amdgcn_s_setprio(0); } while (0)
; #define PG8_WAIT_V(n) asm volatile("s_waitcnt vmcnt(" #n ")" ::: "memory")
; #define PG8_WAIT_L(n) asm volatile("s_waitcnt lgkmcnt(" #n ")" ::: "memory")
; #define PG8_BAR __builtin_amdgcn_s_barrier()
; #define PG8_SCHED __builtin_amdgcn_sched_barrier(0)
; template <class Epi, class Sched, bool ALIGN_EPI = false, bool SP2 = false>
; __device__ __forceinline__ void gemm_phase(PG8_LAS unsigned char* lds, const Gemm g, const Sched& S, const Epi& E, int tid_in) {
;     ...
;             PG8_LDB(B0, 1, 0); PG8_LDB(B1, 1, 1); PG8_SCHED; PG8_LDA(At, 1, 0); PG8_STAGE(PG8_SA(0, 1), a2 + hstep, voffA);
;             PG8_WAIT_V(8); PG8_WAIT_L(0); PG8_BAR; PG8_MMA(0, 0, At, B0); PG8_MMA(0, 1, At, B1); PG8_BAR; PG8_SCHED;
;             PG8_LDA(At, 1, 1); PG8_STAGE(PG8_SB(1, 0), b3, voffB); PG8_STAGE(PG8_SB(1, 1), b3 + hstepB, voffB); PG8_STAGE(PG8_SA(1, 0), a3, voffA);
	s_add_i32 s33, 0, 0x18000
	s_add_i32 s56, 0, 0x1c000
	v_add_u32_e32 v166, s33, v137
	v_add_u32_e32 v182, s56, v137
	ds_read_b128 v[146:149], v166
	ds_read_b128 v[158:161], v166 offset:1024
	ds_read_b128 v[162:165], v166 offset:2048
	ds_read_b128 v[166:169], v166 offset:3072
	ds_read_b128 v[170:173], v182
	ds_read_b128 v[174:177], v182 offset:1024
	ds_read_b128 v[178:181], v182 offset:2048
	ds_read_b128 v[182:185], v182 offset:3072
	s_add_u32 s26, s60, 0x204000
	s_addc_u32 s27, s61, 0
	s_mov_b32 m0, s66
	ds_read_b128 v[186:189], v155 offset:32768
	ds_read_b128 v[190:193], v155 offset:33792
	ds_read_b128 v[194:197], v155 offset:34816
	ds_read_b128 v[198:201], v155 offset:35840
	ds_read_b128 v[202:205], v155 offset:36864
	ds_read_b128 v[206:209], v155 offset:37888
	ds_read_b128 v[212:215], v155 offset:38912
	ds_read_b128 v[216:219], v155 offset:39936
	global_load_lds_dwordx4 v128, s[26:27]
	s_mov_b32 m0, s67
	s_nop 0
	global_load_lds_dwordx4 v132, s[26:27]
	s_waitcnt vmcnt(8)
	s_waitcnt lgkmcnt(0)
	s_barrier
	s_setprio 1
	s_waitcnt lgkmcnt(0)
	v_mfma_f32_16x16x32_bf16 v[124:127], v[146:149], v[186:189], v[124:127]
	v_mfma_f32_16x16x32_bf16 v[120:123], v[162:165], v[186:189], v[120:123]
	v_mfma_f32_16x16x32_bf16 v[108:111], v[146:149], v[194:197], v[108:111]
	v_mfma_f32_16x16x32_bf16 v[104:107], v[162:165], v[194:197], v[104:107]
	v_mfma_f32_16x16x32_bf16 v[92:95], v[146:149], v[202:205], v[92:95]
	v_mfma_f32_16x16x32_bf16 v[88:91], v[162:165], v[202:205], v[88:91]
	v_mfma_f32_16x16x32_bf16 v[76:79], v[146:149], v[212:215], v[76:79]
	v_mfma_f32_16x16x32_bf16 v[72:75], v[162:165], v[212:215], v[72:75]
	v_mfma_f32_16x16x32_bf16 v[124:127], v[158:161], v[190:193], v[124:127]
	v_mfma_f32_16x16x32_bf16 v[120:123], v[166:169], v[190:193], v[120:123]
	v_mfma_f32_16x16x32_bf16 v[108:111], v[158:161], v[198:201], v[108:111]
	v_mfma_f32_16x16x32_bf16 v[104:107], v[166:169], v[198:201], v[104:107]
	v_mfma_f32_16x16x32_bf16 v[92:95], v[158:161], v[206:209], v[92:95]
	v_mfma_f32_16x16x32_bf16 v[88:91], v[166:169], v[206:209], v[88:91]
	v_mfma_f32_16x16x32_bf16 v[76:79], v[158:161], v[216:219], v[76:79]
	v_mfma_f32_16x16x32_bf16 v[72:75], v[166:169], v[216:219], v[72:75]
	s_setprio 0
	s_setprio 1
	v_mfma_f32_16x16x32_bf16 v[116:119], v[170:173], v[186:189], v[116:119]
	v_mfma_f32_16x16x32_bf16 v[112:115], v[178:181], v[186:189], v[112:115]
	v_mfma_f32_16x16x32_bf16 v[100:103], v[170:173], v[194:197], v[100:103]
	v_mfma_f32_16x16x32_bf16 v[96:99], v[178:181], v[194:197], v[96:99]
	v_mfma_f32_16x16x32_bf16 v[84:87], v[170:173], v[202:205], v[84:87]
	v_mfma_f32_16x16x32_bf16 v[80:83], v[178:181], v[202:205], v[80:83]
	v_mfma_f32_16x16x32_bf16 v[68:71], v[170:173], v[212:215], v[68:71]
	v_mfma_f32_16x16x32_bf16 v[64:67], v[178:181], v[212:215], v[64:67]
	v_mfma_f32_16x16x32_bf16 v[116:119], v[174:177], v[190:193], v[116:119]
	v_mfma_f32_16x16x32_bf16 v[112:115], v[182:185], v[190:193], v[112:115]
	v_mfma_f32_16x16x32_bf16 v[100:103], v[174:177], v[198:201], v[100:103]
	v_mfma_f32_16x16x32_bf16 v[96:99], v[182:185], v[198:201], v[96:99]
	v_mfma_f32_16x16x32_bf16 v[84:87], v[174:177], v[206:209], v[84:87]
	v_mfma_f32_16x16x32_bf16 v[80:83], v[182:185], v[206:209], v[80:83]
	v_mfma_f32_16x16x32_bf16 v[68:71], v[174:177], v[216:219], v[68:71]
	v_mfma_f32_16x16x32_bf16 v[64:67], v[182:185], v[216:219], v[64:67]
	s_setprio 0
	s_barrier
	s_add_i32 s26, s33, s64
	s_add_i32 m0, s26, 0xffffff80
	ds_read_b128 v[186:189], v155 offset:49152
	ds_read_b128 v[190:193], v155 offset:50176
	ds_read_b128 v[194:197], v155 offset:51200
	ds_read_b128 v[198:201], v155 offset:52224
	ds_read_b128 v[202:205], v155 offset:53248
	ds_read_b128 v[206:209], v155 offset:54272
	ds_read_b128 v[212:215], v155 offset:55296
	ds_read_b128 v[216:219], v155 offset:56320
	global_load_lds_dwordx4 v130, s[58:59] offset:128
	s_add_i32 m0, s26, 0x1f80
	s_add_u32 s26, s58, 0x80080
	s_addc_u32 s27, s59, 0
	s_add_i32 s33, s56, s64
	global_load_lds_dwordx4 v134, s[58:59] offset:128
	s_mov_b32 m0, s33
	s_nop 0
	global_load_lds_dwordx4 v130, s[26:27]
	s_add_i32 m0, s33, 0x2000
	s_nop 0
	global_load_lds_dwordx4 v134, s[26:27]
	s_add_i32 m0, s69, 0xffffff80
	s_nop 0
	global_load_lds_dwordx4 v128, s[60:61] offset:128
	s_add_i32 m0, s70, 0xffffff80
	s_nop 0
	global_load_lds_dwordx4 v132, s[60:61] offset:128
	s_waitcnt vmcnt(8)
	s_waitcnt lgkmcnt(0)
	s_barrier
; #define PG8_MMA(ai, bj, At, Bt) do { __builtin_amdgcn_s_setprio(1); _Pragma("unroll") for (int m = 0; m < 4; ++m) _Pragma("unroll") for (int n = 0; n < 2; ++n) _Pragma("unroll") for (int k = 0; k < 2; ++k) \
;         acc[ai][bj][m][n] = __builtin_amdgcn_mfma_f32_16x16x32_bf16(Bt[n][k], At[m][k], acc[ai][bj][m][n], 0, 0, 0); __builtin_amdgcn_s_setprio(0); } while (0)
; #define PG8_WAIT_V(n) asm volatile("s_waitcnt vmcnt(" #n ")" ::: "memory")
; #define PG8_WAIT_L(n) asm volatile("s_waitcnt lgkmcnt(" #n ")" ::: "memory")
; #define PG8_BAR __builtin_amdgcn_s_barrier()
; #define PG8_SCHED __builtin_amdgcn_sched_barrier(0)
; template <class Epi, class Sched, bool ALIGN_EPI = false, bool SP2 = false>
; __device__ __forceinline__ void gemm_phase(PG8_LAS unsigned char* lds, const Gemm g, const Sched& S, const Epi& E, int tid_in) {
;     ...
;             PG8_WAIT_V(8); PG8_WAIT_L(0); PG8_BAR; PG8_MMA(1, 0, At, B0); PG8_MMA(1, 1, At, B1); PG8_BAR; PG8_SCHED;
;     __device__ __forceinline__ void operator()(const f32x4 (&acc)[2][2][4][2], const Unit& u, int wr, int wc, int fr, int fq) const {
;     ...
;                 const int row = u.pm * BM + ai * HALF + wr * 64 + m * 16 + r; float q = 0.f;
; #pragma unroll
;                 for (int bj = 0; bj < 2; ++bj) {
;                     const size_t off = (size_t)row * 2048 + u.pn * BM + wc * 64 + bj * 32 + 8 * p;
;                     f32x4 b0, b1;
;                     if (BASE_F32) { b0 = *(const f32x4*)((const float*)base + off); b1 = *(const f32x4*)((const float*)base + off + 4); }
;                     else { const u32x4 bb = *(const u32x4*)((const bf16_t*)base + off);
;                         b0 = (f32x4){__uint_as_float(bb.x << 16), __uint_as_float(bb.x & 0xffff0000u), __uint_as_float(bb.y << 16), __uint_as_float(bb.y & 0xffff0000u)};
;                         b1 = (f32x4){__uint_as_float(bb.z << 16), __uint_as_float(bb.z & 0xffff0000u), __uint_as_float(bb.w << 16), __uint_as_float(bb.w & 0xffff0000u)}; }
	s_setprio 1
	s_waitcnt lgkmcnt(0)
	v_mfma_f32_16x16x32_bf16 v[60:63], v[146:149], v[186:189], v[60:63]
	v_mfma_f32_16x16x32_bf16 v[56:59], v[162:165], v[186:189], v[56:59]
	v_mfma_f32_16x16x32_bf16 v[44:47], v[146:149], v[194:197], v[44:47]
	v_mfma_f32_16x16x32_bf16 v[40:43], v[162:165], v[194:197], v[40:43]
	v_mfma_f32_16x16x32_bf16 v[28:31], v[146:149], v[202:205], v[28:31]
	v_mfma_f32_16x16x32_bf16 v[24:27], v[162:165], v[202:205], v[24:27]
	v_mfma_f32_16x16x32_bf16 v[12:15], v[146:149], v[212:215], v[12:15]
	v_mfma_f32_16x16x32_bf16 v[8:11], v[162:165], v[212:215], v[8:11]
	v_mfma_f32_16x16x32_bf16 v[60:63], v[158:161], v[190:193], v[60:63]
	v_mfma_f32_16x16x32_bf16 v[56:59], v[166:169], v[190:193], v[56:59]
	v_mfma_f32_16x16x32_bf16 v[44:47], v[158:161], v[198:201], v[44:47]
	v_mfma_f32_16x16x32_bf16 v[40:43], v[166:169], v[198:201], v[40:43]
	v_mfma_f32_16x16x32_bf16 v[28:31], v[158:161], v[206:209], v[28:31]
	v_mfma_f32_16x16x32_bf16 v[24:27], v[166:169], v[206:209], v[24:27]
	v_mfma_f32_16x16x32_bf16 v[12:15], v[158:161], v[216:219], v[12:15]
	v_mfma_f32_16x16x32_bf16 v[8:11], v[166:169], v[216:219], v[8:11]
	s_setprio 0
	s_setprio 1
	v_mfma_f32_16x16x32_bf16 v[52:55], v[170:173], v[186:189], v[52:55]
	v_mfma_f32_16x16x32_bf16 v[48:51], v[178:181], v[186:189], v[48:51]
	v_mfma_f32_16x16x32_bf16 v[36:39], v[170:173], v[194:197], v[36:39]
	v_mfma_f32_16x16x32_bf16 v[32:35], v[178:181], v[194:197], v[32:35]
	v_mfma_f32_16x16x32_bf16 v[20:23], v[170:173], v[202:205], v[20:23]
	v_mfma_f32_16x16x32_bf16 v[16:19], v[178:181], v[202:205], v[16:19]
	v_mfma_f32_16x16x32_bf16 v[4:7], v[170:173], v[212:215], v[4:7]
	v_mfma_f32_16x16x32_bf16 v[0:3], v[178:181], v[212:215], v[0:3]
	v_mfma_f32_16x16x32_bf16 v[52:55], v[174:177], v[190:193], v[52:55]
	v_mfma_f32_16x16x32_bf16 v[48:51], v[182:185], v[190:193], v[48:51]
	v_mfma_f32_16x16x32_bf16 v[36:39], v[174:177], v[198:201], v[36:39]
	v_mfma_f32_16x16x32_bf16 v[32:35], v[182:185], v[198:201], v[32:35]
	v_mfma_f32_16x16x32_bf16 v[20:23], v[174:177], v[206:209], v[20:23]
	v_mfma_f32_16x16x32_bf16 v[16:19], v[182:185], v[206:209], v[16:19]
	v_mfma_f32_16x16x32_bf16 v[4:7], v[174:177], v[216:219], v[4:7]
	v_mfma_f32_16x16x32_bf16 v[0:3], v[182:185], v[216:219], v[0:3]
	s_setprio 0
	s_barrier
	s_add_i32 s79, s79, 2
	s_add_u32 s76, s76, 0x100
	s_addc_u32 s77, s77, 0
	s_cmpk_gt_u32 s79, 0x7d
	s_mov_b64 s[56:57], s[12:13]
	s_cbranch_scc0 .LBB0_474
	v_lshl_add_u32 v148, s74, 8, v150
	v_lshl_or_b32 v146, s54, 8, v136
	v_lshl_add_u32 v147, v148, 11, v146
	v_lshlrev_b32_e32 v159, 1, v147
	v_lshlrev_b32_e32 v208, 3, v148
	global_load_dwordx4 v[160:163], v159, s[38:39]
	global_load_dwordx4 v[164:167], v159, s[38:39] offset:64
	v_add_u32_e32 v149, 0x10000, v159
	global_load_dwordx4 v[168:171], v149, s[38:39]
	global_load_dwordx4 v[172:175], v149, s[38:39] offset:64
	v_add_u32_e32 v209, 0x20000, v159
	global_load_dwordx4 v[176:179], v209, s[38:39]
	global_load_dwordx4 v[180:183], v209, s[38:39] offset:64
	v_add_u32_e32 v149, 0x30000, v159
	global_load_dwordx4 v[184:187], v149, s[38:39]
	global_load_dwordx4 v[188:191], v149, s[38:39] offset:64
	v_add_u32_e32 v209, 0x80000, v159
	global_load_dwordx4 v[192:195], v209, s[38:39]
	global_load_dwordx4 v[196:199], v209, s[38:39] offset:64
	v_add_u32_e32 v149, 0x90000, v159
	global_load_dwordx4 v[200:203], v149, s[38:39]
	global_load_dwordx4 v[204:207], v149, s[38:39] offset:64
	v_add_u32_e32 v209, 0xa0000, v159
	global_load_dwordx4 v[212:215], v209, s[38:39]
	global_load_dwordx4 v[216:219], v209, s[38:39] offset:64
	v_add_u32_e32 v149, 0xb0000, v159
	global_load_dwordx4 v[220:223], v149, s[38:39]
	global_load_dwordx4 v[224:227], v149, s[38:39] offset:64
	s_and_b64 vcc, exec, s[46:47]
	s_cbranch_vccz .LBB0_477
	s_barrier

; #define PG8_STAGE(bufoff, gbase, voff) do { _Pragma("unroll") for (int _i = 0; _i < 2; ++_i) \
;         __builtin_amdgcn_global_load_lds((const unsigned*)((const char*)(gbase) + (voff)[_i]), (PG8_LAS unsigned*)(lds + (bufoff) + ldsw + _i * 8192), 16, 0, 0); } while (0)
; #define PG8_LDA(dst, b, h) do { _Pragma("unroll") for (int m = 0; m < 4; ++m) _Pragma("unroll") for (int k = 0; k < 2; ++k) dst[m][k] = *(const PG8_LAS bf16x8*)(lds + PG8_SA(b, h) + aoff + m * 2048 + k * 1024); } while (0)
; #define PG8_LDB(dst, b, h) do { _Pragma("unroll") for (int n = 0; n < 2; ++n) _Pragma("unroll") for (int k = 0; k < 2; ++k) dst[n][k] = *(const PG8_LAS bf16x8*)(lds + PG8_SB(b, h) + boff + n * 2048 + k * 1024); } while (0)
; #define PG8_WAIT_V(n) asm volatile("s_waitcnt vmcnt(" #n ")" ::: "memory")
; #define PG8_WAIT_L(n) asm volatile("s_waitcnt lgkmcnt(" #n ")" ::: "memory")
; #define PG8_BAR __builtin_amdgcn_s_barrier()
; #define PG8_SCHED __builtin_amdgcn_sched_barrier(0)
; template <class Epi, class Sched, bool ALIGN_EPI = false, bool SP2 = false>
; __device__ __forceinline__ void gemm_phase(PG8_LAS unsigned char* lds, const Gemm g, const Sched& S, const Epi& E, int tid_in) {
;     ...
;         const char* nA = has_next ? (const char*)g.A + (size_t)nxt.pm * tstep : cA; const char* nB = has_next ? (const char*)g.Bt + (size_t)nxt.pn * tstepB : cB;
;         for (int t = 0; t < nt; t += 2) {
;             const bool last = (t == nt - 2);
;             const char* a1 = cA + (size_t)(t + 1) * kstep;
;             const char* a2 = last ? nA : cA + (size_t)(t + 2) * kstep; const char* b2 = last ? nB : cB + (size_t)(t + 2) * kstep;
;             const char* a3 = a2 + kstep; const char* b3 = b2 + kstep;
;             if (last && has_next) S.a_ready(nxt);
;             if constexpr (SP2) {
;             PG8_LDB(B0, 0, 0); PG8_LDB(B1, 0, 1); PG8_SCHED; PG8_LDA(At, 0, 0); PG8_STAGE(PG8_SA(1, 1), a1 + hstep, voffA);
;             PG8_WAIT_V(8); PG8_WAIT_L(0); PG8_BAR; PG8_MMA(0, 0, At, B0); PG8_MMA(0, 1, At, B1); PG8_BAR; PG8_SCHED;
;             PG8_LDA(At, 0, 1); PG8_STAGE(PG8_SB(0, 0), b2, voffB); PG8_STAGE(PG8_SB(0, 1), b2 + hstepB, voffB); PG8_STAGE(PG8_SA(0, 0), a2, voffA);
;             PG8_WAIT_V(8); PG8_WAIT_L(0); PG8_BAR; PG8_MMA(1, 0, At, B0); PG8_MMA(1, 1, At, B1); PG8_BAR; PG8_SCHED;
.Lkb_skip_4:
.LBB0_597:
	ds_read_b128 v[128:131], v171
	ds_read_b128 v[132:135], v171 offset:1024
	ds_read_b128 v[136:139], v171 offset:2048
	ds_read_b128 v[184:187], v171 offset:3072
	ds_read_b128 v[188:191], v172
	ds_read_b128 v[192:195], v172 offset:1024
	ds_read_b128 v[196:199], v172 offset:2048
	ds_read_b128 v[200:203], v172 offset:3072
	s_add_u32 s26, s60, 0xfff80080
	s_addc_u32 s27, s61, -1
	s_cmp_eq_u32 s88, 28
	s_cselect_b32 s65, s11, s27
	s_cselect_b32 s64, s53, s26
	s_cselect_b32 s63, s51, s87
	s_cselect_b32 s62, s85, s86
	s_add_i32 m0, s59, 0xc000
	ds_read_b128 v[204:207], v173
	ds_read_b128 v[212:215], v173 offset:1024
	ds_read_b128 v[216:219], v173 offset:2048
	ds_read_b128 v[220:223], v173 offset:3072
	ds_read_b128 v[224:227], v173 offset:4096
	ds_read_b128 v[228:231], v173 offset:5120
	ds_read_b128 v[232:235], v173 offset:6144
	ds_read_b128 v[236:239], v173 offset:7168
	global_load_lds_dwordx4 v158, s[60:61]
	s_add_i32 m0, s59, 0xe000
	s_nop 0
	global_load_lds_dwordx4 v160, s[60:61]
	s_waitcnt vmcnt(8)
	s_waitcnt lgkmcnt(0)
	s_barrier
	s_setprio 1
	s_waitcnt lgkmcnt(0)
	v_mfma_f32_16x16x32_bf16 v[124:127], v[128:131], v[204:207], v[124:127]
	v_mfma_f32_16x16x32_bf16 v[120:123], v[136:139], v[204:207], v[120:123]
	v_mfma_f32_16x16x32_bf16 v[108:111], v[128:131], v[216:219], v[108:111]
	v_mfma_f32_16x16x32_bf16 v[104:107], v[136:139], v[216:219], v[104:107]
	v_mfma_f32_16x16x32_bf16 v[92:95], v[128:131], v[224:227], v[92:95]
	v_mfma_f32_16x16x32_bf16 v[88:91], v[136:139], v[224:227], v[88:91]
	v_mfma_f32_16x16x32_bf16 v[76:79], v[128:131], v[232:235], v[76:79]
	v_mfma_f32_16x16x32_bf16 v[72:75], v[136:139], v[232:235], v[72:75]
	v_mfma_f32_16x16x32_bf16 v[124:127], v[132:135], v[212:215], v[124:127]
	v_mfma_f32_16x16x32_bf16 v[120:123], v[184:187], v[212:215], v[120:123]
	v_mfma_f32_16x16x32_bf16 v[108:111], v[132:135], v[220:223], v[108:111]
	v_mfma_f32_16x16x32_bf16 v[104:107], v[184:187], v[220:223], v[104:107]
	v_mfma_f32_16x16x32_bf16 v[92:95], v[132:135], v[228:231], v[92:95]
	v_mfma_f32_16x16x32_bf16 v[88:91], v[184:187], v[228:231], v[88:91]
	v_mfma_f32_16x16x32_bf16 v[76:79], v[132:135], v[236:239], v[76:79]
	v_mfma_f32_16x16x32_bf16 v[72:75], v[184:187], v[236:239], v[72:75]
	s_setprio 0
	s_setprio 1
	v_mfma_f32_16x16x32_bf16 v[116:119], v[188:191], v[204:207], v[116:119]
	v_mfma_f32_16x16x32_bf16 v[112:115], v[196:199], v[204:207], v[112:115]
	v_mfma_f32_16x16x32_bf16 v[100:103], v[188:191], v[216:219], v[100:103]
	v_mfma_f32_16x16x32_bf16 v[96:99], v[196:199], v[216:219], v[96:99]
	v_mfma_f32_16x16x32_bf16 v[84:87], v[188:191], v[224:227], v[84:87]
	v_mfma_f32_16x16x32_bf16 v[80:83], v[196:199], v[224:227], v[80:83]
	v_mfma_f32_16x16x32_bf16 v[68:71], v[188:191], v[232:235], v[68:71]
	v_mfma_f32_16x16x32_bf16 v[64:67], v[196:199], v[232:235], v[64:67]
	v_mfma_f32_16x16x32_bf16 v[116:119], v[192:195], v[212:215], v[116:119]
	v_mfma_f32_16x16x32_bf16 v[112:115], v[200:203], v[212:215], v[112:115]
	v_mfma_f32_16x16x32_bf16 v[100:103], v[192:195], v[220:223], v[100:103]
	v_mfma_f32_16x16x32_bf16 v[96:99], v[200:203], v[220:223], v[96:99]
	v_mfma_f32_16x16x32_bf16 v[84:87], v[192:195], v[228:231], v[84:87]
	v_mfma_f32_16x16x32_bf16 v[80:83], v[200:203], v[228:231], v[80:83]
	v_mfma_f32_16x16x32_bf16 v[68:71], v[192:195], v[236:239], v[68:71]
	v_mfma_f32_16x16x32_bf16 v[64:67], v[200:203], v[236:239], v[64:67]
	s_setprio 0
	s_barrier
	s_add_i32 s26, s78, s68
	s_mov_b32 m0, s26
	ds_read_b128 v[204:207], v173 offset:16384
	ds_read_b128 v[212:215], v173 offset:17408
	ds_read_b128 v[216:219], v173 offset:18432
	ds_read_b128 v[220:223], v173 offset:19456
	ds_read_b128 v[224:227], v173 offset:20480
	ds_read_b128 v[228:231], v173 offset:21504
	ds_read_b128 v[232:235], v173 offset:22528
	ds_read_b128 v[236:239], v173 offset:23552
	global_load_lds_dwordx4 v144, s[62:63]
	s_add_i32 m0, s26, 0x2000
	s_add_u32 s26, s62, 0x20000
	s_addc_u32 s27, s63, 0
	s_add_i32 s33, s79, s68
	global_load_lds_dwordx4 v148, s[62:63]
	s_mov_b32 m0, s33
	s_nop 0
	global_load_lds_dwordx4 v144, s[26:27]
	s_add_i32 m0, s33, 0x2000
	s_nop 0
	global_load_lds_dwordx4 v148, s[26:27]
	s_mov_b32 m0, s59
	s_nop 0
	global_load_lds_dwordx4 v142, s[64:65]
	s_mov_b32 m0, s69
	s_nop 0
	global_load_lds_dwordx4 v146, s[64:65]
	s_waitcnt vmcnt(8)
	s_waitcnt lgkmcnt(0)
	s_barrier
	s_setprio 1
	s_waitcnt lgkmcnt(0)
	v_mfma_f32_16x16x32_bf16 v[60:63], v[128:131], v[204:207], v[60:63]
	v_mfma_f32_16x16x32_bf16 v[56:59], v[136:139], v[204:207], v[56:59]
	v_mfma_f32_16x16x32_bf16 v[44:47], v[128:131], v[216:219], v[44:47]
	v_mfma_f32_16x16x32_bf16 v[40:43], v[136:139], v[216:219], v[40:43]
	v_mfma_f32_16x16x32_bf16 v[28:31], v[128:131], v[224:227], v[28:31]
	v_mfma_f32_16x16x32_bf16 v[24:27], v[136:139], v[224:227], v[24:27]
	v_mfma_f32_16x16x32_bf16 v[12:15], v[128:131], v[232:235], v[12:15]
	v_mfma_f32_16x16x32_bf16 v[8:11], v[136:139], v[232:235], v[8:11]
	v_mfma_f32_16x16x32_bf16 v[60:63], v[132:135], v[212:215], v[60:63]
	v_mfma_f32_16x16x32_bf16 v[56:59], v[184:187], v[212:215], v[56:59]
	v_mfma_f32_16x16x32_bf16 v[44:47], v[132:135], v[220:223], v[44:47]
	v_mfma_f32_16x16x32_bf16 v[40:43], v[184:187], v[220:223], v[40:43]
	v_mfma_f32_16x16x32_bf16 v[28:31], v[132:135], v[228:231], v[28:31]
	v_mfma_f32_16x16x32_bf16 v[24:27], v[184:187], v[228:231], v[24:27]
	v_mfma_f32_16x16x32_bf16 v[12:15], v[132:135], v[236:239], v[12:15]
	v_mfma_f32_16x16x32_bf16 v[8:11], v[184:187], v[236:239], v[8:11]
	s_setprio 0
	s_setprio 1
	v_mfma_f32_16x16x32_bf16 v[52:55], v[188:191], v[204:207], v[52:55]
	v_mfma_f32_16x16x32_bf16 v[48:51], v[196:199], v[204:207], v[48:51]
	v_mfma_f32_16x16x32_bf16 v[36:39], v[188:191], v[216:219], v[36:39]
	v_mfma_f32_16x16x32_bf16 v[32:35], v[196:199], v[216:219], v[32:35]
	v_mfma_f32_16x16x32_bf16 v[20:23], v[188:191], v[224:227], v[20:23]
	v_mfma_f32_16x16x32_bf16 v[16:19], v[196:199], v[224:227], v[16:19]
	v_mfma_f32_16x16x32_bf16 v[4:7], v[188:191], v[232:235], v[4:7]
	v_mfma_f32_16x16x32_bf16 v[0:3], v[196:199], v[232:235], v[0:3]
	v_mfma_f32_16x16x32_bf16 v[52:55], v[192:195], v[212:215], v[52:55]
	v_mfma_f32_16x16x32_bf16 v[48:51], v[200:203], v[212:215], v[48:51]
	v_mfma_f32_16x16x32_bf16 v[36:39], v[192:195], v[220:223], v[36:39]
	v_mfma_f32_16x16x32_bf16 v[32:35], v[200:203], v[220:223], v[32:35]
	v_mfma_f32_16x16x32_bf16 v[20:23], v[192:195], v[228:231], v[20:23]
	v_mfma_f32_16x16x32_bf16 v[16:19], v[200:203], v[228:231], v[16:19]
	v_mfma_f32_16x16x32_bf16 v[4:7], v[192:195], v[236:239], v[4:7]
	v_mfma_f32_16x16x32_bf16 v[0:3], v[200:203], v[236:239], v[0:3]
	s_setprio 0
	s_barrier
; #define PG8_STAGE(bufoff, gbase, voff) do { _Pragma("unroll") for (int _i = 0; _i < 2; ++_i) \
;         __builtin_amdgcn_global_load_lds((const unsigned*)((const char*)(gbase) + (voff)[_i]), (PG8_LAS unsigned*)(lds + (bufoff) + ldsw + _i * 8192), 16, 0, 0); } while (0)
; #define PG8_BAR __builtin_amdgcn_s_barrier()
; template <class Epi, class Sched, bool ALIGN_EPI = false, bool SP2 = false>
; __device__ __forceinline__ void gemm_phase(PG8_LAS unsigned char* lds, const Gemm g, const Sched& S, const Epi& E, int tid_in) {
;     ...
;             PG8_LDB(B0, 1, 0); PG8_LDB(B1, 1, 1); PG8_SCHED; PG8_LDA(At, 1, 0); PG8_STAGE(PG8_SA(0, 1), a2 + hstep, voffA);
;             PG8_WAIT_V(8); PG8_WAIT_L(0); PG8_BAR; PG8_MMA(0, 0, At, B0); PG8_MMA(0, 1, At, B1); PG8_BAR; PG8_SCHED;
;             PG8_LDA(At, 1, 1); PG8_STAGE(PG8_SB(1, 0), b3, voffB); PG8_STAGE(PG8_SB(1, 1), b3 + hstepB, voffB); PG8_STAGE(PG8_SA(1, 0), a3, voffA);
;             PG8_WAIT_V(8); PG8_WAIT_L(0); PG8_BAR; PG8_MMA(1, 0, At, B0); PG8_MMA(1, 1, At, B1); PG8_BAR; PG8_SCHED;
;             } else {
;             PG8_LDB(B0, 0, 0); PG8_SCHED; PG8_LDA(At, 0, 0); PG8_STAGE(PG8_SA(1, 1), a1 + hstep, voffA);
;             PG8_WAIT_L(8); PG8_BAR; PG8_WAIT_L(0); PG8_MMA(0, 0, At, B0); PG8_BAR; PG8_SCHED;
;             PG8_LDB(B1, 0, 1); PG8_STAGE(PG8_SB(0, 0), b2, voffB);
;             PG8_BAR; PG8_WAIT_L(0); PG8_MMA(0, 1, At, B1); PG8_BAR;
;             PG8_LDA(At, 0, 1); PG8_STAGE(PG8_SA(0, 0), a2, voffA);
;             PG8_BAR; PG8_WAIT_L(0); PG8_MMA(1, 0, At, B0); PG8_BAR; PG8_SCHED;
;             PG8_STAGE(PG8_SB(0, 1), b2 + hstepB, voffB);
;             PG8_WAIT_V(6); PG8_BAR; PG8_MMA(1, 1, At, B1); PG8_BAR;
;             PG8_LDB(B0, 1, 0); PG8_SCHED; PG8_LDA(At, 1, 0); PG8_STAGE(PG8_SA(0, 1), a2 + hstep, voffA);
;             PG8_WAIT_L(8); PG8_BAR; PG8_WAIT_L(0); PG8_MMA(0, 0, At, B0); PG8_BAR; PG8_SCHED;
;             PG8_LDB(B1, 1, 1); PG8_STAGE(PG8_SB(1, 0), b3, voffB);
;             PG8_BAR; PG8_WAIT_L(0); PG8_MMA(0, 1, At, B1); PG8_BAR;
;             PG8_LDA(At, 1, 1); PG8_STAGE(PG8_SA(1, 0), a3, voffA);
;             PG8_BAR; PG8_WAIT_L(0); PG8_MMA(1, 0, At, B0); PG8_BAR; PG8_SCHED;
;             PG8_STAGE(PG8_SB(1, 1), b3 + hstepB, voffB);
;             PG8_WAIT_V(6); PG8_BAR; PG8_MMA(1, 1, At, B1); PG8_BAR;
;             }
;         }
;         if constexpr (ALIGN_EPI) { if (wr == 0) PG8_BAR; }
	s_add_i32 s33, 0, 0x18000
	v_add_u32_e32 v150, s33, v167
	s_add_i32 s89, 0, 0x1c000
	ds_read_b128 v[128:131], v150
	ds_read_b128 v[132:135], v150 offset:1024
	ds_read_b128 v[136:139], v150 offset:2048
	ds_read_b128 v[184:187], v150 offset:3072
	v_add_u32_e32 v150, s89, v167
	ds_read_b128 v[188:191], v150
	ds_read_b128 v[192:195], v150 offset:1024
	ds_read_b128 v[196:199], v150 offset:2048
	ds_read_b128 v[200:203], v150 offset:3072
	s_add_u32 s26, s64, 0x80000
	s_addc_u32 s27, s65, 0
	s_mov_b32 m0, s70
	ds_read_b128 v[204:207], v173 offset:32768
	ds_read_b128 v[212:215], v173 offset:33792
	ds_read_b128 v[216:219], v173 offset:34816
	ds_read_b128 v[220:223], v173 offset:35840
	ds_read_b128 v[224:227], v173 offset:36864
	ds_read_b128 v[228:231], v173 offset:37888
	ds_read_b128 v[232:235], v173 offset:38912
	ds_read_b128 v[236:239], v173 offset:39936
	global_load_lds_dwordx4 v142, s[26:27]
	s_mov_b32 m0, s71
	s_nop 0
	global_load_lds_dwordx4 v146, s[26:27]
	s_waitcnt vmcnt(8)
	s_waitcnt lgkmcnt(0)
	s_barrier
	s_setprio 1
	s_waitcnt lgkmcnt(0)
	v_mfma_f32_16x16x32_bf16 v[124:127], v[128:131], v[204:207], v[124:127]
	v_mfma_f32_16x16x32_bf16 v[120:123], v[136:139], v[204:207], v[120:123]
	v_mfma_f32_16x16x32_bf16 v[108:111], v[128:131], v[216:219], v[108:111]
	v_mfma_f32_16x16x32_bf16 v[104:107], v[136:139], v[216:219], v[104:107]
	v_mfma_f32_16x16x32_bf16 v[92:95], v[128:131], v[224:227], v[92:95]
	v_mfma_f32_16x16x32_bf16 v[88:91], v[136:139], v[224:227], v[88:91]
	v_mfma_f32_16x16x32_bf16 v[76:79], v[128:131], v[232:235], v[76:79]
	v_mfma_f32_16x16x32_bf16 v[72:75], v[136:139], v[232:235], v[72:75]
	v_mfma_f32_16x16x32_bf16 v[124:127], v[132:135], v[212:215], v[124:127]
	v_mfma_f32_16x16x32_bf16 v[120:123], v[184:187], v[212:215], v[120:123]
	v_mfma_f32_16x16x32_bf16 v[108:111], v[132:135], v[220:223], v[108:111]
	v_mfma_f32_16x16x32_bf16 v[104:107], v[184:187], v[220:223], v[104:107]
	v_mfma_f32_16x16x32_bf16 v[92:95], v[132:135], v[228:231], v[92:95]
	v_mfma_f32_16x16x32_bf16 v[88:91], v[184:187], v[228:231], v[88:91]
	v_mfma_f32_16x16x32_bf16 v[76:79], v[132:135], v[236:239], v[76:79]
	v_mfma_f32_16x16x32_bf16 v[72:75], v[184:187], v[236:239], v[72:75]
	s_setprio 0
	s_setprio 1
	v_mfma_f32_16x16x32_bf16 v[116:119], v[188:191], v[204:207], v[116:119]
	v_mfma_f32_16x16x32_bf16 v[112:115], v[196:199], v[204:207], v[112:115]
	v_mfma_f32_16x16x32_bf16 v[100:103], v[188:191], v[216:219], v[100:103]
	v_mfma_f32_16x16x32_bf16 v[96:99], v[196:199], v[216:219], v[96:99]
	v_mfma_f32_16x16x32_bf16 v[84:87], v[188:191], v[224:227], v[84:87]
	v_mfma_f32_16x16x32_bf16 v[80:83], v[196:199], v[224:227], v[80:83]
	v_mfma_f32_16x16x32_bf16 v[68:71], v[188:191], v[232:235], v[68:71]
	v_mfma_f32_16x16x32_bf16 v[64:67], v[196:199], v[232:235], v[64:67]
	v_mfma_f32_16x16x32_bf16 v[116:119], v[192:195], v[212:215], v[116:119]
	v_mfma_f32_16x16x32_bf16 v[112:115], v[200:203], v[212:215], v[112:115]
	v_mfma_f32_16x16x32_bf16 v[100:103], v[192:195], v[220:223], v[100:103]
	v_mfma_f32_16x16x32_bf16 v[96:99], v[200:203], v[220:223], v[96:99]
	v_mfma_f32_16x16x32_bf16 v[84:87], v[192:195], v[228:231], v[84:87]
	v_mfma_f32_16x16x32_bf16 v[80:83], v[200:203], v[228:231], v[80:83]
	v_mfma_f32_16x16x32_bf16 v[68:71], v[192:195], v[236:239], v[68:71]
	v_mfma_f32_16x16x32_bf16 v[64:67], v[200:203], v[236:239], v[64:67]
	s_setprio 0
	s_barrier
	s_add_i32 s26, s33, s68
	s_add_i32 m0, s26, 0xffffff80
	ds_read_b128 v[204:207], v173 offset:49152
	ds_read_b128 v[212:215], v173 offset:50176
	ds_read_b128 v[216:219], v173 offset:51200
	ds_read_b128 v[220:223], v173 offset:52224
	ds_read_b128 v[224:227], v173 offset:53248
	ds_read_b128 v[228:231], v173 offset:54272
	ds_read_b128 v[232:235], v173 offset:55296
	ds_read_b128 v[236:239], v173 offset:56320
	global_load_lds_dwordx4 v144, s[62:63] offset:128
	s_add_i32 m0, s26, 0x1f80
	s_add_u32 s26, s62, 0x20080
	s_addc_u32 s27, s63, 0
	s_add_i32 s33, s89, s68
	global_load_lds_dwordx4 v148, s[62:63] offset:128
	s_mov_b32 m0, s33
	s_nop 0
	global_load_lds_dwordx4 v144, s[26:27]
	s_add_i32 m0, s33, 0x2000
	s_nop 0
	global_load_lds_dwordx4 v148, s[26:27]
	s_add_i32 m0, s74, 0xffffff80
	s_nop 0
	global_load_lds_dwordx4 v142, s[64:65] offset:128
	s_add_i32 m0, s75, 0xffffff80
	s_nop 0
	global_load_lds_dwordx4 v146, s[64:65] offset:128
	s_waitcnt vmcnt(8)
	s_waitcnt lgkmcnt(0)
	s_barrier
	s_setprio 1
	s_waitcnt lgkmcnt(0)
	v_mfma_f32_16x16x32_bf16 v[60:63], v[128:131], v[204:207], v[60:63]
	v_mfma_f32_16x16x32_bf16 v[56:59], v[136:139], v[204:207], v[56:59]
	v_mfma_f32_16x16x32_bf16 v[44:47], v[128:131], v[216:219], v[44:47]
	v_mfma_f32_16x16x32_bf16 v[40:43], v[136:139], v[216:219], v[40:43]
	v_mfma_f32_16x16x32_bf16 v[28:31], v[128:131], v[224:227], v[28:31]
	v_mfma_f32_16x16x32_bf16 v[24:27], v[136:139], v[224:227], v[24:27]
	v_mfma_f32_16x16x32_bf16 v[12:15], v[128:131], v[232:235], v[12:15]
	v_mfma_f32_16x16x32_bf16 v[8:11], v[136:139], v[232:235], v[8:11]
	v_mfma_f32_16x16x32_bf16 v[60:63], v[132:135], v[212:215], v[60:63]
	v_mfma_f32_16x16x32_bf16 v[56:59], v[184:187], v[212:215], v[56:59]
	v_mfma_f32_16x16x32_bf16 v[44:47], v[132:135], v[220:223], v[44:47]
	v_mfma_f32_16x16x32_bf16 v[40:43], v[184:187], v[220:223], v[40:43]
	v_mfma_f32_16x16x32_bf16 v[28:31], v[132:135], v[228:231], v[28:31]
	v_mfma_f32_16x16x32_bf16 v[24:27], v[184:187], v[228:231], v[24:27]
	v_mfma_f32_16x16x32_bf16 v[12:15], v[132:135], v[236:239], v[12:15]
	v_mfma_f32_16x16x32_bf16 v[8:11], v[184:187], v[236:239], v[8:11]
	s_setprio 0
	s_setprio 1
	v_mfma_f32_16x16x32_bf16 v[52:55], v[188:191], v[204:207], v[52:55]
	v_mfma_f32_16x16x32_bf16 v[48:51], v[196:199], v[204:207], v[48:51]
	v_mfma_f32_16x16x32_bf16 v[36:39], v[188:191], v[216:219], v[36:39]
	v_mfma_f32_16x16x32_bf16 v[32:35], v[196:199], v[216:219], v[32:35]
	v_mfma_f32_16x16x32_bf16 v[20:23], v[188:191], v[224:227], v[20:23]
	v_mfma_f32_16x16x32_bf16 v[16:19], v[196:199], v[224:227], v[16:19]
	v_mfma_f32_16x16x32_bf16 v[4:7], v[188:191], v[232:235], v[4:7]
	v_mfma_f32_16x16x32_bf16 v[0:3], v[196:199], v[232:235], v[0:3]
	v_mfma_f32_16x16x32_bf16 v[52:55], v[192:195], v[212:215], v[52:55]
	v_mfma_f32_16x16x32_bf16 v[48:51], v[200:203], v[212:215], v[48:51]
	v_mfma_f32_16x16x32_bf16 v[36:39], v[192:195], v[220:223], v[36:39]
	v_mfma_f32_16x16x32_bf16 v[32:35], v[200:203], v[220:223], v[32:35]
	v_mfma_f32_16x16x32_bf16 v[20:23], v[192:195], v[228:231], v[20:23]
	v_mfma_f32_16x16x32_bf16 v[16:19], v[200:203], v[228:231], v[16:19]
	v_mfma_f32_16x16x32_bf16 v[4:7], v[192:195], v[236:239], v[4:7]
	v_mfma_f32_16x16x32_bf16 v[0:3], v[200:203], v[236:239], v[0:3]
	s_setprio 0
	s_barrier
	s_add_i32 s88, s88, 2
	s_add_u32 s60, s60, 0x100
	s_addc_u32 s61, s61, 0
	s_add_u32 s86, s86, 0x100
	s_addc_u32 s87, s87, 0
	s_cmp_gt_u32 s88, 29
	s_cbranch_scc0 .LBB0_597
	s_and_b64 vcc, exec, s[46:47]
	s_cbranch_vccz .LBB0_600
	s_barrier

; #define PG8_STAGE(bufoff, gbase, voff) do { _Pragma("unroll") for (int _i = 0; _i < 2; ++_i) \
;         __builtin_amdgcn_global_load_lds((const unsigned*)((const char*)(gbase) + (voff)[_i]), (PG8_LAS unsigned*)(lds + (bufoff) + ldsw + _i * 8192), 16, 0, 0); } while (0)
; #define PG8_LDA(dst, b, h) do { _Pragma("unroll") for (int m = 0; m < 4; ++m) _Pragma("unroll") for (int k = 0; k < 2; ++k) dst[m][k] = *(const PG8_LAS bf16x8*)(lds + PG8_SA(b, h) + aoff + m * 2048 + k * 1024); } while (0)
; #define PG8_LDB(dst, b, h) do { _Pragma("unroll") for (int n = 0; n < 2; ++n) _Pragma("unroll") for (int k = 0; k < 2; ++k) dst[n][k] = *(const PG8_LAS bf16x8*)(lds + PG8_SB(b, h) + boff + n * 2048 + k * 1024); } while (0)
; #define PG8_WAIT_V(n) asm volatile("s_waitcnt vmcnt(" #n ")" ::: "memory")
; #define PG8_WAIT_L(n) asm volatile("s_waitcnt lgkmcnt(" #n ")" ::: "memory")
; #define PG8_BAR __builtin_amdgcn_s_barrier()
; #define PG8_SCHED __builtin_amdgcn_sched_barrier(0)
; template <class Epi, class Sched, bool ALIGN_EPI = false, bool SP2 = false>
; __device__ __forceinline__ void gemm_phase(PG8_LAS unsigned char* lds, const Gemm g, const Sched& S, const Epi& E, int tid_in) {
;     ...
;         const char* nA = has_next ? (const char*)g.A + (size_t)nxt.pm * tstep : cA; const char* nB = has_next ? (const char*)g.Bt + (size_t)nxt.pn * tstepB : cB;
;         for (int t = 0; t < nt; t += 2) {
;             const bool last = (t == nt - 2);
;             const char* a1 = cA + (size_t)(t + 1) * kstep;
;             const char* a2 = last ? nA : cA + (size_t)(t + 2) * kstep; const char* b2 = last ? nB : cB + (size_t)(t + 2) * kstep;
;             const char* a3 = a2 + kstep; const char* b3 = b2 + kstep;
;             if (last && has_next) S.a_ready(nxt);
;             if constexpr (SP2) {
;             PG8_LDB(B0, 0, 0); PG8_LDB(B1, 0, 1); PG8_SCHED; PG8_LDA(At, 0, 0); PG8_STAGE(PG8_SA(1, 1), a1 + hstep, voffA);
;             PG8_WAIT_V(8); PG8_WAIT_L(0); PG8_BAR; PG8_MMA(0, 0, At, B0); PG8_MMA(0, 1, At, B1); PG8_BAR; PG8_SCHED;
;             PG8_LDA(At, 0, 1); PG8_STAGE(PG8_SB(0, 0), b2, voffB); PG8_STAGE(PG8_SB(0, 1), b2 + hstepB, voffB); PG8_STAGE(PG8_SA(0, 0), a2, voffA);
;             PG8_WAIT_V(8); PG8_WAIT_L(0); PG8_BAR; PG8_MMA(1, 0, At, B0); PG8_MMA(1, 1, At, B1); PG8_BAR; PG8_SCHED;
.Lkb_skip_5:
.LBB0_767:
	ds_read_b128 v[146:149], v153
	ds_read_b128 v[158:161], v153 offset:1024
	ds_read_b128 v[162:165], v153 offset:2048
	ds_read_b128 v[166:169], v153 offset:3072
	ds_read_b128 v[170:173], v154
	ds_read_b128 v[174:177], v154 offset:1024
	ds_read_b128 v[178:181], v154 offset:2048
	ds_read_b128 v[182:185], v154 offset:3072
	s_add_u32 s26, s62, 0xfffc0080
	s_addc_u32 s27, s63, -1
	s_cmp_eq_u32 s83, 12
	s_cselect_b32 s67, s53, s27
	s_cselect_b32 s66, s59, s26
	s_cselect_b32 s65, s51, s79
	s_cselect_b32 s64, s77, s78
	s_add_i32 m0, s61, 0xc000
	ds_read_b128 v[186:189], v155
	ds_read_b128 v[190:193], v155 offset:1024
	ds_read_b128 v[194:197], v155 offset:2048
	ds_read_b128 v[198:201], v155 offset:3072
	ds_read_b128 v[202:205], v155 offset:4096
	ds_read_b128 v[206:209], v155 offset:5120
	ds_read_b128 v[210:213], v155 offset:6144
	ds_read_b128 v[214:217], v155 offset:7168
	global_load_lds_dwordx4 v138, s[62:63]
	s_add_i32 m0, s61, 0xe000
	s_nop 0
	global_load_lds_dwordx4 v140, s[62:63]
	s_waitcnt vmcnt(8)
	s_waitcnt lgkmcnt(0)
	s_barrier
	s_setprio 1
	s_waitcnt lgkmcnt(0)
	v_mfma_f32_16x16x32_bf16 v[124:127], v[146:149], v[186:189], v[124:127]
	v_mfma_f32_16x16x32_bf16 v[120:123], v[162:165], v[186:189], v[120:123]
	v_mfma_f32_16x16x32_bf16 v[108:111], v[146:149], v[194:197], v[108:111]
	v_mfma_f32_16x16x32_bf16 v[104:107], v[162:165], v[194:197], v[104:107]
	v_mfma_f32_16x16x32_bf16 v[92:95], v[146:149], v[202:205], v[92:95]
	v_mfma_f32_16x16x32_bf16 v[88:91], v[162:165], v[202:205], v[88:91]
	v_mfma_f32_16x16x32_bf16 v[76:79], v[146:149], v[210:213], v[76:79]
	v_mfma_f32_16x16x32_bf16 v[72:75], v[162:165], v[210:213], v[72:75]
	v_mfma_f32_16x16x32_bf16 v[124:127], v[158:161], v[190:193], v[124:127]
	v_mfma_f32_16x16x32_bf16 v[120:123], v[166:169], v[190:193], v[120:123]
	v_mfma_f32_16x16x32_bf16 v[108:111], v[158:161], v[198:201], v[108:111]
	v_mfma_f32_16x16x32_bf16 v[104:107], v[166:169], v[198:201], v[104:107]
	v_mfma_f32_16x16x32_bf16 v[92:95], v[158:161], v[206:209], v[92:95]
	v_mfma_f32_16x16x32_bf16 v[88:91], v[166:169], v[206:209], v[88:91]
	v_mfma_f32_16x16x32_bf16 v[76:79], v[158:161], v[214:217], v[76:79]
	v_mfma_f32_16x16x32_bf16 v[72:75], v[166:169], v[214:217], v[72:75]
	s_setprio 0
	s_setprio 1
	v_mfma_f32_16x16x32_bf16 v[116:119], v[170:173], v[186:189], v[116:119]
	v_mfma_f32_16x16x32_bf16 v[112:115], v[178:181], v[186:189], v[112:115]
	v_mfma_f32_16x16x32_bf16 v[100:103], v[170:173], v[194:197], v[100:103]
	v_mfma_f32_16x16x32_bf16 v[96:99], v[178:181], v[194:197], v[96:99]
	v_mfma_f32_16x16x32_bf16 v[84:87], v[170:173], v[202:205], v[84:87]
	v_mfma_f32_16x16x32_bf16 v[80:83], v[178:181], v[202:205], v[80:83]
	v_mfma_f32_16x16x32_bf16 v[68:71], v[170:173], v[210:213], v[68:71]
	v_mfma_f32_16x16x32_bf16 v[64:67], v[178:181], v[210:213], v[64:67]
	v_mfma_f32_16x16x32_bf16 v[116:119], v[174:177], v[190:193], v[116:119]
	v_mfma_f32_16x16x32_bf16 v[112:115], v[182:185], v[190:193], v[112:115]
	v_mfma_f32_16x16x32_bf16 v[100:103], v[174:177], v[198:201], v[100:103]
	v_mfma_f32_16x16x32_bf16 v[96:99], v[182:185], v[198:201], v[96:99]
	v_mfma_f32_16x16x32_bf16 v[84:87], v[174:177], v[206:209], v[84:87]
	v_mfma_f32_16x16x32_bf16 v[80:83], v[182:185], v[206:209], v[80:83]
	v_mfma_f32_16x16x32_bf16 v[68:71], v[174:177], v[214:217], v[68:71]
	v_mfma_f32_16x16x32_bf16 v[64:67], v[182:185], v[214:217], v[64:67]
	s_setprio 0
	s_barrier
	s_add_i32 s26, s75, s68
	s_mov_b32 m0, s26
	ds_read_b128 v[186:189], v155 offset:16384
	ds_read_b128 v[190:193], v155 offset:17408
	ds_read_b128 v[194:197], v155 offset:18432
	ds_read_b128 v[198:201], v155 offset:19456
	ds_read_b128 v[202:205], v155 offset:20480
	ds_read_b128 v[206:209], v155 offset:21504
	ds_read_b128 v[210:213], v155 offset:22528
	ds_read_b128 v[214:217], v155 offset:23552
	global_load_lds_dwordx4 v130, s[64:65]
	s_add_i32 m0, s26, 0x2000
	s_add_u32 s26, s64, 0x10000
	s_addc_u32 s27, s65, 0
	s_add_i32 s33, s76, s68
	global_load_lds_dwordx4 v134, s[64:65]
	s_mov_b32 m0, s33
	s_nop 0
	global_load_lds_dwordx4 v130, s[26:27]
	s_add_i32 m0, s33, 0x2000
	s_nop 0
	global_load_lds_dwordx4 v134, s[26:27]
	s_mov_b32 m0, s61
	s_nop 0
	global_load_lds_dwordx4 v128, s[66:67]
	s_mov_b32 m0, s69
	s_nop 0
	global_load_lds_dwordx4 v132, s[66:67]
	s_waitcnt vmcnt(8)
	s_waitcnt lgkmcnt(0)
	s_barrier
	s_setprio 1
	s_waitcnt lgkmcnt(0)
	v_mfma_f32_16x16x32_bf16 v[60:63], v[146:149], v[186:189], v[60:63]
	v_mfma_f32_16x16x32_bf16 v[56:59], v[162:165], v[186:189], v[56:59]
	v_mfma_f32_16x16x32_bf16 v[44:47], v[146:149], v[194:197], v[44:47]
	v_mfma_f32_16x16x32_bf16 v[40:43], v[162:165], v[194:197], v[40:43]
	v_mfma_f32_16x16x32_bf16 v[28:31], v[146:149], v[202:205], v[28:31]
	v_mfma_f32_16x16x32_bf16 v[24:27], v[162:165], v[202:205], v[24:27]
	v_mfma_f32_16x16x32_bf16 v[12:15], v[146:149], v[210:213], v[12:15]
	v_mfma_f32_16x16x32_bf16 v[8:11], v[162:165], v[210:213], v[8:11]
	v_mfma_f32_16x16x32_bf16 v[60:63], v[158:161], v[190:193], v[60:63]
	v_mfma_f32_16x16x32_bf16 v[56:59], v[166:169], v[190:193], v[56:59]
	v_mfma_f32_16x16x32_bf16 v[44:47], v[158:161], v[198:201], v[44:47]
	v_mfma_f32_16x16x32_bf16 v[40:43], v[166:169], v[198:201], v[40:43]
	v_mfma_f32_16x16x32_bf16 v[28:31], v[158:161], v[206:209], v[28:31]
	v_mfma_f32_16x16x32_bf16 v[24:27], v[166:169], v[206:209], v[24:27]
	v_mfma_f32_16x16x32_bf16 v[12:15], v[158:161], v[214:217], v[12:15]
	v_mfma_f32_16x16x32_bf16 v[8:11], v[166:169], v[214:217], v[8:11]
	s_setprio 0
	s_setprio 1
	v_mfma_f32_16x16x32_bf16 v[52:55], v[170:173], v[186:189], v[52:55]
	v_mfma_f32_16x16x32_bf16 v[48:51], v[178:181], v[186:189], v[48:51]
	v_mfma_f32_16x16x32_bf16 v[36:39], v[170:173], v[194:197], v[36:39]
	v_mfma_f32_16x16x32_bf16 v[32:35], v[178:181], v[194:197], v[32:35]
	v_mfma_f32_16x16x32_bf16 v[20:23], v[170:173], v[202:205], v[20:23]
	v_mfma_f32_16x16x32_bf16 v[16:19], v[178:181], v[202:205], v[16:19]
	v_mfma_f32_16x16x32_bf16 v[4:7], v[170:173], v[210:213], v[4:7]
	v_mfma_f32_16x16x32_bf16 v[0:3], v[178:181], v[210:213], v[0:3]
	v_mfma_f32_16x16x32_bf16 v[52:55], v[174:177], v[190:193], v[52:55]
	v_mfma_f32_16x16x32_bf16 v[48:51], v[182:185], v[190:193], v[48:51]
	v_mfma_f32_16x16x32_bf16 v[36:39], v[174:177], v[198:201], v[36:39]
	v_mfma_f32_16x16x32_bf16 v[32:35], v[182:185], v[198:201], v[32:35]
	v_mfma_f32_16x16x32_bf16 v[20:23], v[174:177], v[206:209], v[20:23]
	v_mfma_f32_16x16x32_bf16 v[16:19], v[182:185], v[206:209], v[16:19]
	v_mfma_f32_16x16x32_bf16 v[4:7], v[174:177], v[214:217], v[4:7]
	v_mfma_f32_16x16x32_bf16 v[0:3], v[182:185], v[214:217], v[0:3]
	s_setprio 0
	s_barrier
; #define PG8_STAGE(bufoff, gbase, voff) do { _Pragma("unroll") for (int _i = 0; _i < 2; ++_i) \
;         __builtin_amdgcn_global_load_lds((const unsigned*)((const char*)(gbase) + (voff)[_i]), (PG8_LAS unsigned*)(lds + (bufoff) + ldsw + _i * 8192), 16, 0, 0); } while (0)
; #define PG8_LDA(dst, b, h) do { _Pragma("unroll") for (int m = 0; m < 4; ++m) _Pragma("unroll") for (int k = 0; k < 2; ++k) dst[m][k] = *(const PG8_LAS bf16x8*)(lds + PG8_SA(b, h) + aoff + m * 2048 + k * 1024); } while (0)
; #define PG8_LDB(dst, b, h) do { _Pragma("unroll") for (int n = 0; n < 2; ++n) _Pragma("unroll") for (int k = 0; k < 2; ++k) dst[n][k] = *(const PG8_LAS bf16x8*)(lds + PG8_SB(b, h) + boff + n * 2048 + k * 1024); } while (0)
; #define PG8_MMA(ai, bj, At, Bt) do { __builtin_amdgcn_s_setprio(1); _Pragma("unroll") for (int m = 0; m < 4; ++m) _Pragma("unroll") for (int n = 0; n < 2; ++n) _Pragma("unroll") for (int k = 0; k < 2; ++k) \
;         acc[ai][bj][m][n] = __builtin_amdgcn_mfma_f32_16x16x32_bf16(Bt[n][k], At[m][k], acc[ai][bj][m][n], 0, 0, 0); __builtin_amdgcn_s_setprio(0); } while (0)
; #define PG8_WAIT_V(n) asm volatile("s_waitcnt vmcnt(" #n ")" ::: "memory")
; #define PG8_WAIT_L(n) asm volatile("s_waitcnt lgkmcnt(" #n ")" ::: "memory")
; #define PG8_BAR __builtin_amdgcn_s_barrier()
; #define PG8_SCHED __builtin_amdgcn_sched_barrier(0)
; template <class Epi, class Sched, bool ALIGN_EPI = false, bool SP2 = false>
; __device__ __forceinline__ void gemm_phase(PG8_LAS unsigned char* lds, const Gemm g, const Sched& S, const Epi& E, int tid_in) {
;     ...
;             PG8_LDB(B0, 1, 0); PG8_LDB(B1, 1, 1); PG8_SCHED; PG8_LDA(At, 1, 0); PG8_STAGE(PG8_SA(0, 1), a2 + hstep, voffA);
;             PG8_WAIT_V(8); PG8_WAIT_L(0); PG8_BAR; PG8_MMA(0, 0, At, B0); PG8_MMA(0, 1, At, B1); PG8_BAR; PG8_SCHED;
;             PG8_LDA(At, 1, 1); PG8_STAGE(PG8_SB(1, 0), b3, voffB); PG8_STAGE(PG8_SB(1, 1), b3 + hstepB, voffB); PG8_STAGE(PG8_SA(1, 0), a3, voffA);
	s_add_i32 s33, 0, 0x18000
	s_add_i32 s84, 0, 0x1c000
	v_add_u32_e32 v166, s33, v137
	v_add_u32_e32 v182, s84, v137
	ds_read_b128 v[146:149], v166
	ds_read_b128 v[158:161], v166 offset:1024
	ds_read_b128 v[162:165], v166 offset:2048
	ds_read_b128 v[166:169], v166 offset:3072
	ds_read_b128 v[170:173], v182
	ds_read_b128 v[174:177], v182 offset:1024
	ds_read_b128 v[178:181], v182 offset:2048
	ds_read_b128 v[182:185], v182 offset:3072
	s_add_u32 s26, s66, 0x40000
	s_addc_u32 s27, s67, 0
	s_mov_b32 m0, s70
	ds_read_b128 v[186:189], v155 offset:32768
	ds_read_b128 v[190:193], v155 offset:33792
	ds_read_b128 v[194:197], v155 offset:34816
	ds_read_b128 v[198:201], v155 offset:35840
	ds_read_b128 v[202:205], v155 offset:36864
	ds_read_b128 v[206:209], v155 offset:37888
	ds_read_b128 v[210:213], v155 offset:38912
	ds_read_b128 v[214:217], v155 offset:39936
	global_load_lds_dwordx4 v128, s[26:27]
	s_mov_b32 m0, s71
	s_nop 0
	global_load_lds_dwordx4 v132, s[26:27]
	s_waitcnt vmcnt(8)
	s_waitcnt lgkmcnt(0)
	s_barrier
	s_setprio 1
	s_waitcnt lgkmcnt(0)
	v_mfma_f32_16x16x32_bf16 v[124:127], v[146:149], v[186:189], v[124:127]
	v_mfma_f32_16x16x32_bf16 v[120:123], v[162:165], v[186:189], v[120:123]
	v_mfma_f32_16x16x32_bf16 v[108:111], v[146:149], v[194:197], v[108:111]
	v_mfma_f32_16x16x32_bf16 v[104:107], v[162:165], v[194:197], v[104:107]
	v_mfma_f32_16x16x32_bf16 v[92:95], v[146:149], v[202:205], v[92:95]
	v_mfma_f32_16x16x32_bf16 v[88:91], v[162:165], v[202:205], v[88:91]
	v_mfma_f32_16x16x32_bf16 v[76:79], v[146:149], v[210:213], v[76:79]
	v_mfma_f32_16x16x32_bf16 v[72:75], v[162:165], v[210:213], v[72:75]
	v_mfma_f32_16x16x32_bf16 v[124:127], v[158:161], v[190:193], v[124:127]
	v_mfma_f32_16x16x32_bf16 v[120:123], v[166:169], v[190:193], v[120:123]
	v_mfma_f32_16x16x32_bf16 v[108:111], v[158:161], v[198:201], v[108:111]
	v_mfma_f32_16x16x32_bf16 v[104:107], v[166:169], v[198:201], v[104:107]
	v_mfma_f32_16x16x32_bf16 v[92:95], v[158:161], v[206:209], v[92:95]
	v_mfma_f32_16x16x32_bf16 v[88:91], v[166:169], v[206:209], v[88:91]
	v_mfma_f32_16x16x32_bf16 v[76:79], v[158:161], v[214:217], v[76:79]
	v_mfma_f32_16x16x32_bf16 v[72:75], v[166:169], v[214:217], v[72:75]
	s_setprio 0
	s_setprio 1
	v_mfma_f32_16x16x32_bf16 v[116:119], v[170:173], v[186:189], v[116:119]
	v_mfma_f32_16x16x32_bf16 v[112:115], v[178:181], v[186:189], v[112:115]
	v_mfma_f32_16x16x32_bf16 v[100:103], v[170:173], v[194:197], v[100:103]
	v_mfma_f32_16x16x32_bf16 v[96:99], v[178:181], v[194:197], v[96:99]
	v_mfma_f32_16x16x32_bf16 v[84:87], v[170:173], v[202:205], v[84:87]
	v_mfma_f32_16x16x32_bf16 v[80:83], v[178:181], v[202:205], v[80:83]
	v_mfma_f32_16x16x32_bf16 v[68:71], v[170:173], v[210:213], v[68:71]
	v_mfma_f32_16x16x32_bf16 v[64:67], v[178:181], v[210:213], v[64:67]
	v_mfma_f32_16x16x32_bf16 v[116:119], v[174:177], v[190:193], v[116:119]
	v_mfma_f32_16x16x32_bf16 v[112:115], v[182:185], v[190:193], v[112:115]
	v_mfma_f32_16x16x32_bf16 v[100:103], v[174:177], v[198:201], v[100:103]
	v_mfma_f32_16x16x32_bf16 v[96:99], v[182:185], v[198:201], v[96:99]
	v_mfma_f32_16x16x32_bf16 v[84:87], v[174:177], v[206:209], v[84:87]
	v_mfma_f32_16x16x32_bf16 v[80:83], v[182:185], v[206:209], v[80:83]
	v_mfma_f32_16x16x32_bf16 v[68:71], v[174:177], v[214:217], v[68:71]
	v_mfma_f32_16x16x32_bf16 v[64:67], v[182:185], v[214:217], v[64:67]
	s_setprio 0
	s_barrier
	s_add_i32 s26, s33, s68
	s_add_i32 m0, s26, 0xffffff80
	ds_read_b128 v[186:189], v155 offset:49152
	ds_read_b128 v[190:193], v155 offset:50176
	ds_read_b128 v[194:197], v155 offset:51200
	ds_read_b128 v[198:201], v155 offset:52224
	ds_read_b128 v[202:205], v155 offset:53248
	ds_read_b128 v[206:209], v155 offset:54272
	ds_read_b128 v[210:213], v155 offset:55296
	ds_read_b128 v[214:217], v155 offset:56320
	global_load_lds_dwordx4 v130, s[64:65] offset:128
	s_add_i32 m0, s26, 0x1f80
	s_add_u32 s26, s64, 0x10080
	s_addc_u32 s27, s65, 0
	s_add_i32 s33, s84, s68
	global_load_lds_dwordx4 v134, s[64:65] offset:128
	s_mov_b32 m0, s33
	s_nop 0
	global_load_lds_dwordx4 v130, s[26:27]
	s_add_i32 m0, s33, 0x2000
	s_nop 0
	global_load_lds_dwordx4 v134, s[26:27]
	s_add_i32 m0, s73, 0xffffff80
	s_nop 0
	global_load_lds_dwordx4 v128, s[66:67] offset:128
	s_add_i32 m0, s74, 0xffffff80
	s_nop 0
	global_load_lds_dwordx4 v132, s[66:67] offset:128
	s_waitcnt vmcnt(8)
	s_waitcnt lgkmcnt(0)
	s_barrier
; #define PG8_STAGE(bufoff, gbase, voff) do { _Pragma("unroll") for (int _i = 0; _i < 2; ++_i) \
;         __builtin_amdgcn_global_load_lds((const unsigned*)((const char*)(gbase) + (voff)[_i]), (PG8_LAS unsigned*)(lds + (bufoff) + ldsw + _i * 8192), 16, 0, 0); } while (0)
; #define PG8_LDA(dst, b, h) do { _Pragma("unroll") for (int m = 0; m < 4; ++m) _Pragma("unroll") for (int k = 0; k < 2; ++k) dst[m][k] = *(const PG8_LAS bf16x8*)(lds + PG8_SA(b, h) + aoff + m * 2048 + k * 1024); } while (0)
; #define PG8_WAIT_V(n) asm volatile("s_waitcnt vmcnt(" #n ")" ::: "memory")
; #define PG8_WAIT_L(n) asm volatile("s_waitcnt lgkmcnt(" #n ")" ::: "memory")
; #define PG8_BAR __builtin_amdgcn_s_barrier()
; #define PG8_SCHED __builtin_amdgcn_sched_barrier(0)
; template <class Epi, class Sched, bool ALIGN_EPI = false, bool SP2 = false>
; __device__ __forceinline__ void gemm_phase(PG8_LAS unsigned char* lds, const Gemm g, const Sched& S, const Epi& E, int tid_in) {
;     ...
;             PG8_WAIT_V(8); PG8_WAIT_L(0); PG8_BAR; PG8_MMA(0, 0, At, B0); PG8_MMA(0, 1, At, B1); PG8_BAR; PG8_SCHED;
;             PG8_LDA(At, 1, 1); PG8_STAGE(PG8_SB(1, 0), b3, voffB); PG8_STAGE(PG8_SB(1, 1), b3 + hstepB, voffB); PG8_STAGE(PG8_SA(1, 0), a3, voffA);
;             PG8_WAIT_V(8); PG8_WAIT_L(0); PG8_BAR; PG8_MMA(1, 0, At, B0); PG8_MMA(1, 1, At, B1); PG8_BAR; PG8_SCHED;
;     __device__ __forceinline__ void operator()(const f32x4 (&acc)[2][2][4][2], const Unit& u, int wr, int wc, int fr, int fq) const {
;     ...
;                 const int row = u.pm * BM + ai * HALF + wr * 64 + m * 16 + r; float q = 0.f;
; #pragma unroll
;                 for (int bj = 0; bj < 2; ++bj) {
;                     const size_t off = (size_t)row * 2048 + u.pn * BM + wc * 64 + bj * 32 + 8 * p;
;                     f32x4 b0, b1;
;                     if (BASE_F32) { b0 = *(const f32x4*)((const float*)base + off); b1 = *(const f32x4*)((const float*)base + off + 4); }
;                     else { const u32x4 bb = *(const u32x4*)((const bf16_t*)base + off);
;                         b0 = (f32x4){__uint_as_float(bb.x << 16), __uint_as_float(bb.x & 0xffff0000u), __uint_as_float(bb.y << 16), __uint_as_float(bb.y & 0xffff0000u)};
;                         b1 = (f32x4){__uint_as_float(bb.z << 16), __uint_as_float(bb.z & 0xffff0000u), __uint_as_float(bb.w << 16), __uint_as_float(bb.w & 0xffff0000u)}; }
	s_setprio 1
	s_waitcnt lgkmcnt(0)
	v_mfma_f32_16x16x32_bf16 v[60:63], v[146:149], v[186:189], v[60:63]
	v_mfma_f32_16x16x32_bf16 v[56:59], v[162:165], v[186:189], v[56:59]
	v_mfma_f32_16x16x32_bf16 v[44:47], v[146:149], v[194:197], v[44:47]
	v_mfma_f32_16x16x32_bf16 v[40:43], v[162:165], v[194:197], v[40:43]
	v_mfma_f32_16x16x32_bf16 v[28:31], v[146:149], v[202:205], v[28:31]
	v_mfma_f32_16x16x32_bf16 v[24:27], v[162:165], v[202:205], v[24:27]
	v_mfma_f32_16x16x32_bf16 v[12:15], v[146:149], v[210:213], v[12:15]
	v_mfma_f32_16x16x32_bf16 v[8:11], v[162:165], v[210:213], v[8:11]
	v_mfma_f32_16x16x32_bf16 v[60:63], v[158:161], v[190:193], v[60:63]
	v_mfma_f32_16x16x32_bf16 v[56:59], v[166:169], v[190:193], v[56:59]
	v_mfma_f32_16x16x32_bf16 v[44:47], v[158:161], v[198:201], v[44:47]
	v_mfma_f32_16x16x32_bf16 v[40:43], v[166:169], v[198:201], v[40:43]
	v_mfma_f32_16x16x32_bf16 v[28:31], v[158:161], v[206:209], v[28:31]
	v_mfma_f32_16x16x32_bf16 v[24:27], v[166:169], v[206:209], v[24:27]
	v_mfma_f32_16x16x32_bf16 v[12:15], v[158:161], v[214:217], v[12:15]
	v_mfma_f32_16x16x32_bf16 v[8:11], v[166:169], v[214:217], v[8:11]
	s_setprio 0
	s_setprio 1
	v_mfma_f32_16x16x32_bf16 v[52:55], v[170:173], v[186:189], v[52:55]
	v_mfma_f32_16x16x32_bf16 v[48:51], v[178:181], v[186:189], v[48:51]
	v_mfma_f32_16x16x32_bf16 v[36:39], v[170:173], v[194:197], v[36:39]
	v_mfma_f32_16x16x32_bf16 v[32:35], v[178:181], v[194:197], v[32:35]
	v_mfma_f32_16x16x32_bf16 v[20:23], v[170:173], v[202:205], v[20:23]
	v_mfma_f32_16x16x32_bf16 v[16:19], v[178:181], v[202:205], v[16:19]
	v_mfma_f32_16x16x32_bf16 v[4:7], v[170:173], v[210:213], v[4:7]
	v_mfma_f32_16x16x32_bf16 v[0:3], v[178:181], v[210:213], v[0:3]
	v_mfma_f32_16x16x32_bf16 v[52:55], v[174:177], v[190:193], v[52:55]
	v_mfma_f32_16x16x32_bf16 v[48:51], v[182:185], v[190:193], v[48:51]
	v_mfma_f32_16x16x32_bf16 v[36:39], v[174:177], v[198:201], v[36:39]
	v_mfma_f32_16x16x32_bf16 v[32:35], v[182:185], v[198:201], v[32:35]
	v_mfma_f32_16x16x32_bf16 v[20:23], v[174:177], v[206:209], v[20:23]
	v_mfma_f32_16x16x32_bf16 v[16:19], v[182:185], v[206:209], v[16:19]
	v_mfma_f32_16x16x32_bf16 v[4:7], v[174:177], v[214:217], v[4:7]
	v_mfma_f32_16x16x32_bf16 v[0:3], v[182:185], v[214:217], v[0:3]
	s_setprio 0
	s_barrier
	s_add_i32 s83, s83, 2
	s_add_u32 s62, s62, 0x100
	s_addc_u32 s63, s63, 0
	s_add_u32 s78, s78, 0x100
	s_addc_u32 s79, s79, 0
	s_cmp_gt_u32 s83, 13
	s_cbranch_scc0 .LBB0_767
	v_lshl_add_u32 v148, s58, 8, v150
	v_lshl_or_b32 v146, s60, 8, v136
	v_lshl_add_u32 v147, v148, 11, v146
	v_lshlrev_b32_e32 v159, 1, v147
	v_lshlrev_b32_e32 v208, 3, v148
	global_load_dwordx4 v[160:163], v159, s[28:29]
	global_load_dwordx4 v[164:167], v159, s[28:29] offset:64
	v_add_u32_e32 v149, 0x10000, v159
	global_load_dwordx4 v[168:171], v149, s[28:29]
	global_load_dwordx4 v[172:175], v149, s[28:29] offset:64
	v_add_u32_e32 v209, 0x20000, v159
	global_load_dwordx4 v[176:179], v209, s[28:29]
	global_load_dwordx4 v[180:183], v209, s[28:29] offset:64
	v_add_u32_e32 v149, 0x30000, v159
	global_load_dwordx4 v[184:187], v149, s[28:29]
	global_load_dwordx4 v[188:191], v149, s[28:29] offset:64
	v_add_u32_e32 v209, 0x80000, v159
	global_load_dwordx4 v[192:195], v209, s[28:29]
	global_load_dwordx4 v[196:199], v209, s[28:29] offset:64
	v_add_u32_e32 v149, 0x90000, v159
	global_load_dwordx4 v[200:203], v149, s[28:29]
	global_load_dwordx4 v[204:207], v149, s[28:29] offset:64
	v_add_u32_e32 v209, 0xa0000, v159
	global_load_dwordx4 v[212:215], v209, s[28:29]
	global_load_dwordx4 v[216:219], v209, s[28:29] offset:64
	v_add_u32_e32 v149, 0xb0000, v159
	global_load_dwordx4 v[220:223], v149, s[28:29]
	global_load_dwordx4 v[224:227], v149, s[28:29] offset:64
	s_and_b64 vcc, exec, s[48:49]
	s_cbranch_vccz .LBB0_770
	s_barrier

; #define PG8_STAGE(bufoff, gbase, voff) do { _Pragma("unroll") for (int _i = 0; _i < 2; ++_i) \
;         __builtin_amdgcn_global_load_lds((const unsigned*)((const char*)(gbase) + (voff)[_i]), (PG8_LAS unsigned*)(lds + (bufoff) + ldsw + _i * 8192), 16, 0, 0); } while (0)
; #define PG8_LDA(dst, b, h) do { _Pragma("unroll") for (int m = 0; m < 4; ++m) _Pragma("unroll") for (int k = 0; k < 2; ++k) dst[m][k] = *(const PG8_LAS bf16x8*)(lds + PG8_SA(b, h) + aoff + m * 2048 + k * 1024); } while (0)
; #define PG8_LDB(dst, b, h) do { _Pragma("unroll") for (int n = 0; n < 2; ++n) _Pragma("unroll") for (int k = 0; k < 2; ++k) dst[n][k] = *(const PG8_LAS bf16x8*)(lds + PG8_SB(b, h) + boff + n * 2048 + k * 1024); } while (0)
; #define PG8_MMA(ai, bj, At, Bt) do { __builtin_amdgcn_s_setprio(1); _Pragma("unroll") for (int m = 0; m < 4; ++m) _Pragma("unroll") for (int n = 0; n < 2; ++n) _Pragma("unroll") for (int k = 0; k < 2; ++k) \
;         acc[ai][bj][m][n] = __builtin_amdgcn_mfma_f32_16x16x32_bf16(Bt[n][k], At[m][k], acc[ai][bj][m][n], 0, 0, 0); __builtin_amdgcn_s_setprio(0); } while (0)
; #define PG8_WAIT_V(n) asm volatile("s_waitcnt vmcnt(" #n ")" ::: "memory")
; #define PG8_WAIT_L(n) asm volatile("s_waitcnt lgkmcnt(" #n ")" ::: "memory")
; #define PG8_BAR __builtin_amdgcn_s_barrier()
; #define PG8_SCHED __builtin_amdgcn_sched_barrier(0)
; template <class Epi, class Sched, bool ALIGN_EPI = false, bool SP2 = false>
; __device__ __forceinline__ void gemm_phase(PG8_LAS unsigned char* lds, const Gemm g, const Sched& S, const Epi& E, int tid_in) {
;     ...
;             PG8_LDB(B0, 0, 0); PG8_LDB(B1, 0, 1); PG8_SCHED; PG8_LDA(At, 0, 0); PG8_STAGE(PG8_SA(1, 1), a1 + hstep, voffA);
;             PG8_WAIT_V(8); PG8_WAIT_L(0); PG8_BAR; PG8_MMA(0, 0, At, B0); PG8_MMA(0, 1, At, B1); PG8_BAR; PG8_SCHED;
;             PG8_LDA(At, 0, 1); PG8_STAGE(PG8_SB(0, 0), b2, voffB); PG8_STAGE(PG8_SB(0, 1), b2 + hstepB, voffB); PG8_STAGE(PG8_SA(0, 0), a2, voffA);
;             PG8_WAIT_V(8); PG8_WAIT_L(0); PG8_BAR; PG8_MMA(1, 0, At, B0); PG8_MMA(1, 1, At, B1); PG8_BAR; PG8_SCHED;
.Lkb_skip_6:
.LBB0_869:
	ds_read_b128 v[156:159], v150
	ds_read_b128 v[160:163], v150 offset:1024
	ds_read_b128 v[164:167], v150 offset:2048
	ds_read_b128 v[168:171], v150 offset:3072
	ds_read_b128 v[172:175], v151
	ds_read_b128 v[176:179], v151 offset:1024
	ds_read_b128 v[180:183], v151 offset:2048
	ds_read_b128 v[184:187], v151 offset:3072
	s_add_u32 s26, s50, 0xfff80080
	s_addc_u32 s27, s51, -1
	s_cmp_eq_u32 s72, 28
	s_cselect_b32 s55, s41, s27
	s_cselect_b32 s54, s68, s26
	s_cselect_b32 s53, s39, s71
	s_cselect_b32 s52, s69, s70
	s_add_i32 m0, s49, 0xc000
	ds_read_b128 v[188:191], v152
	ds_read_b128 v[192:195], v152 offset:1024
	ds_read_b128 v[196:199], v152 offset:2048
	ds_read_b128 v[200:203], v152 offset:3072
	ds_read_b128 v[204:207], v152 offset:4096
	ds_read_b128 v[208:211], v152 offset:5120
	ds_read_b128 v[212:215], v152 offset:6144
	ds_read_b128 v[216:219], v152 offset:7168
	global_load_lds_dwordx4 v138, s[50:51]
	s_add_i32 m0, s49, 0xe000
	s_nop 0
	global_load_lds_dwordx4 v140, s[50:51]
	s_waitcnt vmcnt(8)
	s_waitcnt lgkmcnt(0)
	s_barrier
	s_setprio 1
	s_waitcnt lgkmcnt(0)
	v_mfma_f32_16x16x32_bf16 v[124:127], v[156:159], v[188:191], v[124:127]
	v_mfma_f32_16x16x32_bf16 v[120:123], v[164:167], v[188:191], v[120:123]
	v_mfma_f32_16x16x32_bf16 v[108:111], v[156:159], v[196:199], v[108:111]
	v_mfma_f32_16x16x32_bf16 v[104:107], v[164:167], v[196:199], v[104:107]
	v_mfma_f32_16x16x32_bf16 v[92:95], v[156:159], v[204:207], v[92:95]
	v_mfma_f32_16x16x32_bf16 v[88:91], v[164:167], v[204:207], v[88:91]
	v_mfma_f32_16x16x32_bf16 v[76:79], v[156:159], v[212:215], v[76:79]
	v_mfma_f32_16x16x32_bf16 v[72:75], v[164:167], v[212:215], v[72:75]
	v_mfma_f32_16x16x32_bf16 v[124:127], v[160:163], v[192:195], v[124:127]
	v_mfma_f32_16x16x32_bf16 v[120:123], v[168:171], v[192:195], v[120:123]
	v_mfma_f32_16x16x32_bf16 v[108:111], v[160:163], v[200:203], v[108:111]
	v_mfma_f32_16x16x32_bf16 v[104:107], v[168:171], v[200:203], v[104:107]
	v_mfma_f32_16x16x32_bf16 v[92:95], v[160:163], v[208:211], v[92:95]
	v_mfma_f32_16x16x32_bf16 v[88:91], v[168:171], v[208:211], v[88:91]
	v_mfma_f32_16x16x32_bf16 v[76:79], v[160:163], v[216:219], v[76:79]
	v_mfma_f32_16x16x32_bf16 v[72:75], v[168:171], v[216:219], v[72:75]
	s_setprio 0
	s_setprio 1
	v_mfma_f32_16x16x32_bf16 v[116:119], v[172:175], v[188:191], v[116:119]
	v_mfma_f32_16x16x32_bf16 v[112:115], v[180:183], v[188:191], v[112:115]
	v_mfma_f32_16x16x32_bf16 v[100:103], v[172:175], v[196:199], v[100:103]
	v_mfma_f32_16x16x32_bf16 v[96:99], v[180:183], v[196:199], v[96:99]
	v_mfma_f32_16x16x32_bf16 v[84:87], v[172:175], v[204:207], v[84:87]
	v_mfma_f32_16x16x32_bf16 v[80:83], v[180:183], v[204:207], v[80:83]
	v_mfma_f32_16x16x32_bf16 v[68:71], v[172:175], v[212:215], v[68:71]
	v_mfma_f32_16x16x32_bf16 v[64:67], v[180:183], v[212:215], v[64:67]
	v_mfma_f32_16x16x32_bf16 v[116:119], v[176:179], v[192:195], v[116:119]
	v_mfma_f32_16x16x32_bf16 v[112:115], v[184:187], v[192:195], v[112:115]
	v_mfma_f32_16x16x32_bf16 v[100:103], v[176:179], v[200:203], v[100:103]
	v_mfma_f32_16x16x32_bf16 v[96:99], v[184:187], v[200:203], v[96:99]
	v_mfma_f32_16x16x32_bf16 v[84:87], v[176:179], v[208:211], v[84:87]
	v_mfma_f32_16x16x32_bf16 v[80:83], v[184:187], v[208:211], v[80:83]
	v_mfma_f32_16x16x32_bf16 v[68:71], v[176:179], v[216:219], v[68:71]
	v_mfma_f32_16x16x32_bf16 v[64:67], v[184:187], v[216:219], v[64:67]
	s_setprio 0
	s_barrier
	s_add_i32 s26, s64, s56
	s_mov_b32 m0, s26
	ds_read_b128 v[188:191], v152 offset:16384
	ds_read_b128 v[192:195], v152 offset:17408
	ds_read_b128 v[196:199], v152 offset:18432
	ds_read_b128 v[200:203], v152 offset:19456
	ds_read_b128 v[204:207], v152 offset:20480
	ds_read_b128 v[208:211], v152 offset:21504
	ds_read_b128 v[212:215], v152 offset:22528
	ds_read_b128 v[216:219], v152 offset:23552
	global_load_lds_dwordx4 v130, s[52:53]
	s_add_i32 m0, s26, 0x2000
	s_add_u32 s26, s52, 0x20000
	s_addc_u32 s27, s53, 0
	s_add_i32 s33, s65, s56
	global_load_lds_dwordx4 v134, s[52:53]
	s_mov_b32 m0, s33
	s_nop 0
	global_load_lds_dwordx4 v130, s[26:27]
	s_add_i32 m0, s33, 0x2000
	s_nop 0
	global_load_lds_dwordx4 v134, s[26:27]
	s_mov_b32 m0, s49
	s_nop 0
	global_load_lds_dwordx4 v128, s[54:55]
	s_mov_b32 m0, s57
	s_nop 0
	global_load_lds_dwordx4 v132, s[54:55]
	s_waitcnt vmcnt(8)
	s_waitcnt lgkmcnt(0)
	s_barrier
	s_setprio 1
	s_waitcnt lgkmcnt(0)
	v_mfma_f32_16x16x32_bf16 v[60:63], v[156:159], v[188:191], v[60:63]
	v_mfma_f32_16x16x32_bf16 v[56:59], v[164:167], v[188:191], v[56:59]
	v_mfma_f32_16x16x32_bf16 v[44:47], v[156:159], v[196:199], v[44:47]
	v_mfma_f32_16x16x32_bf16 v[40:43], v[164:167], v[196:199], v[40:43]
	v_mfma_f32_16x16x32_bf16 v[28:31], v[156:159], v[204:207], v[28:31]
	v_mfma_f32_16x16x32_bf16 v[24:27], v[164:167], v[204:207], v[24:27]
	v_mfma_f32_16x16x32_bf16 v[12:15], v[156:159], v[212:215], v[12:15]
	v_mfma_f32_16x16x32_bf16 v[8:11], v[164:167], v[212:215], v[8:11]
	v_mfma_f32_16x16x32_bf16 v[60:63], v[160:163], v[192:195], v[60:63]
	v_mfma_f32_16x16x32_bf16 v[56:59], v[168:171], v[192:195], v[56:59]
	v_mfma_f32_16x16x32_bf16 v[44:47], v[160:163], v[200:203], v[44:47]
	v_mfma_f32_16x16x32_bf16 v[40:43], v[168:171], v[200:203], v[40:43]
	v_mfma_f32_16x16x32_bf16 v[28:31], v[160:163], v[208:211], v[28:31]
	v_mfma_f32_16x16x32_bf16 v[24:27], v[168:171], v[208:211], v[24:27]
	v_mfma_f32_16x16x32_bf16 v[12:15], v[160:163], v[216:219], v[12:15]
	v_mfma_f32_16x16x32_bf16 v[8:11], v[168:171], v[216:219], v[8:11]
	s_setprio 0
	s_setprio 1
	v_mfma_f32_16x16x32_bf16 v[52:55], v[172:175], v[188:191], v[52:55]
	v_mfma_f32_16x16x32_bf16 v[48:51], v[180:183], v[188:191], v[48:51]
	v_mfma_f32_16x16x32_bf16 v[36:39], v[172:175], v[196:199], v[36:39]
	v_mfma_f32_16x16x32_bf16 v[32:35], v[180:183], v[196:199], v[32:35]
	v_mfma_f32_16x16x32_bf16 v[20:23], v[172:175], v[204:207], v[20:23]
	v_mfma_f32_16x16x32_bf16 v[16:19], v[180:183], v[204:207], v[16:19]
	v_mfma_f32_16x16x32_bf16 v[4:7], v[172:175], v[212:215], v[4:7]
	v_mfma_f32_16x16x32_bf16 v[0:3], v[180:183], v[212:215], v[0:3]
	v_mfma_f32_16x16x32_bf16 v[52:55], v[176:179], v[192:195], v[52:55]
	v_mfma_f32_16x16x32_bf16 v[48:51], v[184:187], v[192:195], v[48:51]
	v_mfma_f32_16x16x32_bf16 v[36:39], v[176:179], v[200:203], v[36:39]
	v_mfma_f32_16x16x32_bf16 v[32:35], v[184:187], v[200:203], v[32:35]
	v_mfma_f32_16x16x32_bf16 v[20:23], v[176:179], v[208:211], v[20:23]
	v_mfma_f32_16x16x32_bf16 v[16:19], v[184:187], v[208:211], v[16:19]
	v_mfma_f32_16x16x32_bf16 v[4:7], v[176:179], v[216:219], v[4:7]
	v_mfma_f32_16x16x32_bf16 v[0:3], v[184:187], v[216:219], v[0:3]
	s_setprio 0
	s_barrier
; #define PG8_STAGE(bufoff, gbase, voff) do { _Pragma("unroll") for (int _i = 0; _i < 2; ++_i) \
;         __builtin_amdgcn_global_load_lds((const unsigned*)((const char*)(gbase) + (voff)[_i]), (PG8_LAS unsigned*)(lds + (bufoff) + ldsw + _i * 8192), 16, 0, 0); } while (0)
; #define PG8_LDA(dst, b, h) do { _Pragma("unroll") for (int m = 0; m < 4; ++m) _Pragma("unroll") for (int k = 0; k < 2; ++k) dst[m][k] = *(const PG8_LAS bf16x8*)(lds + PG8_SA(b, h) + aoff + m * 2048 + k * 1024); } while (0)
; #define PG8_LDB(dst, b, h) do { _Pragma("unroll") for (int n = 0; n < 2; ++n) _Pragma("unroll") for (int k = 0; k < 2; ++k) dst[n][k] = *(const PG8_LAS bf16x8*)(lds + PG8_SB(b, h) + boff + n * 2048 + k * 1024); } while (0)
; #define PG8_MMA(ai, bj, At, Bt) do { __builtin_amdgcn_s_setprio(1); _Pragma("unroll") for (int m = 0; m < 4; ++m) _Pragma("unroll") for (int n = 0; n < 2; ++n) _Pragma("unroll") for (int k = 0; k < 2; ++k) \
;         acc[ai][bj][m][n] = __builtin_amdgcn_mfma_f32_16x16x32_bf16(Bt[n][k], At[m][k], acc[ai][bj][m][n], 0, 0, 0); __builtin_amdgcn_s_setprio(0); } while (0)
; #define PG8_WAIT_V(n) asm volatile("s_waitcnt vmcnt(" #n ")" ::: "memory")
; #define PG8_WAIT_L(n) asm volatile("s_waitcnt lgkmcnt(" #n ")" ::: "memory")
; #define PG8_BAR __builtin_amdgcn_s_barrier()
; #define PG8_SCHED __builtin_amdgcn_sched_barrier(0)
; template <class Epi, class Sched, bool ALIGN_EPI = false, bool SP2 = false>
; __device__ __forceinline__ void gemm_phase(PG8_LAS unsigned char* lds, const Gemm g, const Sched& S, const Epi& E, int tid_in) {
;     ...
;         for (int t = 0; t < nt; t += 2) {
;             const bool last = (t == nt - 2);
;     ...
;             PG8_LDB(B0, 1, 0); PG8_LDB(B1, 1, 1); PG8_SCHED; PG8_LDA(At, 1, 0); PG8_STAGE(PG8_SA(0, 1), a2 + hstep, voffA);
;             PG8_WAIT_V(8); PG8_WAIT_L(0); PG8_BAR; PG8_MMA(0, 0, At, B0); PG8_MMA(0, 1, At, B1); PG8_BAR; PG8_SCHED;
;             PG8_LDA(At, 1, 1); PG8_STAGE(PG8_SB(1, 0), b3, voffB); PG8_STAGE(PG8_SB(1, 1), b3 + hstepB, voffB); PG8_STAGE(PG8_SA(1, 0), a3, voffA);
;             PG8_WAIT_V(8); PG8_WAIT_L(0); PG8_BAR; PG8_MMA(1, 0, At, B0); PG8_MMA(1, 1, At, B1); PG8_BAR; PG8_SCHED;
	s_add_i32 s33, 0, 0x18000
	v_add_u32_e32 v155, s33, v146
	s_add_i32 s73, 0, 0x1c000
	ds_read_b128 v[156:159], v155
	ds_read_b128 v[160:163], v155 offset:1024
	ds_read_b128 v[164:167], v155 offset:2048
	ds_read_b128 v[168:171], v155 offset:3072
	v_add_u32_e32 v155, s73, v146
	ds_read_b128 v[172:175], v155
	ds_read_b128 v[176:179], v155 offset:1024
	ds_read_b128 v[180:183], v155 offset:2048
	ds_read_b128 v[184:187], v155 offset:3072
	s_add_u32 s26, s54, 0x80000
	s_addc_u32 s27, s55, 0
	s_mov_b32 m0, s58
	ds_read_b128 v[188:191], v152 offset:32768
	ds_read_b128 v[192:195], v152 offset:33792
	ds_read_b128 v[196:199], v152 offset:34816
	ds_read_b128 v[200:203], v152 offset:35840
	ds_read_b128 v[204:207], v152 offset:36864
	ds_read_b128 v[208:211], v152 offset:37888
	ds_read_b128 v[212:215], v152 offset:38912
	ds_read_b128 v[216:219], v152 offset:39936
	global_load_lds_dwordx4 v128, s[26:27]
	s_mov_b32 m0, s59
	s_nop 0
	global_load_lds_dwordx4 v132, s[26:27]
	s_waitcnt vmcnt(8)
	s_waitcnt lgkmcnt(0)
	s_barrier
	s_setprio 1
	s_waitcnt lgkmcnt(0)
	v_mfma_f32_16x16x32_bf16 v[124:127], v[156:159], v[188:191], v[124:127]
	v_mfma_f32_16x16x32_bf16 v[120:123], v[164:167], v[188:191], v[120:123]
	v_mfma_f32_16x16x32_bf16 v[108:111], v[156:159], v[196:199], v[108:111]
	v_mfma_f32_16x16x32_bf16 v[104:107], v[164:167], v[196:199], v[104:107]
	v_mfma_f32_16x16x32_bf16 v[92:95], v[156:159], v[204:207], v[92:95]
	v_mfma_f32_16x16x32_bf16 v[88:91], v[164:167], v[204:207], v[88:91]
	v_mfma_f32_16x16x32_bf16 v[76:79], v[156:159], v[212:215], v[76:79]
	v_mfma_f32_16x16x32_bf16 v[72:75], v[164:167], v[212:215], v[72:75]
	v_mfma_f32_16x16x32_bf16 v[124:127], v[160:163], v[192:195], v[124:127]
	v_mfma_f32_16x16x32_bf16 v[120:123], v[168:171], v[192:195], v[120:123]
	v_mfma_f32_16x16x32_bf16 v[108:111], v[160:163], v[200:203], v[108:111]
	v_mfma_f32_16x16x32_bf16 v[104:107], v[168:171], v[200:203], v[104:107]
	v_mfma_f32_16x16x32_bf16 v[92:95], v[160:163], v[208:211], v[92:95]
	v_mfma_f32_16x16x32_bf16 v[88:91], v[168:171], v[208:211], v[88:91]
	v_mfma_f32_16x16x32_bf16 v[76:79], v[160:163], v[216:219], v[76:79]
	v_mfma_f32_16x16x32_bf16 v[72:75], v[168:171], v[216:219], v[72:75]
	s_setprio 0
	s_setprio 1
	v_mfma_f32_16x16x32_bf16 v[116:119], v[172:175], v[188:191], v[116:119]
	v_mfma_f32_16x16x32_bf16 v[112:115], v[180:183], v[188:191], v[112:115]
	v_mfma_f32_16x16x32_bf16 v[100:103], v[172:175], v[196:199], v[100:103]
	v_mfma_f32_16x16x32_bf16 v[96:99], v[180:183], v[196:199], v[96:99]
	v_mfma_f32_16x16x32_bf16 v[84:87], v[172:175], v[204:207], v[84:87]
	v_mfma_f32_16x16x32_bf16 v[80:83], v[180:183], v[204:207], v[80:83]
	v_mfma_f32_16x16x32_bf16 v[68:71], v[172:175], v[212:215], v[68:71]
	v_mfma_f32_16x16x32_bf16 v[64:67], v[180:183], v[212:215], v[64:67]
	v_mfma_f32_16x16x32_bf16 v[116:119], v[176:179], v[192:195], v[116:119]
	v_mfma_f32_16x16x32_bf16 v[112:115], v[184:187], v[192:195], v[112:115]
	v_mfma_f32_16x16x32_bf16 v[100:103], v[176:179], v[200:203], v[100:103]
	v_mfma_f32_16x16x32_bf16 v[96:99], v[184:187], v[200:203], v[96:99]
	v_mfma_f32_16x16x32_bf16 v[84:87], v[176:179], v[208:211], v[84:87]
	v_mfma_f32_16x16x32_bf16 v[80:83], v[184:187], v[208:211], v[80:83]
	v_mfma_f32_16x16x32_bf16 v[68:71], v[176:179], v[216:219], v[68:71]
	v_mfma_f32_16x16x32_bf16 v[64:67], v[184:187], v[216:219], v[64:67]
	s_setprio 0
	s_barrier
	s_add_i32 s26, s33, s56
	s_add_i32 m0, s26, 0xffffff80
	ds_read_b128 v[188:191], v152 offset:49152
	ds_read_b128 v[192:195], v152 offset:50176
	ds_read_b128 v[196:199], v152 offset:51200
	ds_read_b128 v[200:203], v152 offset:52224
	ds_read_b128 v[204:207], v152 offset:53248
	ds_read_b128 v[208:211], v152 offset:54272
	ds_read_b128 v[212:215], v152 offset:55296
	ds_read_b128 v[216:219], v152 offset:56320
	global_load_lds_dwordx4 v130, s[52:53] offset:128
	s_add_i32 m0, s26, 0x1f80
	s_add_u32 s26, s52, 0x20080
	s_addc_u32 s27, s53, 0
	s_add_i32 s33, s73, s56
	global_load_lds_dwordx4 v134, s[52:53] offset:128
	s_mov_b32 m0, s33
	s_nop 0
	global_load_lds_dwordx4 v130, s[26:27]
	s_add_i32 m0, s33, 0x2000
	s_nop 0
	global_load_lds_dwordx4 v134, s[26:27]
	s_add_i32 m0, s62, 0xffffff80
	s_nop 0
	global_load_lds_dwordx4 v128, s[54:55] offset:128
	s_add_i32 m0, s63, 0xffffff80
	s_nop 0
	global_load_lds_dwordx4 v132, s[54:55] offset:128
	s_waitcnt vmcnt(8)
	s_waitcnt lgkmcnt(0)
	s_barrier
	s_setprio 1
	s_waitcnt lgkmcnt(0)
	v_mfma_f32_16x16x32_bf16 v[60:63], v[156:159], v[188:191], v[60:63]
	v_mfma_f32_16x16x32_bf16 v[56:59], v[164:167], v[188:191], v[56:59]
	v_mfma_f32_16x16x32_bf16 v[44:47], v[156:159], v[196:199], v[44:47]
	v_mfma_f32_16x16x32_bf16 v[40:43], v[164:167], v[196:199], v[40:43]
	v_mfma_f32_16x16x32_bf16 v[28:31], v[156:159], v[204:207], v[28:31]
	v_mfma_f32_16x16x32_bf16 v[24:27], v[164:167], v[204:207], v[24:27]
	v_mfma_f32_16x16x32_bf16 v[12:15], v[156:159], v[212:215], v[12:15]
	v_mfma_f32_16x16x32_bf16 v[8:11], v[164:167], v[212:215], v[8:11]
	v_mfma_f32_16x16x32_bf16 v[60:63], v[160:163], v[192:195], v[60:63]
	v_mfma_f32_16x16x32_bf16 v[56:59], v[168:171], v[192:195], v[56:59]
	v_mfma_f32_16x16x32_bf16 v[44:47], v[160:163], v[200:203], v[44:47]
	v_mfma_f32_16x16x32_bf16 v[40:43], v[168:171], v[200:203], v[40:43]
	v_mfma_f32_16x16x32_bf16 v[28:31], v[160:163], v[208:211], v[28:31]
	v_mfma_f32_16x16x32_bf16 v[24:27], v[168:171], v[208:211], v[24:27]
	v_mfma_f32_16x16x32_bf16 v[12:15], v[160:163], v[216:219], v[12:15]
	v_mfma_f32_16x16x32_bf16 v[8:11], v[168:171], v[216:219], v[8:11]
	s_setprio 0
	s_setprio 1
	v_mfma_f32_16x16x32_bf16 v[52:55], v[172:175], v[188:191], v[52:55]
	v_mfma_f32_16x16x32_bf16 v[48:51], v[180:183], v[188:191], v[48:51]
	v_mfma_f32_16x16x32_bf16 v[36:39], v[172:175], v[196:199], v[36:39]
	v_mfma_f32_16x16x32_bf16 v[32:35], v[180:183], v[196:199], v[32:35]
	v_mfma_f32_16x16x32_bf16 v[20:23], v[172:175], v[204:207], v[20:23]
	v_mfma_f32_16x16x32_bf16 v[16:19], v[180:183], v[204:207], v[16:19]
	v_mfma_f32_16x16x32_bf16 v[4:7], v[172:175], v[212:215], v[4:7]
	v_mfma_f32_16x16x32_bf16 v[0:3], v[180:183], v[212:215], v[0:3]
	v_mfma_f32_16x16x32_bf16 v[52:55], v[176:179], v[192:195], v[52:55]
	v_mfma_f32_16x16x32_bf16 v[48:51], v[184:187], v[192:195], v[48:51]
	v_mfma_f32_16x16x32_bf16 v[36:39], v[176:179], v[200:203], v[36:39]
	v_mfma_f32_16x16x32_bf16 v[32:35], v[184:187], v[200:203], v[32:35]
	v_mfma_f32_16x16x32_bf16 v[20:23], v[176:179], v[208:211], v[20:23]
	v_mfma_f32_16x16x32_bf16 v[16:19], v[184:187], v[208:211], v[16:19]
	v_mfma_f32_16x16x32_bf16 v[4:7], v[176:179], v[216:219], v[4:7]
	v_mfma_f32_16x16x32_bf16 v[0:3], v[184:187], v[216:219], v[0:3]
	s_setprio 0
	s_barrier
	s_add_i32 s72, s72, 2
	s_add_u32 s50, s50, 0x100
	s_addc_u32 s51, s51, 0
	s_add_u32 s70, s70, 0x100
	s_addc_u32 s71, s71, 0
	s_cmp_gt_u32 s72, 29
	s_cbranch_scc0 .LBB0_869
	s_and_b64 vcc, exec, s[36:37]
	s_cbranch_vccz .LBB0_872
	s_barrier

; #define PG8_STAGE(bufoff, gbase, voff) do { _Pragma("unroll") for (int _i = 0; _i < 2; ++_i) \
;         __builtin_amdgcn_global_load_lds((const unsigned*)((const char*)(gbase) + (voff)[_i]), (PG8_LAS unsigned*)(lds + (bufoff) + ldsw + _i * 8192), 16, 0, 0); } while (0)
; #define PG8_LDA(dst, b, h) do { _Pragma("unroll") for (int m = 0; m < 4; ++m) _Pragma("unroll") for (int k = 0; k < 2; ++k) dst[m][k] = *(const PG8_LAS bf16x8*)(lds + PG8_SA(b, h) + aoff + m * 2048 + k * 1024); } while (0)
; #define PG8_LDB(dst, b, h) do { _Pragma("unroll") for (int n = 0; n < 2; ++n) _Pragma("unroll") for (int k = 0; k < 2; ++k) dst[n][k] = *(const PG8_LAS bf16x8*)(lds + PG8_SB(b, h) + boff + n * 2048 + k * 1024); } while (0)
; #define PG8_MMA(ai, bj, At, Bt) do { __builtin_amdgcn_s_setprio(1); _Pragma("unroll") for (int m = 0; m < 4; ++m) _Pragma("unroll") for (int n = 0; n < 2; ++n) _Pragma("unroll") for (int k = 0; k < 2; ++k) \
;         acc[ai][bj][m][n] = __builtin_amdgcn_mfma_f32_16x16x32_bf16(Bt[n][k], At[m][k], acc[ai][bj][m][n], 0, 0, 0); __builtin_amdgcn_s_setprio(0); } while (0)
; #define PG8_WAIT_V(n) asm volatile("s_waitcnt vmcnt(" #n ")" ::: "memory")
; #define PG8_WAIT_L(n) asm volatile("s_waitcnt lgkmcnt(" #n ")" ::: "memory")
; #define PG8_BAR __builtin_amdgcn_s_barrier()
; #define PG8_SCHED __builtin_amdgcn_sched_barrier(0)
; template <class Epi, class Sched, bool ALIGN_EPI = false, bool SP2 = false>
; __device__ __forceinline__ void gemm_phase(PG8_LAS unsigned char* lds, const Gemm g, const Sched& S, const Epi& E, int tid_in) {
;     ...
;             PG8_LDB(B0, 0, 0); PG8_LDB(B1, 0, 1); PG8_SCHED; PG8_LDA(At, 0, 0); PG8_STAGE(PG8_SA(1, 1), a1 + hstep, voffA);
;             PG8_WAIT_V(8); PG8_WAIT_L(0); PG8_BAR; PG8_MMA(0, 0, At, B0); PG8_MMA(0, 1, At, B1); PG8_BAR; PG8_SCHED;
;             PG8_LDA(At, 0, 1); PG8_STAGE(PG8_SB(0, 0), b2, voffB); PG8_STAGE(PG8_SB(0, 1), b2 + hstepB, voffB); PG8_STAGE(PG8_SA(0, 0), a2, voffA);
;             PG8_WAIT_V(8); PG8_WAIT_L(0); PG8_BAR; PG8_MMA(1, 0, At, B0); PG8_MMA(1, 1, At, B1); PG8_BAR; PG8_SCHED;
.Lkb_skip_7:
.LBB0_949:
	ds_read_b128 v[146:149], v153
	ds_read_b128 v[158:161], v153 offset:1024
	ds_read_b128 v[162:165], v153 offset:2048
	ds_read_b128 v[166:169], v153 offset:3072
	ds_read_b128 v[170:173], v154
	ds_read_b128 v[174:177], v154 offset:1024
	ds_read_b128 v[178:181], v154 offset:2048
	ds_read_b128 v[182:185], v154 offset:3072
	s_add_u32 s10, s50, 0x100
	s_addc_u32 s11, s51, 0
	s_cmpk_eq_i32 s70, 0x7c
	s_cselect_b32 s55, s45, s11
	s_cselect_b32 s54, s44, s10
	s_cselect_b32 s53, s43, s69
	s_cselect_b32 s52, s67, s68
	s_add_i32 m0, s49, 0xc000
	ds_read_b128 v[186:189], v155
	ds_read_b128 v[190:193], v155 offset:1024
	ds_read_b128 v[194:197], v155 offset:2048
	ds_read_b128 v[198:201], v155 offset:3072
	ds_read_b128 v[202:205], v155 offset:4096
	ds_read_b128 v[206:209], v155 offset:5120
	ds_read_b128 v[210:213], v155 offset:6144
	ds_read_b128 v[214:217], v155 offset:7168
	global_load_lds_dwordx4 v138, s[50:51]
	s_add_i32 m0, s49, 0xe000
	s_nop 0
	global_load_lds_dwordx4 v140, s[50:51]
	s_waitcnt vmcnt(8)
	s_waitcnt lgkmcnt(0)
	s_barrier
	s_setprio 1
	s_waitcnt lgkmcnt(0)
	v_mfma_f32_16x16x32_bf16 v[124:127], v[146:149], v[186:189], v[124:127]
	v_mfma_f32_16x16x32_bf16 v[120:123], v[162:165], v[186:189], v[120:123]
	v_mfma_f32_16x16x32_bf16 v[108:111], v[146:149], v[194:197], v[108:111]
	v_mfma_f32_16x16x32_bf16 v[104:107], v[162:165], v[194:197], v[104:107]
	v_mfma_f32_16x16x32_bf16 v[92:95], v[146:149], v[202:205], v[92:95]
	v_mfma_f32_16x16x32_bf16 v[88:91], v[162:165], v[202:205], v[88:91]
	v_mfma_f32_16x16x32_bf16 v[76:79], v[146:149], v[210:213], v[76:79]
	v_mfma_f32_16x16x32_bf16 v[72:75], v[162:165], v[210:213], v[72:75]
	v_mfma_f32_16x16x32_bf16 v[124:127], v[158:161], v[190:193], v[124:127]
	v_mfma_f32_16x16x32_bf16 v[120:123], v[166:169], v[190:193], v[120:123]
	v_mfma_f32_16x16x32_bf16 v[108:111], v[158:161], v[198:201], v[108:111]
	v_mfma_f32_16x16x32_bf16 v[104:107], v[166:169], v[198:201], v[104:107]
	v_mfma_f32_16x16x32_bf16 v[92:95], v[158:161], v[206:209], v[92:95]
	v_mfma_f32_16x16x32_bf16 v[88:91], v[166:169], v[206:209], v[88:91]
	v_mfma_f32_16x16x32_bf16 v[76:79], v[158:161], v[214:217], v[76:79]
	v_mfma_f32_16x16x32_bf16 v[72:75], v[166:169], v[214:217], v[72:75]
	s_setprio 0
	s_setprio 1
	v_mfma_f32_16x16x32_bf16 v[116:119], v[170:173], v[186:189], v[116:119]
	v_mfma_f32_16x16x32_bf16 v[112:115], v[178:181], v[186:189], v[112:115]
	v_mfma_f32_16x16x32_bf16 v[100:103], v[170:173], v[194:197], v[100:103]
	v_mfma_f32_16x16x32_bf16 v[96:99], v[178:181], v[194:197], v[96:99]
	v_mfma_f32_16x16x32_bf16 v[84:87], v[170:173], v[202:205], v[84:87]
	v_mfma_f32_16x16x32_bf16 v[80:83], v[178:181], v[202:205], v[80:83]
	v_mfma_f32_16x16x32_bf16 v[68:71], v[170:173], v[210:213], v[68:71]
	v_mfma_f32_16x16x32_bf16 v[64:67], v[178:181], v[210:213], v[64:67]
	v_mfma_f32_16x16x32_bf16 v[116:119], v[174:177], v[190:193], v[116:119]
	v_mfma_f32_16x16x32_bf16 v[112:115], v[182:185], v[190:193], v[112:115]
	v_mfma_f32_16x16x32_bf16 v[100:103], v[174:177], v[198:201], v[100:103]
	v_mfma_f32_16x16x32_bf16 v[96:99], v[182:185], v[198:201], v[96:99]
	v_mfma_f32_16x16x32_bf16 v[84:87], v[174:177], v[206:209], v[84:87]
	v_mfma_f32_16x16x32_bf16 v[80:83], v[182:185], v[206:209], v[80:83]
	v_mfma_f32_16x16x32_bf16 v[68:71], v[174:177], v[214:217], v[68:71]
	v_mfma_f32_16x16x32_bf16 v[64:67], v[182:185], v[214:217], v[64:67]
	s_setprio 0
	s_barrier
	s_add_i32 s26, s63, s56
	s_mov_b32 m0, s26
	ds_read_b128 v[186:189], v155 offset:16384
	ds_read_b128 v[190:193], v155 offset:17408
	ds_read_b128 v[194:197], v155 offset:18432
	ds_read_b128 v[198:201], v155 offset:19456
	ds_read_b128 v[202:205], v155 offset:20480
	ds_read_b128 v[206:209], v155 offset:21504
	ds_read_b128 v[210:213], v155 offset:22528
	ds_read_b128 v[214:217], v155 offset:23552
	global_load_lds_dwordx4 v130, s[52:53]
	s_add_i32 m0, s26, 0x2000
	s_add_u32 s26, s52, 0x80000
	s_addc_u32 s27, s53, 0
	s_add_i32 s33, s64, s56
	global_load_lds_dwordx4 v134, s[52:53]
	s_mov_b32 m0, s33
	s_nop 0
	global_load_lds_dwordx4 v130, s[26:27]
	s_add_i32 m0, s33, 0x2000
	s_nop 0
	global_load_lds_dwordx4 v134, s[26:27]
	s_mov_b32 m0, s49
	s_nop 0
	global_load_lds_dwordx4 v128, s[54:55]
	s_mov_b32 m0, s57
	s_nop 0
	global_load_lds_dwordx4 v132, s[54:55]
	s_waitcnt vmcnt(8)
	s_waitcnt lgkmcnt(0)
	s_barrier
	s_setprio 1
	s_waitcnt lgkmcnt(0)
	v_mfma_f32_16x16x32_bf16 v[60:63], v[146:149], v[186:189], v[60:63]
	v_mfma_f32_16x16x32_bf16 v[56:59], v[162:165], v[186:189], v[56:59]
	v_mfma_f32_16x16x32_bf16 v[44:47], v[146:149], v[194:197], v[44:47]
	v_mfma_f32_16x16x32_bf16 v[40:43], v[162:165], v[194:197], v[40:43]
	v_mfma_f32_16x16x32_bf16 v[28:31], v[146:149], v[202:205], v[28:31]
	v_mfma_f32_16x16x32_bf16 v[24:27], v[162:165], v[202:205], v[24:27]
	v_mfma_f32_16x16x32_bf16 v[12:15], v[146:149], v[210:213], v[12:15]
	v_mfma_f32_16x16x32_bf16 v[8:11], v[162:165], v[210:213], v[8:11]
	v_mfma_f32_16x16x32_bf16 v[60:63], v[158:161], v[190:193], v[60:63]
	v_mfma_f32_16x16x32_bf16 v[56:59], v[166:169], v[190:193], v[56:59]
	v_mfma_f32_16x16x32_bf16 v[44:47], v[158:161], v[198:201], v[44:47]
	v_mfma_f32_16x16x32_bf16 v[40:43], v[166:169], v[198:201], v[40:43]
	v_mfma_f32_16x16x32_bf16 v[28:31], v[158:161], v[206:209], v[28:31]
	v_mfma_f32_16x16x32_bf16 v[24:27], v[166:169], v[206:209], v[24:27]
	v_mfma_f32_16x16x32_bf16 v[12:15], v[158:161], v[214:217], v[12:15]
	v_mfma_f32_16x16x32_bf16 v[8:11], v[166:169], v[214:217], v[8:11]
	s_setprio 0
	s_setprio 1
	v_mfma_f32_16x16x32_bf16 v[52:55], v[170:173], v[186:189], v[52:55]
	v_mfma_f32_16x16x32_bf16 v[48:51], v[178:181], v[186:189], v[48:51]
	v_mfma_f32_16x16x32_bf16 v[36:39], v[170:173], v[194:197], v[36:39]
	v_mfma_f32_16x16x32_bf16 v[32:35], v[178:181], v[194:197], v[32:35]
	v_mfma_f32_16x16x32_bf16 v[20:23], v[170:173], v[202:205], v[20:23]
	v_mfma_f32_16x16x32_bf16 v[16:19], v[178:181], v[202:205], v[16:19]
	v_mfma_f32_16x16x32_bf16 v[4:7], v[170:173], v[210:213], v[4:7]
	v_mfma_f32_16x16x32_bf16 v[0:3], v[178:181], v[210:213], v[0:3]
	v_mfma_f32_16x16x32_bf16 v[52:55], v[174:177], v[190:193], v[52:55]
	v_mfma_f32_16x16x32_bf16 v[48:51], v[182:185], v[190:193], v[48:51]
	v_mfma_f32_16x16x32_bf16 v[36:39], v[174:177], v[198:201], v[36:39]
	v_mfma_f32_16x16x32_bf16 v[32:35], v[182:185], v[198:201], v[32:35]
	v_mfma_f32_16x16x32_bf16 v[20:23], v[174:177], v[206:209], v[20:23]
	v_mfma_f32_16x16x32_bf16 v[16:19], v[182:185], v[206:209], v[16:19]
	v_mfma_f32_16x16x32_bf16 v[4:7], v[174:177], v[214:217], v[4:7]
	v_mfma_f32_16x16x32_bf16 v[0:3], v[182:185], v[214:217], v[0:3]
	s_setprio 0
	s_barrier
; #define PG8_STAGE(bufoff, gbase, voff) do { _Pragma("unroll") for (int _i = 0; _i < 2; ++_i) \
;         __builtin_amdgcn_global_load_lds((const unsigned*)((const char*)(gbase) + (voff)[_i]), (PG8_LAS unsigned*)(lds + (bufoff) + ldsw + _i * 8192), 16, 0, 0); } while (0)
; #define PG8_LDA(dst, b, h) do { _Pragma("unroll") for (int m = 0; m < 4; ++m) _Pragma("unroll") for (int k = 0; k < 2; ++k) dst[m][k] = *(const PG8_LAS bf16x8*)(lds + PG8_SA(b, h) + aoff + m * 2048 + k * 1024); } while (0)
; #define PG8_LDB(dst, b, h) do { _Pragma("unroll") for (int n = 0; n < 2; ++n) _Pragma("unroll") for (int k = 0; k < 2; ++k) dst[n][k] = *(const PG8_LAS bf16x8*)(lds + PG8_SB(b, h) + boff + n * 2048 + k * 1024); } while (0)
; #define PG8_MMA(ai, bj, At, Bt) do { __builtin_amdgcn_s_setprio(1); _Pragma("unroll") for (int m = 0; m < 4; ++m) _Pragma("unroll") for (int n = 0; n < 2; ++n) _Pragma("unroll") for (int k = 0; k < 2; ++k) \
;         acc[ai][bj][m][n] = __builtin_amdgcn_mfma_f32_16x16x32_bf16(Bt[n][k], At[m][k], acc[ai][bj][m][n], 0, 0, 0); __builtin_amdgcn_s_setprio(0); } while (0)
; #define PG8_WAIT_V(n) asm volatile("s_waitcnt vmcnt(" #n ")" ::: "memory")
; #define PG8_WAIT_L(n) asm volatile("s_waitcnt lgkmcnt(" #n ")" ::: "memory")
; #define PG8_BAR __builtin_amdgcn_s_barrier()
; #define PG8_SCHED __builtin_amdgcn_sched_barrier(0)
; template <class Epi, class Sched, bool ALIGN_EPI = false, bool SP2 = false>
; __device__ __forceinline__ void gemm_phase(PG8_LAS unsigned char* lds, const Gemm g, const Sched& S, const Epi& E, int tid_in) {
;     ...
;             PG8_LDB(B0, 1, 0); PG8_LDB(B1, 1, 1); PG8_SCHED; PG8_LDA(At, 1, 0); PG8_STAGE(PG8_SA(0, 1), a2 + hstep, voffA);
;             PG8_WAIT_V(8); PG8_WAIT_L(0); PG8_BAR; PG8_MMA(0, 0, At, B0); PG8_MMA(0, 1, At, B1); PG8_BAR; PG8_SCHED;
;             PG8_LDA(At, 1, 1); PG8_STAGE(PG8_SB(1, 0), b3, voffB); PG8_STAGE(PG8_SB(1, 1), b3 + hstepB, voffB); PG8_STAGE(PG8_SA(1, 0), a3, voffA);
;             PG8_WAIT_V(8); PG8_WAIT_L(0); PG8_BAR; PG8_MMA(1, 0, At, B0); PG8_MMA(1, 1, At, B1); PG8_BAR; PG8_SCHED;
	s_add_i32 s33, 0, 0x18000
	s_add_i32 s50, 0, 0x1c000
	v_add_u32_e32 v166, s33, v137
	v_add_u32_e32 v182, s50, v137
	ds_read_b128 v[146:149], v166
	ds_read_b128 v[158:161], v166 offset:1024
	ds_read_b128 v[162:165], v166 offset:2048
	ds_read_b128 v[166:169], v166 offset:3072
	ds_read_b128 v[170:173], v182
	ds_read_b128 v[174:177], v182 offset:1024
	ds_read_b128 v[178:181], v182 offset:2048
	ds_read_b128 v[182:185], v182 offset:3072
	s_add_u32 s26, s54, 0x204000
	s_addc_u32 s27, s55, 0
	s_mov_b32 m0, s58
	ds_read_b128 v[186:189], v155 offset:32768
	ds_read_b128 v[190:193], v155 offset:33792
	ds_read_b128 v[194:197], v155 offset:34816
	ds_read_b128 v[198:201], v155 offset:35840
	ds_read_b128 v[202:205], v155 offset:36864
	ds_read_b128 v[206:209], v155 offset:37888
	ds_read_b128 v[210:213], v155 offset:38912
	ds_read_b128 v[214:217], v155 offset:39936
	global_load_lds_dwordx4 v128, s[26:27]
	s_mov_b32 m0, s59
	s_nop 0
	global_load_lds_dwordx4 v132, s[26:27]
	s_waitcnt vmcnt(8)
	s_waitcnt lgkmcnt(0)
	s_barrier
	s_setprio 1
	s_waitcnt lgkmcnt(0)
	v_mfma_f32_16x16x32_bf16 v[124:127], v[146:149], v[186:189], v[124:127]
	v_mfma_f32_16x16x32_bf16 v[120:123], v[162:165], v[186:189], v[120:123]
	v_mfma_f32_16x16x32_bf16 v[108:111], v[146:149], v[194:197], v[108:111]
	v_mfma_f32_16x16x32_bf16 v[104:107], v[162:165], v[194:197], v[104:107]
	v_mfma_f32_16x16x32_bf16 v[92:95], v[146:149], v[202:205], v[92:95]
	v_mfma_f32_16x16x32_bf16 v[88:91], v[162:165], v[202:205], v[88:91]
	v_mfma_f32_16x16x32_bf16 v[76:79], v[146:149], v[210:213], v[76:79]
	v_mfma_f32_16x16x32_bf16 v[72:75], v[162:165], v[210:213], v[72:75]
	v_mfma_f32_16x16x32_bf16 v[124:127], v[158:161], v[190:193], v[124:127]
	v_mfma_f32_16x16x32_bf16 v[120:123], v[166:169], v[190:193], v[120:123]
	v_mfma_f32_16x16x32_bf16 v[108:111], v[158:161], v[198:201], v[108:111]
	v_mfma_f32_16x16x32_bf16 v[104:107], v[166:169], v[198:201], v[104:107]
	v_mfma_f32_16x16x32_bf16 v[92:95], v[158:161], v[206:209], v[92:95]
	v_mfma_f32_16x16x32_bf16 v[88:91], v[166:169], v[206:209], v[88:91]
	v_mfma_f32_16x16x32_bf16 v[76:79], v[158:161], v[214:217], v[76:79]
	v_mfma_f32_16x16x32_bf16 v[72:75], v[166:169], v[214:217], v[72:75]
	s_setprio 0
	s_setprio 1
	v_mfma_f32_16x16x32_bf16 v[116:119], v[170:173], v[186:189], v[116:119]
	v_mfma_f32_16x16x32_bf16 v[112:115], v[178:181], v[186:189], v[112:115]
	v_mfma_f32_16x16x32_bf16 v[100:103], v[170:173], v[194:197], v[100:103]
	v_mfma_f32_16x16x32_bf16 v[96:99], v[178:181], v[194:197], v[96:99]
	v_mfma_f32_16x16x32_bf16 v[84:87], v[170:173], v[202:205], v[84:87]
	v_mfma_f32_16x16x32_bf16 v[80:83], v[178:181], v[202:205], v[80:83]
	v_mfma_f32_16x16x32_bf16 v[68:71], v[170:173], v[210:213], v[68:71]
	v_mfma_f32_16x16x32_bf16 v[64:67], v[178:181], v[210:213], v[64:67]
	v_mfma_f32_16x16x32_bf16 v[116:119], v[174:177], v[190:193], v[116:119]
	v_mfma_f32_16x16x32_bf16 v[112:115], v[182:185], v[190:193], v[112:115]
	v_mfma_f32_16x16x32_bf16 v[100:103], v[174:177], v[198:201], v[100:103]
	v_mfma_f32_16x16x32_bf16 v[96:99], v[182:185], v[198:201], v[96:99]
	v_mfma_f32_16x16x32_bf16 v[84:87], v[174:177], v[206:209], v[84:87]
	v_mfma_f32_16x16x32_bf16 v[80:83], v[182:185], v[206:209], v[80:83]
	v_mfma_f32_16x16x32_bf16 v[68:71], v[174:177], v[214:217], v[68:71]
	v_mfma_f32_16x16x32_bf16 v[64:67], v[182:185], v[214:217], v[64:67]
	s_setprio 0
	s_barrier
	s_add_i32 s26, s33, s56
	s_add_i32 m0, s26, 0xffffff80
	ds_read_b128 v[186:189], v155 offset:49152
	ds_read_b128 v[190:193], v155 offset:50176
	ds_read_b128 v[194:197], v155 offset:51200
	ds_read_b128 v[198:201], v155 offset:52224
	ds_read_b128 v[202:205], v155 offset:53248
	ds_read_b128 v[206:209], v155 offset:54272
	ds_read_b128 v[210:213], v155 offset:55296
	ds_read_b128 v[214:217], v155 offset:56320
	global_load_lds_dwordx4 v130, s[52:53] offset:128
	s_add_i32 m0, s26, 0x1f80
	s_add_u32 s26, s52, 0x80080
	s_addc_u32 s27, s53, 0
	s_add_i32 s33, s50, s56
	global_load_lds_dwordx4 v134, s[52:53] offset:128
	s_mov_b32 m0, s33
	s_nop 0
	global_load_lds_dwordx4 v130, s[26:27]
	s_add_i32 m0, s33, 0x2000
	s_nop 0
	global_load_lds_dwordx4 v134, s[26:27]
	s_add_i32 m0, s61, 0xffffff80
	s_nop 0
	global_load_lds_dwordx4 v128, s[54:55] offset:128
	s_add_i32 m0, s62, 0xffffff80
	s_nop 0
	global_load_lds_dwordx4 v132, s[54:55] offset:128
	s_waitcnt vmcnt(8)
	s_waitcnt lgkmcnt(0)
	s_barrier
; #define PG8_STAGE(bufoff, gbase, voff) do { _Pragma("unroll") for (int _i = 0; _i < 2; ++_i) \
;         __builtin_amdgcn_global_load_lds((const unsigned*)((const char*)(gbase) + (voff)[_i]), (PG8_LAS unsigned*)(lds + (bufoff) + ldsw + _i * 8192), 16, 0, 0); } while (0)
; #define PG8_LDA(dst, b, h) do { _Pragma("unroll") for (int m = 0; m < 4; ++m) _Pragma("unroll") for (int k = 0; k < 2; ++k) dst[m][k] = *(const PG8_LAS bf16x8*)(lds + PG8_SA(b, h) + aoff + m * 2048 + k * 1024); } while (0)
; #define PG8_MMA(ai, bj, At, Bt) do { __builtin_amdgcn_s_setprio(1); _Pragma("unroll") for (int m = 0; m < 4; ++m) _Pragma("unroll") for (int n = 0; n < 2; ++n) _Pragma("unroll") for (int k = 0; k < 2; ++k) \
;         acc[ai][bj][m][n] = __builtin_amdgcn_mfma_f32_16x16x32_bf16(Bt[n][k], At[m][k], acc[ai][bj][m][n], 0, 0, 0); __builtin_amdgcn_s_setprio(0); } while (0)
; template <class Epi, class Sched, bool ALIGN_EPI = false, bool SP2 = false>
; __device__ __forceinline__ void gemm_phase(PG8_LAS unsigned char* lds, const Gemm g, const Sched& S, const Epi& E, int tid_in) {
;     ...
;             PG8_LDA(At, 1, 1); PG8_STAGE(PG8_SB(1, 0), b3, voffB); PG8_STAGE(PG8_SB(1, 1), b3 + hstepB, voffB); PG8_STAGE(PG8_SA(1, 0), a3, voffA);
;             PG8_WAIT_V(8); PG8_WAIT_L(0); PG8_BAR; PG8_MMA(1, 0, At, B0); PG8_MMA(1, 1, At, B1); PG8_BAR; PG8_SCHED;
;     __device__ __forceinline__ void operator()(const f32x4 (&acc)[2][2][4][2], const Unit& u, int wr, int wc, int fr, int fq) const {
;     ...
;                 const int row = u.pm * BM + ai * HALF + wr * 64 + m * 16 + r; float q = 0.f;
; #pragma unroll
;                 for (int bj = 0; bj < 2; ++bj) {
;                     const size_t off = (size_t)row * 2048 + u.pn * BM + wc * 64 + bj * 32 + 8 * p;
;                     f32x4 b0, b1;
;                     if (BASE_F32) { b0 = *(const f32x4*)((const float*)base + off); b1 = *(const f32x4*)((const float*)base + off + 4); }
;                     else { const u32x4 bb = *(const u32x4*)((const bf16_t*)base + off);
;                         b0 = (f32x4){__uint_as_float(bb.x << 16), __uint_as_float(bb.x & 0xffff0000u), __uint_as_float(bb.y << 16), __uint_as_float(bb.y & 0xffff0000u)};
;                         b1 = (f32x4){__uint_as_float(bb.z << 16), __uint_as_float(bb.z & 0xffff0000u), __uint_as_float(bb.w << 16), __uint_as_float(bb.w & 0xffff0000u)}; }
	s_setprio 1
	s_waitcnt lgkmcnt(0)
	v_mfma_f32_16x16x32_bf16 v[60:63], v[146:149], v[186:189], v[60:63]
	v_mfma_f32_16x16x32_bf16 v[56:59], v[162:165], v[186:189], v[56:59]
	v_mfma_f32_16x16x32_bf16 v[44:47], v[146:149], v[194:197], v[44:47]
	v_mfma_f32_16x16x32_bf16 v[40:43], v[162:165], v[194:197], v[40:43]
	v_mfma_f32_16x16x32_bf16 v[28:31], v[146:149], v[202:205], v[28:31]
	v_mfma_f32_16x16x32_bf16 v[24:27], v[162:165], v[202:205], v[24:27]
	v_mfma_f32_16x16x32_bf16 v[12:15], v[146:149], v[210:213], v[12:15]
	v_mfma_f32_16x16x32_bf16 v[8:11], v[162:165], v[210:213], v[8:11]
	v_mfma_f32_16x16x32_bf16 v[60:63], v[158:161], v[190:193], v[60:63]
	v_mfma_f32_16x16x32_bf16 v[56:59], v[166:169], v[190:193], v[56:59]
	v_mfma_f32_16x16x32_bf16 v[44:47], v[158:161], v[198:201], v[44:47]
	v_mfma_f32_16x16x32_bf16 v[40:43], v[166:169], v[198:201], v[40:43]
	v_mfma_f32_16x16x32_bf16 v[28:31], v[158:161], v[206:209], v[28:31]
	v_mfma_f32_16x16x32_bf16 v[24:27], v[166:169], v[206:209], v[24:27]
	v_mfma_f32_16x16x32_bf16 v[12:15], v[158:161], v[214:217], v[12:15]
	v_mfma_f32_16x16x32_bf16 v[8:11], v[166:169], v[214:217], v[8:11]
	s_setprio 0
	s_setprio 1
	v_mfma_f32_16x16x32_bf16 v[52:55], v[170:173], v[186:189], v[52:55]
	v_mfma_f32_16x16x32_bf16 v[48:51], v[178:181], v[186:189], v[48:51]
	v_mfma_f32_16x16x32_bf16 v[36:39], v[170:173], v[194:197], v[36:39]
	v_mfma_f32_16x16x32_bf16 v[32:35], v[178:181], v[194:197], v[32:35]
	v_mfma_f32_16x16x32_bf16 v[20:23], v[170:173], v[202:205], v[20:23]
	v_mfma_f32_16x16x32_bf16 v[16:19], v[178:181], v[202:205], v[16:19]
	v_mfma_f32_16x16x32_bf16 v[4:7], v[170:173], v[210:213], v[4:7]
	v_mfma_f32_16x16x32_bf16 v[0:3], v[178:181], v[210:213], v[0:3]
	v_mfma_f32_16x16x32_bf16 v[52:55], v[174:177], v[190:193], v[52:55]
	v_mfma_f32_16x16x32_bf16 v[48:51], v[182:185], v[190:193], v[48:51]
	v_mfma_f32_16x16x32_bf16 v[36:39], v[174:177], v[198:201], v[36:39]
	v_mfma_f32_16x16x32_bf16 v[32:35], v[182:185], v[198:201], v[32:35]
	v_mfma_f32_16x16x32_bf16 v[20:23], v[174:177], v[206:209], v[20:23]
	v_mfma_f32_16x16x32_bf16 v[16:19], v[182:185], v[206:209], v[16:19]
	v_mfma_f32_16x16x32_bf16 v[4:7], v[174:177], v[214:217], v[4:7]
	v_mfma_f32_16x16x32_bf16 v[0:3], v[182:185], v[214:217], v[0:3]
	s_setprio 0
	s_barrier
	s_add_i32 s70, s70, 2
	s_add_u32 s68, s68, 0x100
	s_addc_u32 s69, s69, 0
	s_cmpk_gt_u32 s70, 0x7d
	s_mov_b64 s[50:51], s[10:11]
	s_cbranch_scc0 .LBB0_949
	v_lshl_add_u32 v148, s66, 8, v150
	v_lshl_or_b32 v146, s48, 8, v136
	v_lshl_add_u32 v147, v148, 11, v146
	v_lshlrev_b32_e32 v159, 1, v147
	v_lshlrev_b32_e32 v208, 3, v148
	global_load_dwordx4 v[160:163], v159, s[28:29]
	global_load_dwordx4 v[164:167], v159, s[28:29] offset:64
	v_add_u32_e32 v149, 0x10000, v159
	global_load_dwordx4 v[168:171], v149, s[28:29]
	global_load_dwordx4 v[172:175], v149, s[28:29] offset:64
	v_add_u32_e32 v209, 0x20000, v159
	global_load_dwordx4 v[176:179], v209, s[28:29]
	global_load_dwordx4 v[180:183], v209, s[28:29] offset:64
	v_add_u32_e32 v149, 0x30000, v159
	global_load_dwordx4 v[184:187], v149, s[28:29]
	global_load_dwordx4 v[188:191], v149, s[28:29] offset:64
	v_add_u32_e32 v209, 0x80000, v159
	global_load_dwordx4 v[192:195], v209, s[28:29]
	global_load_dwordx4 v[196:199], v209, s[28:29] offset:64
	v_add_u32_e32 v149, 0x90000, v159
	global_load_dwordx4 v[200:203], v149, s[28:29]
	global_load_dwordx4 v[204:207], v149, s[28:29] offset:64
	v_add_u32_e32 v209, 0xa0000, v159
	global_load_dwordx4 v[212:215], v209, s[28:29]
	global_load_dwordx4 v[216:219], v209, s[28:29] offset:64
	v_add_u32_e32 v149, 0xb0000, v159
	global_load_dwordx4 v[220:223], v149, s[28:29]
	global_load_dwordx4 v[224:227], v149, s[28:29] offset:64
	s_and_b64 vcc, exec, s[40:41]
	s_cbranch_vccz .LBB0_952
	s_barrier
